# prologue: transposing loops issue both 16-load batches together; ada GEMV loop rewritten (silu once per lane + readlane broadcast, 32 loads deep); plus earlier edits
# baseline (speedup 1.0000x reference)
; #define LAS __attribute__((address_space(3)))
; __device__ __forceinline__ void transpose_item(const float* W, int N, bf16_t* WT, int ldw, int drow0, int dk0, LAS float* scr, int k0, int n0, int lane) {
; #pragma unroll 8
;     for (int i = 0; i < 32; ++i) { const int kk = 2 * i + (lane >> 5); scr[kk * 33 + (lane & 31)] = W[(size_t)(k0 + kk) * N + n0 + (lane & 31)]; }
.LBB0_41:
	s_lshl_b32 s15, s12, 1
	s_lshl_b32 s16, s9, 1
	v_or_b32_e32 v30, s15, v1
	v_or_b32_e32 v41, s16, v32
	s_add_i32 s17, s15, 4
	s_add_i32 s18, s16, 4
	s_add_i32 s19, s15, 8
	s_add_i32 s20, s16, 8
	s_add_i32 s21, s15, 12
	s_add_i32 s22, s16, 12
	s_add_i32 s23, s15, 16
	s_add_i32 s26, s16, 16
	s_add_i32 s27, s15, 20
	s_add_i32 s34, s16, 20
	s_add_i32 s35, s15, 24
	s_add_i32 s40, s16, 24
	s_add_i32 s15, s15, 28
	s_add_i32 s16, s16, 28
	v_add_u32_e32 v6, s8, v41
	v_or_b32_e32 v48, s17, v1
	v_or_b32_e32 v49, s18, v32
	v_or_b32_e32 v50, s19, v1
	v_or_b32_e32 v51, s20, v32
	v_or_b32_e32 v52, s21, v1
	v_or_b32_e32 v53, s22, v32
	v_or_b32_e32 v54, s23, v1
	v_or_b32_e32 v55, s26, v32
	v_or_b32_e32 v56, s27, v1
	v_or_b32_e32 v57, s34, v32
	v_or_b32_e32 v71, s35, v1
	v_or_b32_e32 v76, s40, v32
	v_or_b32_e32 v77, s15, v1
	v_or_b32_e32 v78, s16, v32
	v_add_u32_e32 v4, s13, v30
	v_ashrrev_i32_e32 v7, 31, v6
	v_add_u32_e32 v8, s13, v48
	v_add_u32_e32 v10, s8, v49
	v_add_u32_e32 v12, s13, v50
	v_add_u32_e32 v14, s8, v51
	v_add_u32_e32 v16, s13, v52
	v_add_u32_e32 v18, s8, v53
	v_add_u32_e32 v20, s13, v54
	v_add_u32_e32 v22, s8, v55
	v_add_u32_e32 v24, s13, v56
	v_add_u32_e32 v26, s8, v57
	v_add_u32_e32 v28, s13, v71
	v_add_u32_e32 v42, s8, v76
	v_add_u32_e32 v44, s13, v77
	v_add_u32_e32 v46, s8, v78
	v_ashrrev_i32_e32 v5, 31, v4
	v_lshlrev_b64 v[6:7], 12, v[6:7]
	v_ashrrev_i32_e32 v11, 31, v10
	v_ashrrev_i32_e32 v9, 31, v8
	v_ashrrev_i32_e32 v15, 31, v14
	v_ashrrev_i32_e32 v13, 31, v12
	v_ashrrev_i32_e32 v19, 31, v18
	v_ashrrev_i32_e32 v17, 31, v16
	v_ashrrev_i32_e32 v23, 31, v22
	v_ashrrev_i32_e32 v21, 31, v20
	v_ashrrev_i32_e32 v27, 31, v26
	v_ashrrev_i32_e32 v25, 31, v24
	v_ashrrev_i32_e32 v43, 31, v42
	v_ashrrev_i32_e32 v29, 31, v28
	v_ashrrev_i32_e32 v47, 31, v46
	v_ashrrev_i32_e32 v45, 31, v44
	v_lshlrev_b64 v[4:5], 12, v[4:5]
	v_lshl_add_u64 v[6:7], v[2:3], 0, v[6:7]
	v_lshlrev_b64 v[8:9], 12, v[8:9]
	v_lshlrev_b64 v[10:11], 12, v[10:11]
	v_lshlrev_b64 v[12:13], 12, v[12:13]
	v_lshlrev_b64 v[14:15], 12, v[14:15]
	v_lshlrev_b64 v[16:17], 12, v[16:17]
	v_lshlrev_b64 v[18:19], 12, v[18:19]
	v_lshlrev_b64 v[20:21], 12, v[20:21]
	v_lshlrev_b64 v[22:23], 12, v[22:23]
	v_lshlrev_b64 v[24:25], 12, v[24:25]
	v_lshlrev_b64 v[26:27], 12, v[26:27]
	v_lshlrev_b64 v[28:29], 12, v[28:29]
	v_lshlrev_b64 v[42:43], 12, v[42:43]
	v_lshlrev_b64 v[44:45], 12, v[44:45]
	v_lshlrev_b64 v[46:47], 12, v[46:47]
	v_lshl_add_u64 v[4:5], v[2:3], 0, v[4:5]
	v_lshl_add_u64 v[10:11], v[2:3], 0, v[10:11]
	v_lshl_add_u64 v[8:9], v[2:3], 0, v[8:9]
	v_lshl_add_u64 v[14:15], v[2:3], 0, v[14:15]
	v_lshl_add_u64 v[12:13], v[2:3], 0, v[12:13]
	v_lshl_add_u64 v[18:19], v[2:3], 0, v[18:19]
	v_lshl_add_u64 v[16:17], v[2:3], 0, v[16:17]
	v_lshl_add_u64 v[22:23], v[2:3], 0, v[22:23]
	v_lshl_add_u64 v[20:21], v[2:3], 0, v[20:21]
	v_lshl_add_u64 v[26:27], v[2:3], 0, v[26:27]
	v_lshl_add_u64 v[24:25], v[2:3], 0, v[24:25]
	v_lshl_add_u64 v[42:43], v[2:3], 0, v[42:43]
	v_lshl_add_u64 v[28:29], v[2:3], 0, v[28:29]
	v_lshl_add_u64 v[46:47], v[2:3], 0, v[46:47]
	v_lshl_add_u64 v[44:45], v[2:3], 0, v[44:45]
	global_load_dword v79, v[6:7], off
	global_load_dword v80, v[4:5], off
	global_load_dword v81, v[10:11], off
	global_load_dword v82, v[8:9], off
	global_load_dword v83, v[14:15], off
	global_load_dword v84, v[12:13], off
	global_load_dword v85, v[18:19], off
	global_load_dword v86, v[16:17], off
	global_load_dword v87, v[22:23], off
	global_load_dword v88, v[20:21], off
	global_load_dword v89, v[26:27], off
	global_load_dword v90, v[24:25], off
	global_load_dword v91, v[42:43], off
	global_load_dword v92, v[28:29], off
	global_load_dword v93, v[46:47], off
	global_load_dword v94, v[44:45], off
	s_add_i32 s9, s9, 16
	s_add_i32 s12, s12, 16
	s_add_i32 s14, s14, -16
	s_lshl_b32 s15, s12, 1
	s_lshl_b32 s16, s9, 1
	v_or_b32_e32 v170, s15, v1
	v_or_b32_e32 v181, s16, v32
	s_add_i32 s17, s15, 4
	s_add_i32 s18, s16, 4
	s_add_i32 s19, s15, 8
	s_add_i32 s20, s16, 8
	s_add_i32 s21, s15, 12
	s_add_i32 s22, s16, 12
	s_add_i32 s23, s15, 16
	s_add_i32 s26, s16, 16
	s_add_i32 s27, s15, 20
	s_add_i32 s34, s16, 20
	s_add_i32 s35, s15, 24
	s_add_i32 s40, s16, 24
	s_add_i32 s15, s15, 28
	s_add_i32 s16, s16, 28
	v_add_u32_e32 v146, s8, v181
	v_or_b32_e32 v188, s17, v1
	v_or_b32_e32 v189, s18, v32
	v_or_b32_e32 v190, s19, v1
	v_or_b32_e32 v191, s20, v32
	v_or_b32_e32 v192, s21, v1
	v_or_b32_e32 v193, s22, v32
	v_or_b32_e32 v194, s23, v1
	v_or_b32_e32 v195, s26, v32
	v_or_b32_e32 v196, s27, v1
	v_or_b32_e32 v197, s34, v32
	v_or_b32_e32 v211, s35, v1
	v_or_b32_e32 v216, s40, v32
	v_or_b32_e32 v217, s15, v1
	v_or_b32_e32 v218, s16, v32
	v_add_u32_e32 v144, s13, v170
	v_ashrrev_i32_e32 v147, 31, v146
	v_add_u32_e32 v148, s13, v188
	v_add_u32_e32 v150, s8, v189
	v_add_u32_e32 v152, s13, v190
	v_add_u32_e32 v154, s8, v191
	v_add_u32_e32 v156, s13, v192
	v_add_u32_e32 v158, s8, v193
	v_add_u32_e32 v160, s13, v194
	v_add_u32_e32 v162, s8, v195
	v_add_u32_e32 v164, s13, v196
	v_add_u32_e32 v166, s8, v197
	v_add_u32_e32 v168, s13, v211
	v_add_u32_e32 v182, s8, v216
	v_add_u32_e32 v184, s13, v217
	v_add_u32_e32 v186, s8, v218
	v_ashrrev_i32_e32 v145, 31, v144
	v_lshlrev_b64 v[146:147], 12, v[146:147]
	v_ashrrev_i32_e32 v151, 31, v150
	v_ashrrev_i32_e32 v149, 31, v148
	v_ashrrev_i32_e32 v155, 31, v154
	v_ashrrev_i32_e32 v153, 31, v152
	v_ashrrev_i32_e32 v159, 31, v158
	v_ashrrev_i32_e32 v157, 31, v156
	v_ashrrev_i32_e32 v163, 31, v162
	v_ashrrev_i32_e32 v161, 31, v160
	v_ashrrev_i32_e32 v167, 31, v166
	v_ashrrev_i32_e32 v165, 31, v164
	v_ashrrev_i32_e32 v183, 31, v182
	v_ashrrev_i32_e32 v169, 31, v168
	v_ashrrev_i32_e32 v187, 31, v186
; __device__ __forceinline__ void transpose_item(const float* W, int N, bf16_t* WT, int ldw, int drow0, int dk0, LAS float* scr, int k0, int n0, int lane) {
;     ...
;     for (int i = 0; i < 32; ++i) { const int kk = 2 * i + (lane >> 5); scr[kk * 33 + (lane & 31)] = W[(size_t)(k0 + kk) * N + n0 + (lane & 31)]; }
	v_ashrrev_i32_e32 v185, 31, v184
	v_lshlrev_b64 v[144:145], 12, v[144:145]
	v_lshl_add_u64 v[146:147], v[2:3], 0, v[146:147]
	v_lshlrev_b64 v[148:149], 12, v[148:149]
	v_lshlrev_b64 v[150:151], 12, v[150:151]
	v_lshlrev_b64 v[152:153], 12, v[152:153]
	v_lshlrev_b64 v[154:155], 12, v[154:155]
	v_lshlrev_b64 v[156:157], 12, v[156:157]
	v_lshlrev_b64 v[158:159], 12, v[158:159]
	v_lshlrev_b64 v[160:161], 12, v[160:161]
	v_lshlrev_b64 v[162:163], 12, v[162:163]
	v_lshlrev_b64 v[164:165], 12, v[164:165]
	v_lshlrev_b64 v[166:167], 12, v[166:167]
	v_lshlrev_b64 v[168:169], 12, v[168:169]
	v_lshlrev_b64 v[182:183], 12, v[182:183]
	v_lshlrev_b64 v[184:185], 12, v[184:185]
	v_lshlrev_b64 v[186:187], 12, v[186:187]
	v_lshl_add_u64 v[144:145], v[2:3], 0, v[144:145]
	v_lshl_add_u64 v[150:151], v[2:3], 0, v[150:151]
	v_lshl_add_u64 v[148:149], v[2:3], 0, v[148:149]
	v_lshl_add_u64 v[154:155], v[2:3], 0, v[154:155]
	v_lshl_add_u64 v[152:153], v[2:3], 0, v[152:153]
	v_lshl_add_u64 v[158:159], v[2:3], 0, v[158:159]
	v_lshl_add_u64 v[156:157], v[2:3], 0, v[156:157]
	v_lshl_add_u64 v[162:163], v[2:3], 0, v[162:163]
	v_lshl_add_u64 v[160:161], v[2:3], 0, v[160:161]
	v_lshl_add_u64 v[166:167], v[2:3], 0, v[166:167]
	v_lshl_add_u64 v[164:165], v[2:3], 0, v[164:165]
	v_lshl_add_u64 v[182:183], v[2:3], 0, v[182:183]
	v_lshl_add_u64 v[168:169], v[2:3], 0, v[168:169]
	v_lshl_add_u64 v[186:187], v[2:3], 0, v[186:187]
	v_lshl_add_u64 v[184:185], v[2:3], 0, v[184:185]
	global_load_dword v219, v[146:147], off
	global_load_dword v220, v[144:145], off
	global_load_dword v221, v[150:151], off
	global_load_dword v222, v[148:149], off
	global_load_dword v223, v[154:155], off
	global_load_dword v224, v[152:153], off
	global_load_dword v225, v[158:159], off
	global_load_dword v226, v[156:157], off
	global_load_dword v227, v[162:163], off
	global_load_dword v228, v[160:161], off
	global_load_dword v229, v[166:167], off
	global_load_dword v230, v[164:165], off
	global_load_dword v231, v[182:183], off
	global_load_dword v232, v[168:169], off
	global_load_dword v233, v[186:187], off
	global_load_dword v234, v[184:185], off
	v_mad_u64_u32 v[4:5], s[16:17], v41, s67, v[36:37]
	v_mad_u64_u32 v[6:7], s[16:17], v30, s67, v[36:37]
	v_mad_u64_u32 v[8:9], s[16:17], v49, s67, v[36:37]
	v_mad_u64_u32 v[10:11], s[16:17], v48, s67, v[36:37]
	v_mad_u64_u32 v[12:13], s[16:17], v51, s67, v[36:37]
	v_mad_u64_u32 v[14:15], s[16:17], v50, s67, v[36:37]
	v_mad_u64_u32 v[16:17], s[16:17], v53, s67, v[36:37]
	v_mad_u64_u32 v[18:19], s[16:17], v52, s67, v[36:37]
	v_mad_u64_u32 v[20:21], s[16:17], v55, s67, v[36:37]
	v_mad_u64_u32 v[22:23], s[16:17], v54, s67, v[36:37]
	v_mad_u64_u32 v[24:25], s[16:17], v57, s67, v[36:37]
	v_mad_u64_u32 v[26:27], s[16:17], v56, s67, v[36:37]
	v_mad_u64_u32 v[28:29], s[16:17], v76, s67, v[36:37]
	v_mad_u64_u32 v[42:43], s[16:17], v71, s67, v[36:37]
	v_mad_u64_u32 v[44:45], s[16:17], v78, s67, v[36:37]
	v_mad_u64_u32 v[46:47], s[16:17], v77, s67, v[36:37]
	s_waitcnt vmcnt(31)
	ds_write_b32 v4, v79
	s_waitcnt vmcnt(30)
	ds_write_b32 v6, v80
	s_waitcnt vmcnt(29)
	ds_write_b32 v8, v81
	s_waitcnt vmcnt(28)
	ds_write_b32 v10, v82
	s_waitcnt vmcnt(27)
	ds_write_b32 v12, v83
	s_waitcnt vmcnt(26)
	ds_write_b32 v14, v84
	s_waitcnt vmcnt(25)
	ds_write_b32 v16, v85
	s_waitcnt vmcnt(24)
	ds_write_b32 v18, v86
	s_waitcnt vmcnt(23)
	ds_write_b32 v20, v87
	s_waitcnt vmcnt(22)
	ds_write_b32 v22, v88
	s_waitcnt vmcnt(21)
	ds_write_b32 v24, v89
	s_waitcnt vmcnt(20)
	ds_write_b32 v26, v90
	s_waitcnt vmcnt(19)
	ds_write_b32 v28, v91
	s_waitcnt vmcnt(18)
	ds_write_b32 v42, v92
	s_waitcnt vmcnt(17)
	ds_write_b32 v44, v93
	s_waitcnt vmcnt(16)
; #define LAS __attribute__((address_space(3)))
; __device__ __forceinline__ unsigned cvtpk_s(float lo, float hi) { f32x2_t v = {lo, hi}; bf16x2_t b = __builtin_convertvector(v, bf16x2_t); return __builtin_bit_cast(unsigned, b); }
; #define LDS_WAIT() asm volatile("s_waitcnt lgkmcnt(0)" ::: "memory")
; __device__ __forceinline__ void transpose_item(const float* W, int N, bf16_t* WT, int ldw, int drow0, int dk0, LAS float* scr, int k0, int n0, int lane) {
;     ...
;     for (int i = 0; i < 32; ++i) { const int kk = 2 * i + (lane >> 5); scr[kk * 33 + (lane & 31)] = W[(size_t)(k0 + kk) * N + n0 + (lane & 31)]; }
;     LDS_WAIT(); asm volatile("" ::: "memory");
;     const int c = lane & 7;
; #pragma unroll
;     for (int j = 0; j < 4; ++j) { const int n = (lane >> 3) + 8 * j; const LAS float* s = scr + (8 * c) * 33 + n;
;         u32x4 o; o.x = cvtpk_s(s[0 * 33], s[1 * 33]); o.y = cvtpk_s(s[2 * 33], s[3 * 33]); o.z = cvtpk_s(s[4 * 33], s[5 * 33]); o.w = cvtpk_s(s[6 * 33], s[7 * 33]);
;         *(u32x4*)(WT + (size_t)(drow0 + n) * ldw + dk0 + k0 + 8 * c) = o; }
	ds_write_b32 v46, v94
	s_add_i32 s9, s9, 16
	s_add_i32 s12, s12, 16
	s_add_i32 s14, s14, -16
	v_mad_u64_u32 v[144:145], s[16:17], v181, s67, v[36:37]
	v_mad_u64_u32 v[146:147], s[16:17], v170, s67, v[36:37]
	v_mad_u64_u32 v[148:149], s[16:17], v189, s67, v[36:37]
	v_mad_u64_u32 v[150:151], s[16:17], v188, s67, v[36:37]
	v_mad_u64_u32 v[152:153], s[16:17], v191, s67, v[36:37]
	v_mad_u64_u32 v[154:155], s[16:17], v190, s67, v[36:37]
	v_mad_u64_u32 v[156:157], s[16:17], v193, s67, v[36:37]
	v_mad_u64_u32 v[158:159], s[16:17], v192, s67, v[36:37]
	v_mad_u64_u32 v[160:161], s[16:17], v195, s67, v[36:37]
	v_mad_u64_u32 v[162:163], s[16:17], v194, s67, v[36:37]
	v_mad_u64_u32 v[164:165], s[16:17], v197, s67, v[36:37]
	v_mad_u64_u32 v[166:167], s[16:17], v196, s67, v[36:37]
	v_mad_u64_u32 v[168:169], s[16:17], v216, s67, v[36:37]
	v_mad_u64_u32 v[182:183], s[16:17], v211, s67, v[36:37]
	v_mad_u64_u32 v[184:185], s[16:17], v218, s67, v[36:37]
	v_mad_u64_u32 v[186:187], s[16:17], v217, s67, v[36:37]
	s_waitcnt vmcnt(15)
	ds_write_b32 v144, v219
	s_waitcnt vmcnt(14)
	ds_write_b32 v146, v220
	s_waitcnt vmcnt(13)
	ds_write_b32 v148, v221
	s_waitcnt vmcnt(12)
	ds_write_b32 v150, v222
	s_waitcnt vmcnt(11)
	ds_write_b32 v152, v223
	s_waitcnt vmcnt(10)
	ds_write_b32 v154, v224
	s_waitcnt vmcnt(9)
	ds_write_b32 v156, v225
	s_waitcnt vmcnt(8)
	ds_write_b32 v158, v226
	s_waitcnt vmcnt(7)
	ds_write_b32 v160, v227
	s_waitcnt vmcnt(6)
	ds_write_b32 v162, v228
	s_waitcnt vmcnt(5)
	ds_write_b32 v164, v229
	s_waitcnt vmcnt(4)
	ds_write_b32 v166, v230
	s_waitcnt vmcnt(3)
	ds_write_b32 v168, v231
	s_waitcnt vmcnt(2)
	ds_write_b32 v182, v232
	s_waitcnt vmcnt(1)
	ds_write_b32 v184, v233
	s_waitcnt vmcnt(0)
	ds_write_b32 v186, v234
	s_mov_b32 s9, s41
	s_waitcnt lgkmcnt(0)
	s_lshl_b64 s[8:9], s[8:9], 1
	s_add_u32 s8, s4, s8
	s_addc_u32 s9, s5, s9
	v_lshlrev_b32_e32 v30, 1, v38
	ds_read2_b32 v[6:7], v60 offset0:33 offset1:41
	ds_read2_b32 v[8:9], v60 offset1:8
	ds_read2_b32 v[10:11], v60 offset0:66 offset1:74
	ds_read2_b32 v[12:13], v60 offset0:99 offset1:107
	ds_read2_b32 v[14:15], v60 offset0:132 offset1:140
	ds_read2_b32 v[16:17], v60 offset0:165 offset1:173
	ds_read2_b32 v[18:19], v60 offset0:198 offset1:206
	ds_read2_b32 v[20:21], v60 offset0:231 offset1:239
	v_lshl_add_u64 v[2:3], s[8:9], 0, v[30:31]
	v_lshl_add_u64 v[22:23], v[2:3], 0, s[46:47]
	s_waitcnt lgkmcnt(6)
	v_cvt_pk_bf16_f32 v2, v8, v6
	v_or_b32_e32 v6, s11, v59
	v_mul_u32_u24_e32 v6, 0xb00, v6
	v_lshlrev_b32_e32 v30, 1, v6
	s_waitcnt lgkmcnt(4)
	v_cvt_pk_bf16_f32 v3, v10, v12
	s_waitcnt lgkmcnt(2)
	v_cvt_pk_bf16_f32 v4, v14, v16
	s_waitcnt lgkmcnt(0)
	v_cvt_pk_bf16_f32 v5, v18, v20
	v_lshl_add_u64 v[24:25], v[22:23], 0, v[30:31]
	v_or_b32_e32 v6, s11, v61
	global_store_dwordx4 v[24:25], v[2:5], off
	v_mul_u32_u24_e32 v6, 0xb00, v6
	v_lshlrev_b32_e32 v30, 1, v6
	v_cvt_pk_bf16_f32 v2, v9, v7
	v_cvt_pk_bf16_f32 v3, v11, v13
	v_cvt_pk_bf16_f32 v4, v15, v17
	v_cvt_pk_bf16_f32 v5, v19, v21
	ds_read2_b32 v[8:9], v60 offset0:16 offset1:24
	ds_read2_b32 v[10:11], v60 offset0:49 offset1:57
	ds_read2_b32 v[12:13], v60 offset0:82 offset1:90
	ds_read2_b32 v[14:15], v60 offset0:115 offset1:123
	ds_read2_b32 v[16:17], v60 offset0:148 offset1:156
	ds_read2_b32 v[18:19], v60 offset0:181 offset1:189
	ds_read2_b32 v[20:21], v60 offset0:214 offset1:222
	ds_read2_b32 v[24:25], v60 offset0:247 offset1:255
	v_lshl_add_u64 v[6:7], v[22:23], 0, v[30:31]
	global_store_dwordx4 v[6:7], v[2:5], off
	v_or_b32_e32 v6, s11, v62
	v_mul_u32_u24_e32 v6, 0xb00, v6
	v_lshlrev_b32_e32 v30, 1, v6
	s_waitcnt lgkmcnt(6)
	v_cvt_pk_bf16_f32 v2, v8, v10
	s_waitcnt lgkmcnt(4)
	v_cvt_pk_bf16_f32 v3, v12, v14
	s_waitcnt lgkmcnt(2)
	v_cvt_pk_bf16_f32 v4, v16, v18
	s_waitcnt lgkmcnt(0)
	v_cvt_pk_bf16_f32 v5, v20, v24
	v_lshl_add_u64 v[6:7], v[22:23], 0, v[30:31]
	global_store_dwordx4 v[6:7], v[2:5], off
	v_or_b32_e32 v6, s11, v63
	v_mul_u32_u24_e32 v6, 0xb00, v6
	v_lshlrev_b32_e32 v30, 1, v6
	v_cvt_pk_bf16_f32 v2, v9, v11
	v_cvt_pk_bf16_f32 v3, v13, v15
	v_cvt_pk_bf16_f32 v4, v17, v19
	v_cvt_pk_bf16_f32 v5, v21, v25
	v_lshl_add_u64 v[6:7], v[22:23], 0, v[30:31]
	global_store_dwordx4 v[6:7], v[2:5], off
	s_waitcnt lgkmcnt(0)

; #define LAS __attribute__((address_space(3)))
; __device__ __forceinline__ void transpose_item(const float* W, int N, bf16_t* WT, int ldw, int drow0, int dk0, LAS float* scr, int k0, int n0, int lane) {
; #pragma unroll 8
;     for (int i = 0; i < 32; ++i) { const int kk = 2 * i + (lane >> 5); scr[kk * 33 + (lane & 31)] = W[(size_t)(k0 + kk) * N + n0 + (lane & 31)]; }
.LBB0_50:
	s_lshl_b32 s16, s14, 1
	s_lshl_b32 s17, s8, 1
	v_or_b32_e32 v30, s16, v1
	v_or_b32_e32 v41, s17, v32
	s_add_i32 s18, s16, 4
	s_add_i32 s19, s17, 4
	s_add_i32 s20, s16, 8
	s_add_i32 s21, s17, 8
	s_add_i32 s22, s16, 12
	s_add_i32 s23, s17, 12
	s_add_i32 s26, s16, 16
	s_add_i32 s27, s17, 16
	s_add_i32 s34, s16, 20
	s_add_i32 s35, s17, 20
	s_add_i32 s40, s16, 24
	s_add_i32 s64, s17, 24
	s_add_i32 s16, s16, 28
	s_add_i32 s17, s17, 28
	v_add_u32_e32 v4, s12, v41
	v_or_b32_e32 v48, s18, v1
	v_or_b32_e32 v49, s19, v32
	v_or_b32_e32 v50, s20, v1
	v_or_b32_e32 v51, s21, v32
	v_or_b32_e32 v52, s22, v1
	v_or_b32_e32 v53, s23, v32
	v_or_b32_e32 v54, s26, v1
	v_or_b32_e32 v55, s27, v32
	v_or_b32_e32 v56, s34, v1
	v_or_b32_e32 v57, s35, v32
	v_or_b32_e32 v71, s40, v1
	v_or_b32_e32 v76, s64, v32
	v_or_b32_e32 v77, s16, v1
	v_or_b32_e32 v78, s17, v32
	v_add_u32_e32 v6, s13, v30
	v_mad_u64_u32 v[4:5], s[16:17], v4, s81, v[2:3]
	v_add_u32_e32 v10, s13, v48
	v_add_u32_e32 v8, s12, v49
	v_add_u32_e32 v14, s13, v50
	v_add_u32_e32 v12, s12, v51
	v_add_u32_e32 v18, s13, v52
	v_add_u32_e32 v16, s12, v53
	v_add_u32_e32 v22, s13, v54
	v_add_u32_e32 v20, s12, v55
	v_add_u32_e32 v26, s13, v56
	v_add_u32_e32 v24, s12, v57
	v_add_u32_e32 v42, s13, v71
	v_add_u32_e32 v28, s12, v76
	v_add_u32_e32 v46, s13, v77
	v_add_u32_e32 v44, s12, v78
	v_mad_u64_u32 v[6:7], s[16:17], v6, s81, v[2:3]
	v_mad_u64_u32 v[8:9], s[16:17], v8, s81, v[2:3]
	v_mad_u64_u32 v[10:11], s[16:17], v10, s81, v[2:3]
	v_mad_u64_u32 v[12:13], s[16:17], v12, s81, v[2:3]
	v_mad_u64_u32 v[14:15], s[16:17], v14, s81, v[2:3]
	v_mad_u64_u32 v[16:17], s[16:17], v16, s81, v[2:3]
	v_mad_u64_u32 v[18:19], s[16:17], v18, s81, v[2:3]
	v_mad_u64_u32 v[20:21], s[16:17], v20, s81, v[2:3]
	v_mad_u64_u32 v[22:23], s[16:17], v22, s81, v[2:3]
	v_mad_u64_u32 v[24:25], s[16:17], v24, s81, v[2:3]
	v_mad_u64_u32 v[26:27], s[16:17], v26, s81, v[2:3]
	v_mad_u64_u32 v[28:29], s[16:17], v28, s81, v[2:3]
	v_mad_u64_u32 v[42:43], s[16:17], v42, s81, v[2:3]
	v_mad_u64_u32 v[44:45], s[16:17], v44, s81, v[2:3]
	v_mad_u64_u32 v[46:47], s[16:17], v46, s81, v[2:3]
	global_load_dword v79, v[4:5], off
	global_load_dword v80, v[6:7], off
	global_load_dword v81, v[8:9], off
	global_load_dword v82, v[10:11], off
	global_load_dword v83, v[12:13], off
	global_load_dword v84, v[14:15], off
	global_load_dword v85, v[16:17], off
	global_load_dword v86, v[18:19], off
	global_load_dword v87, v[20:21], off
	global_load_dword v88, v[22:23], off
	global_load_dword v89, v[24:25], off
	global_load_dword v90, v[26:27], off
	global_load_dword v91, v[28:29], off
	global_load_dword v92, v[42:43], off
	global_load_dword v93, v[44:45], off
	global_load_dword v94, v[46:47], off
	s_add_i32 s8, s8, 16
	s_add_i32 s14, s14, 16
	s_add_i32 s15, s15, -16
	s_lshl_b32 s16, s14, 1
	s_lshl_b32 s17, s8, 1
	v_or_b32_e32 v170, s16, v1
	v_or_b32_e32 v181, s17, v32
	s_add_i32 s18, s16, 4
	s_add_i32 s19, s17, 4
	s_add_i32 s20, s16, 8
	s_add_i32 s21, s17, 8
	s_add_i32 s22, s16, 12
	s_add_i32 s23, s17, 12
	s_add_i32 s26, s16, 16
	s_add_i32 s27, s17, 16
	s_add_i32 s34, s16, 20
	s_add_i32 s35, s17, 20
	s_add_i32 s40, s16, 24
	s_add_i32 s64, s17, 24
	s_add_i32 s16, s16, 28
	s_add_i32 s17, s17, 28
	v_add_u32_e32 v144, s12, v181
	v_or_b32_e32 v188, s18, v1
	v_or_b32_e32 v189, s19, v32
	v_or_b32_e32 v190, s20, v1
	v_or_b32_e32 v191, s21, v32
	v_or_b32_e32 v192, s22, v1
	v_or_b32_e32 v193, s23, v32
	v_or_b32_e32 v194, s26, v1
	v_or_b32_e32 v195, s27, v32
	v_or_b32_e32 v196, s34, v1
	v_or_b32_e32 v197, s35, v32
	v_or_b32_e32 v211, s40, v1
	v_or_b32_e32 v216, s64, v32
	v_or_b32_e32 v217, s16, v1
	v_or_b32_e32 v218, s17, v32
	v_add_u32_e32 v146, s13, v170
	v_mad_u64_u32 v[144:145], s[16:17], v144, s81, v[2:3]
	v_add_u32_e32 v150, s13, v188
	v_add_u32_e32 v148, s12, v189
	v_add_u32_e32 v154, s13, v190
	v_add_u32_e32 v152, s12, v191
	v_add_u32_e32 v158, s13, v192
	v_add_u32_e32 v156, s12, v193
	v_add_u32_e32 v162, s13, v194
	v_add_u32_e32 v160, s12, v195
	v_add_u32_e32 v166, s13, v196
	v_add_u32_e32 v164, s12, v197
	v_add_u32_e32 v182, s13, v211
	v_add_u32_e32 v168, s12, v216
	v_add_u32_e32 v186, s13, v217
	v_add_u32_e32 v184, s12, v218
	v_mad_u64_u32 v[146:147], s[16:17], v146, s81, v[2:3]
	v_mad_u64_u32 v[148:149], s[16:17], v148, s81, v[2:3]
	v_mad_u64_u32 v[150:151], s[16:17], v150, s81, v[2:3]
	v_mad_u64_u32 v[152:153], s[16:17], v152, s81, v[2:3]
	v_mad_u64_u32 v[154:155], s[16:17], v154, s81, v[2:3]
	v_mad_u64_u32 v[156:157], s[16:17], v156, s81, v[2:3]
	v_mad_u64_u32 v[158:159], s[16:17], v158, s81, v[2:3]
	v_mad_u64_u32 v[160:161], s[16:17], v160, s81, v[2:3]
	v_mad_u64_u32 v[162:163], s[16:17], v162, s81, v[2:3]
	v_mad_u64_u32 v[164:165], s[16:17], v164, s81, v[2:3]
	v_mad_u64_u32 v[166:167], s[16:17], v166, s81, v[2:3]
	v_mad_u64_u32 v[168:169], s[16:17], v168, s81, v[2:3]
	v_mad_u64_u32 v[182:183], s[16:17], v182, s81, v[2:3]
	v_mad_u64_u32 v[184:185], s[16:17], v184, s81, v[2:3]
	v_mad_u64_u32 v[186:187], s[16:17], v186, s81, v[2:3]
	global_load_dword v219, v[144:145], off
	global_load_dword v220, v[146:147], off
	global_load_dword v221, v[148:149], off
	global_load_dword v222, v[150:151], off
	global_load_dword v223, v[152:153], off
	global_load_dword v224, v[154:155], off
	global_load_dword v225, v[156:157], off
	global_load_dword v226, v[158:159], off
	global_load_dword v227, v[160:161], off
	global_load_dword v228, v[162:163], off
	global_load_dword v229, v[164:165], off
	global_load_dword v230, v[166:167], off
	global_load_dword v231, v[168:169], off
	global_load_dword v232, v[182:183], off
	global_load_dword v233, v[184:185], off
	global_load_dword v234, v[186:187], off
	v_mad_u64_u32 v[4:5], s[16:17], v41, s67, v[36:37]
	v_mad_u64_u32 v[6:7], s[16:17], v30, s67, v[36:37]
	v_mad_u64_u32 v[8:9], s[16:17], v49, s67, v[36:37]
	v_mad_u64_u32 v[10:11], s[16:17], v48, s67, v[36:37]
	v_mad_u64_u32 v[12:13], s[16:17], v51, s67, v[36:37]
	v_mad_u64_u32 v[14:15], s[16:17], v50, s67, v[36:37]
	v_mad_u64_u32 v[16:17], s[16:17], v53, s67, v[36:37]
	v_mad_u64_u32 v[18:19], s[16:17], v52, s67, v[36:37]
	v_mad_u64_u32 v[20:21], s[16:17], v55, s67, v[36:37]
	v_mad_u64_u32 v[22:23], s[16:17], v54, s67, v[36:37]
	v_mad_u64_u32 v[24:25], s[16:17], v57, s67, v[36:37]
	v_mad_u64_u32 v[26:27], s[16:17], v56, s67, v[36:37]
	v_mad_u64_u32 v[28:29], s[16:17], v76, s67, v[36:37]
	v_mad_u64_u32 v[42:43], s[16:17], v71, s67, v[36:37]
	v_mad_u64_u32 v[44:45], s[16:17], v78, s67, v[36:37]
	v_mad_u64_u32 v[46:47], s[16:17], v77, s67, v[36:37]
	s_waitcnt vmcnt(31)
; #define LAS __attribute__((address_space(3)))
; __device__ __forceinline__ unsigned cvtpk_s(float lo, float hi) { f32x2_t v = {lo, hi}; bf16x2_t b = __builtin_convertvector(v, bf16x2_t); return __builtin_bit_cast(unsigned, b); }
; #define LDS_WAIT() asm volatile("s_waitcnt lgkmcnt(0)" ::: "memory")
; __device__ __forceinline__ void transpose_item(const float* W, int N, bf16_t* WT, int ldw, int drow0, int dk0, LAS float* scr, int k0, int n0, int lane) {
;     ...
;     for (int i = 0; i < 32; ++i) { const int kk = 2 * i + (lane >> 5); scr[kk * 33 + (lane & 31)] = W[(size_t)(k0 + kk) * N + n0 + (lane & 31)]; }
;     LDS_WAIT(); asm volatile("" ::: "memory");
;     const int c = lane & 7;
; #pragma unroll
;     for (int j = 0; j < 4; ++j) { const int n = (lane >> 3) + 8 * j; const LAS float* s = scr + (8 * c) * 33 + n;
;         u32x4 o; o.x = cvtpk_s(s[0 * 33], s[1 * 33]); o.y = cvtpk_s(s[2 * 33], s[3 * 33]); o.z = cvtpk_s(s[4 * 33], s[5 * 33]); o.w = cvtpk_s(s[6 * 33], s[7 * 33]);
;         *(u32x4*)(WT + (size_t)(drow0 + n) * ldw + dk0 + k0 + 8 * c) = o; }
	ds_write_b32 v4, v79
	s_waitcnt vmcnt(30)
	ds_write_b32 v6, v80
	s_waitcnt vmcnt(29)
	ds_write_b32 v8, v81
	s_waitcnt vmcnt(28)
	ds_write_b32 v10, v82
	s_waitcnt vmcnt(27)
	ds_write_b32 v12, v83
	s_waitcnt vmcnt(26)
	ds_write_b32 v14, v84
	s_waitcnt vmcnt(25)
	ds_write_b32 v16, v85
	s_waitcnt vmcnt(24)
	ds_write_b32 v18, v86
	s_waitcnt vmcnt(23)
	ds_write_b32 v20, v87
	s_waitcnt vmcnt(22)
	ds_write_b32 v22, v88
	s_waitcnt vmcnt(21)
	ds_write_b32 v24, v89
	s_waitcnt vmcnt(20)
	ds_write_b32 v26, v90
	s_waitcnt vmcnt(19)
	ds_write_b32 v28, v91
	s_waitcnt vmcnt(18)
	ds_write_b32 v42, v92
	s_waitcnt vmcnt(17)
	ds_write_b32 v44, v93
	s_waitcnt vmcnt(16)
	ds_write_b32 v46, v94
	s_add_i32 s8, s8, 16
	s_add_i32 s14, s14, 16
	s_add_i32 s15, s15, -16
	v_mad_u64_u32 v[144:145], s[16:17], v181, s67, v[36:37]
	v_mad_u64_u32 v[146:147], s[16:17], v170, s67, v[36:37]
	v_mad_u64_u32 v[148:149], s[16:17], v189, s67, v[36:37]
	v_mad_u64_u32 v[150:151], s[16:17], v188, s67, v[36:37]
	v_mad_u64_u32 v[152:153], s[16:17], v191, s67, v[36:37]
	v_mad_u64_u32 v[154:155], s[16:17], v190, s67, v[36:37]
	v_mad_u64_u32 v[156:157], s[16:17], v193, s67, v[36:37]
	v_mad_u64_u32 v[158:159], s[16:17], v192, s67, v[36:37]
	v_mad_u64_u32 v[160:161], s[16:17], v195, s67, v[36:37]
	v_mad_u64_u32 v[162:163], s[16:17], v194, s67, v[36:37]
	v_mad_u64_u32 v[164:165], s[16:17], v197, s67, v[36:37]
	v_mad_u64_u32 v[166:167], s[16:17], v196, s67, v[36:37]
	v_mad_u64_u32 v[168:169], s[16:17], v216, s67, v[36:37]
	v_mad_u64_u32 v[182:183], s[16:17], v211, s67, v[36:37]
	v_mad_u64_u32 v[184:185], s[16:17], v218, s67, v[36:37]
	v_mad_u64_u32 v[186:187], s[16:17], v217, s67, v[36:37]
	s_waitcnt vmcnt(15)
	ds_write_b32 v144, v219
	s_waitcnt vmcnt(14)
	ds_write_b32 v146, v220
	s_waitcnt vmcnt(13)
	ds_write_b32 v148, v221
	s_waitcnt vmcnt(12)
	ds_write_b32 v150, v222
	s_waitcnt vmcnt(11)
	ds_write_b32 v152, v223
	s_waitcnt vmcnt(10)
	ds_write_b32 v154, v224
	s_waitcnt vmcnt(9)
	ds_write_b32 v156, v225
	s_waitcnt vmcnt(8)
	ds_write_b32 v158, v226
	s_waitcnt vmcnt(7)
	ds_write_b32 v160, v227
	s_waitcnt vmcnt(6)
	ds_write_b32 v162, v228
	s_waitcnt vmcnt(5)
	ds_write_b32 v164, v229
	s_waitcnt vmcnt(4)
	ds_write_b32 v166, v230
	s_waitcnt vmcnt(3)
	ds_write_b32 v168, v231
	s_waitcnt vmcnt(2)
	ds_write_b32 v182, v232
	s_waitcnt vmcnt(1)
	ds_write_b32 v184, v233
	s_waitcnt vmcnt(0)
	ds_write_b32 v186, v234
	s_waitcnt lgkmcnt(0)
	s_and_b32 s8, 0xffff, s9
	s_lshl_b32 s8, s8, 1
	ds_read2_b32 v[6:7], v60 offset0:33 offset1:41
	ds_read2_b32 v[8:9], v60 offset1:8
	ds_read2_b32 v[10:11], v60 offset0:66 offset1:74
	ds_read2_b32 v[12:13], v60 offset0:99 offset1:107
	ds_read2_b32 v[14:15], v60 offset0:132 offset1:140
	ds_read2_b32 v[16:17], v60 offset0:165 offset1:173
	ds_read2_b32 v[18:19], v60 offset0:198 offset1:206
	ds_read2_b32 v[20:21], v60 offset0:231 offset1:239
	s_add_u32 s8, s4, s8
	s_addc_u32 s9, s5, 0
	v_lshlrev_b32_e32 v30, 1, v38
	v_lshl_add_u64 v[2:3], s[8:9], 0, v[30:31]
	v_add_u32_e32 v30, s11, v59
	v_lshl_add_u64 v[22:23], v[2:3], 0, s[48:49]
	v_lshlrev_b64 v[24:25], 11, v[30:31]
	s_waitcnt lgkmcnt(6)
	v_cvt_pk_bf16_f32 v2, v8, v6
	s_waitcnt lgkmcnt(4)
	v_cvt_pk_bf16_f32 v3, v10, v12
	s_waitcnt lgkmcnt(2)
	v_cvt_pk_bf16_f32 v4, v14, v16
	s_waitcnt lgkmcnt(0)
	v_cvt_pk_bf16_f32 v5, v18, v20
	v_lshl_add_u64 v[24:25], v[22:23], 0, v[24:25]
	global_store_dwordx4 v[24:25], v[2:5], off
	v_add_u32_e32 v30, s11, v61
	s_nop 0
	v_cvt_pk_bf16_f32 v2, v9, v7
	v_cvt_pk_bf16_f32 v3, v11, v13
	v_cvt_pk_bf16_f32 v4, v15, v17
	v_cvt_pk_bf16_f32 v5, v19, v21
	ds_read2_b32 v[8:9], v60 offset0:49 offset1:57
	ds_read2_b32 v[10:11], v60 offset0:16 offset1:24
	ds_read2_b32 v[12:13], v60 offset0:82 offset1:90
	ds_read2_b32 v[14:15], v60 offset0:115 offset1:123
	ds_read2_b32 v[16:17], v60 offset0:148 offset1:156
	ds_read2_b32 v[18:19], v60 offset0:181 offset1:189
	ds_read2_b32 v[20:21], v60 offset0:214 offset1:222
	ds_read2_b32 v[24:25], v60 offset0:247 offset1:255
	v_lshlrev_b64 v[6:7], 11, v[30:31]
	v_lshl_add_u64 v[6:7], v[22:23], 0, v[6:7]
	v_add_u32_e32 v30, s11, v62
	global_store_dwordx4 v[6:7], v[2:5], off
	v_lshlrev_b64 v[6:7], 11, v[30:31]
	v_lshl_add_u64 v[6:7], v[22:23], 0, v[6:7]
	s_waitcnt lgkmcnt(6)
	v_cvt_pk_bf16_f32 v2, v10, v8
	s_waitcnt lgkmcnt(4)
	v_cvt_pk_bf16_f32 v3, v12, v14
	s_waitcnt lgkmcnt(2)
	v_cvt_pk_bf16_f32 v4, v16, v18
	s_waitcnt lgkmcnt(0)
	v_cvt_pk_bf16_f32 v5, v20, v24
	v_add_u32_e32 v30, s11, v63
	global_store_dwordx4 v[6:7], v[2:5], off
	v_lshlrev_b64 v[6:7], 11, v[30:31]
	v_lshl_add_u64 v[6:7], v[22:23], 0, v[6:7]
	v_cvt_pk_bf16_f32 v2, v11, v9
	v_cvt_pk_bf16_f32 v3, v13, v15
	v_cvt_pk_bf16_f32 v4, v17, v19
	v_cvt_pk_bf16_f32 v5, v21, v25
	global_store_dwordx4 v[6:7], v[2:5], off
	s_waitcnt lgkmcnt(0)

; #define LAS __attribute__((address_space(3)))
; __device__ __forceinline__ void transpose_item(const float* W, int N, bf16_t* WT, int ldw, int drow0, int dk0, LAS float* scr, int k0, int n0, int lane) {
; #pragma unroll 8
;     for (int i = 0; i < 32; ++i) { const int kk = 2 * i + (lane >> 5); scr[kk * 33 + (lane & 31)] = W[(size_t)(k0 + kk) * N + n0 + (lane & 31)]; }
.LBB0_55:
	s_lshl_b32 s15, s12, 1
	s_lshl_b32 s16, s9, 1
	v_or_b32_e32 v30, s15, v1
	v_or_b32_e32 v41, s16, v32
	s_add_i32 s17, s15, 4
	s_add_i32 s18, s16, 4
	s_add_i32 s19, s15, 8
	s_add_i32 s20, s16, 8
	s_add_i32 s21, s15, 12
	s_add_i32 s22, s16, 12
	s_add_i32 s23, s15, 16
	s_add_i32 s26, s16, 16
	s_add_i32 s27, s15, 20
	s_add_i32 s34, s16, 20
	s_add_i32 s35, s15, 24
	s_add_i32 s40, s16, 24
	s_add_i32 s15, s15, 28
	s_add_i32 s16, s16, 28
	v_add_u32_e32 v6, s8, v41
	v_or_b32_e32 v48, s17, v1
	v_or_b32_e32 v49, s18, v32
	v_or_b32_e32 v50, s19, v1
	v_or_b32_e32 v51, s20, v32
	v_or_b32_e32 v52, s21, v1
	v_or_b32_e32 v53, s22, v32
	v_or_b32_e32 v54, s23, v1
	v_or_b32_e32 v55, s26, v32
	v_or_b32_e32 v56, s27, v1
	v_or_b32_e32 v57, s34, v32
	v_or_b32_e32 v71, s35, v1
	v_or_b32_e32 v76, s40, v32
	v_or_b32_e32 v77, s15, v1
	v_or_b32_e32 v78, s16, v32
	v_add_u32_e32 v4, s13, v30
	v_ashrrev_i32_e32 v7, 31, v6
	v_add_u32_e32 v8, s13, v48
	v_add_u32_e32 v10, s8, v49
	v_add_u32_e32 v12, s13, v50
	v_add_u32_e32 v14, s8, v51
	v_add_u32_e32 v16, s13, v52
	v_add_u32_e32 v18, s8, v53
	v_add_u32_e32 v20, s13, v54
	v_add_u32_e32 v22, s8, v55
	v_add_u32_e32 v24, s13, v56
	v_add_u32_e32 v26, s8, v57
	v_add_u32_e32 v28, s13, v71
	v_add_u32_e32 v42, s8, v76
	v_add_u32_e32 v44, s13, v77
	v_add_u32_e32 v46, s8, v78
	v_ashrrev_i32_e32 v5, 31, v4
	v_lshlrev_b64 v[6:7], 12, v[6:7]
	v_ashrrev_i32_e32 v11, 31, v10
	v_ashrrev_i32_e32 v9, 31, v8
	v_ashrrev_i32_e32 v15, 31, v14
	v_ashrrev_i32_e32 v13, 31, v12
	v_ashrrev_i32_e32 v19, 31, v18
	v_ashrrev_i32_e32 v17, 31, v16
	v_ashrrev_i32_e32 v23, 31, v22
	v_ashrrev_i32_e32 v21, 31, v20
	v_ashrrev_i32_e32 v27, 31, v26
	v_ashrrev_i32_e32 v25, 31, v24
	v_ashrrev_i32_e32 v43, 31, v42
	v_ashrrev_i32_e32 v29, 31, v28
	v_ashrrev_i32_e32 v47, 31, v46
	v_ashrrev_i32_e32 v45, 31, v44
	v_lshlrev_b64 v[4:5], 12, v[4:5]
	v_lshl_add_u64 v[6:7], v[2:3], 0, v[6:7]
	v_lshlrev_b64 v[8:9], 12, v[8:9]
	v_lshlrev_b64 v[10:11], 12, v[10:11]
	v_lshlrev_b64 v[12:13], 12, v[12:13]
	v_lshlrev_b64 v[14:15], 12, v[14:15]
	v_lshlrev_b64 v[16:17], 12, v[16:17]
	v_lshlrev_b64 v[18:19], 12, v[18:19]
	v_lshlrev_b64 v[20:21], 12, v[20:21]
	v_lshlrev_b64 v[22:23], 12, v[22:23]
	v_lshlrev_b64 v[24:25], 12, v[24:25]
	v_lshlrev_b64 v[26:27], 12, v[26:27]
	v_lshlrev_b64 v[28:29], 12, v[28:29]
	v_lshlrev_b64 v[42:43], 12, v[42:43]
	v_lshlrev_b64 v[44:45], 12, v[44:45]
	v_lshlrev_b64 v[46:47], 12, v[46:47]
	v_lshl_add_u64 v[4:5], v[2:3], 0, v[4:5]
	v_lshl_add_u64 v[10:11], v[2:3], 0, v[10:11]
	v_lshl_add_u64 v[8:9], v[2:3], 0, v[8:9]
	v_lshl_add_u64 v[14:15], v[2:3], 0, v[14:15]
	v_lshl_add_u64 v[12:13], v[2:3], 0, v[12:13]
	v_lshl_add_u64 v[18:19], v[2:3], 0, v[18:19]
	v_lshl_add_u64 v[16:17], v[2:3], 0, v[16:17]
	v_lshl_add_u64 v[22:23], v[2:3], 0, v[22:23]
	v_lshl_add_u64 v[20:21], v[2:3], 0, v[20:21]
	v_lshl_add_u64 v[26:27], v[2:3], 0, v[26:27]
	v_lshl_add_u64 v[24:25], v[2:3], 0, v[24:25]
	v_lshl_add_u64 v[42:43], v[2:3], 0, v[42:43]
	v_lshl_add_u64 v[28:29], v[2:3], 0, v[28:29]
	v_lshl_add_u64 v[46:47], v[2:3], 0, v[46:47]
	v_lshl_add_u64 v[44:45], v[2:3], 0, v[44:45]
	global_load_dword v79, v[6:7], off
	global_load_dword v80, v[4:5], off
	global_load_dword v81, v[10:11], off
	global_load_dword v82, v[8:9], off
	global_load_dword v83, v[14:15], off
	global_load_dword v84, v[12:13], off
	global_load_dword v85, v[18:19], off
	global_load_dword v86, v[16:17], off
	global_load_dword v87, v[22:23], off
	global_load_dword v88, v[20:21], off
	global_load_dword v89, v[26:27], off
	global_load_dword v90, v[24:25], off
	global_load_dword v91, v[42:43], off
	global_load_dword v92, v[28:29], off
	global_load_dword v93, v[46:47], off
	global_load_dword v94, v[44:45], off
	s_add_i32 s9, s9, 16
	s_add_i32 s12, s12, 16
	s_add_i32 s14, s14, -16
	s_lshl_b32 s15, s12, 1
	s_lshl_b32 s16, s9, 1
	v_or_b32_e32 v170, s15, v1
	v_or_b32_e32 v181, s16, v32
	s_add_i32 s17, s15, 4
	s_add_i32 s18, s16, 4
	s_add_i32 s19, s15, 8
	s_add_i32 s20, s16, 8
	s_add_i32 s21, s15, 12
	s_add_i32 s22, s16, 12
	s_add_i32 s23, s15, 16
	s_add_i32 s26, s16, 16
	s_add_i32 s27, s15, 20
	s_add_i32 s34, s16, 20
	s_add_i32 s35, s15, 24
	s_add_i32 s40, s16, 24
	s_add_i32 s15, s15, 28
	s_add_i32 s16, s16, 28
	v_add_u32_e32 v146, s8, v181
	v_or_b32_e32 v188, s17, v1
	v_or_b32_e32 v189, s18, v32
	v_or_b32_e32 v190, s19, v1
	v_or_b32_e32 v191, s20, v32
	v_or_b32_e32 v192, s21, v1
	v_or_b32_e32 v193, s22, v32
	v_or_b32_e32 v194, s23, v1
	v_or_b32_e32 v195, s26, v32
	v_or_b32_e32 v196, s27, v1
	v_or_b32_e32 v197, s34, v32
	v_or_b32_e32 v211, s35, v1
	v_or_b32_e32 v216, s40, v32
	v_or_b32_e32 v217, s15, v1
	v_or_b32_e32 v218, s16, v32
	v_add_u32_e32 v144, s13, v170
	v_ashrrev_i32_e32 v147, 31, v146
	v_add_u32_e32 v148, s13, v188
	v_add_u32_e32 v150, s8, v189
	v_add_u32_e32 v152, s13, v190
	v_add_u32_e32 v154, s8, v191
	v_add_u32_e32 v156, s13, v192
	v_add_u32_e32 v158, s8, v193
	v_add_u32_e32 v160, s13, v194
	v_add_u32_e32 v162, s8, v195
	v_add_u32_e32 v164, s13, v196
	v_add_u32_e32 v166, s8, v197
	v_add_u32_e32 v168, s13, v211
	v_add_u32_e32 v182, s8, v216
	v_add_u32_e32 v184, s13, v217
	v_add_u32_e32 v186, s8, v218
	v_ashrrev_i32_e32 v145, 31, v144
	v_lshlrev_b64 v[146:147], 12, v[146:147]
	v_ashrrev_i32_e32 v151, 31, v150
	v_ashrrev_i32_e32 v149, 31, v148
	v_ashrrev_i32_e32 v155, 31, v154
	v_ashrrev_i32_e32 v153, 31, v152
	v_ashrrev_i32_e32 v159, 31, v158
	v_ashrrev_i32_e32 v157, 31, v156
	v_ashrrev_i32_e32 v163, 31, v162
	v_ashrrev_i32_e32 v161, 31, v160
	v_ashrrev_i32_e32 v167, 31, v166
	v_ashrrev_i32_e32 v165, 31, v164
	v_ashrrev_i32_e32 v183, 31, v182
	v_ashrrev_i32_e32 v169, 31, v168
	v_ashrrev_i32_e32 v187, 31, v186
; __device__ __forceinline__ void transpose_item(const float* W, int N, bf16_t* WT, int ldw, int drow0, int dk0, LAS float* scr, int k0, int n0, int lane) {
;     ...
;     for (int i = 0; i < 32; ++i) { const int kk = 2 * i + (lane >> 5); scr[kk * 33 + (lane & 31)] = W[(size_t)(k0 + kk) * N + n0 + (lane & 31)]; }
	v_ashrrev_i32_e32 v185, 31, v184
	v_lshlrev_b64 v[144:145], 12, v[144:145]
	v_lshl_add_u64 v[146:147], v[2:3], 0, v[146:147]
	v_lshlrev_b64 v[148:149], 12, v[148:149]
	v_lshlrev_b64 v[150:151], 12, v[150:151]
	v_lshlrev_b64 v[152:153], 12, v[152:153]
	v_lshlrev_b64 v[154:155], 12, v[154:155]
	v_lshlrev_b64 v[156:157], 12, v[156:157]
	v_lshlrev_b64 v[158:159], 12, v[158:159]
	v_lshlrev_b64 v[160:161], 12, v[160:161]
	v_lshlrev_b64 v[162:163], 12, v[162:163]
	v_lshlrev_b64 v[164:165], 12, v[164:165]
	v_lshlrev_b64 v[166:167], 12, v[166:167]
	v_lshlrev_b64 v[168:169], 12, v[168:169]
	v_lshlrev_b64 v[182:183], 12, v[182:183]
	v_lshlrev_b64 v[184:185], 12, v[184:185]
	v_lshlrev_b64 v[186:187], 12, v[186:187]
	v_lshl_add_u64 v[144:145], v[2:3], 0, v[144:145]
	v_lshl_add_u64 v[150:151], v[2:3], 0, v[150:151]
	v_lshl_add_u64 v[148:149], v[2:3], 0, v[148:149]
	v_lshl_add_u64 v[154:155], v[2:3], 0, v[154:155]
	v_lshl_add_u64 v[152:153], v[2:3], 0, v[152:153]
	v_lshl_add_u64 v[158:159], v[2:3], 0, v[158:159]
	v_lshl_add_u64 v[156:157], v[2:3], 0, v[156:157]
	v_lshl_add_u64 v[162:163], v[2:3], 0, v[162:163]
	v_lshl_add_u64 v[160:161], v[2:3], 0, v[160:161]
	v_lshl_add_u64 v[166:167], v[2:3], 0, v[166:167]
	v_lshl_add_u64 v[164:165], v[2:3], 0, v[164:165]
	v_lshl_add_u64 v[182:183], v[2:3], 0, v[182:183]
	v_lshl_add_u64 v[168:169], v[2:3], 0, v[168:169]
	v_lshl_add_u64 v[186:187], v[2:3], 0, v[186:187]
	v_lshl_add_u64 v[184:185], v[2:3], 0, v[184:185]
	global_load_dword v219, v[146:147], off
	global_load_dword v220, v[144:145], off
	global_load_dword v221, v[150:151], off
	global_load_dword v222, v[148:149], off
	global_load_dword v223, v[154:155], off
	global_load_dword v224, v[152:153], off
	global_load_dword v225, v[158:159], off
	global_load_dword v226, v[156:157], off
	global_load_dword v227, v[162:163], off
	global_load_dword v228, v[160:161], off
	global_load_dword v229, v[166:167], off
	global_load_dword v230, v[164:165], off
	global_load_dword v231, v[182:183], off
	global_load_dword v232, v[168:169], off
	global_load_dword v233, v[186:187], off
	global_load_dword v234, v[184:185], off
	v_mad_u64_u32 v[4:5], s[16:17], v41, s67, v[36:37]
	v_mad_u64_u32 v[6:7], s[16:17], v30, s67, v[36:37]
	v_mad_u64_u32 v[8:9], s[16:17], v49, s67, v[36:37]
	v_mad_u64_u32 v[10:11], s[16:17], v48, s67, v[36:37]
	v_mad_u64_u32 v[12:13], s[16:17], v51, s67, v[36:37]
	v_mad_u64_u32 v[14:15], s[16:17], v50, s67, v[36:37]
	v_mad_u64_u32 v[16:17], s[16:17], v53, s67, v[36:37]
	v_mad_u64_u32 v[18:19], s[16:17], v52, s67, v[36:37]
	v_mad_u64_u32 v[20:21], s[16:17], v55, s67, v[36:37]
	v_mad_u64_u32 v[22:23], s[16:17], v54, s67, v[36:37]
	v_mad_u64_u32 v[24:25], s[16:17], v57, s67, v[36:37]
	v_mad_u64_u32 v[26:27], s[16:17], v56, s67, v[36:37]
	v_mad_u64_u32 v[28:29], s[16:17], v76, s67, v[36:37]
	v_mad_u64_u32 v[42:43], s[16:17], v71, s67, v[36:37]
	v_mad_u64_u32 v[44:45], s[16:17], v78, s67, v[36:37]
	v_mad_u64_u32 v[46:47], s[16:17], v77, s67, v[36:37]
	s_waitcnt vmcnt(31)
	ds_write_b32 v4, v79
	s_waitcnt vmcnt(30)
	ds_write_b32 v6, v80
	s_waitcnt vmcnt(29)
	ds_write_b32 v8, v81
	s_waitcnt vmcnt(28)
	ds_write_b32 v10, v82
	s_waitcnt vmcnt(27)
	ds_write_b32 v12, v83
	s_waitcnt vmcnt(26)
	ds_write_b32 v14, v84
	s_waitcnt vmcnt(25)
	ds_write_b32 v16, v85
	s_waitcnt vmcnt(24)
	ds_write_b32 v18, v86
	s_waitcnt vmcnt(23)
	ds_write_b32 v20, v87
	s_waitcnt vmcnt(22)
	ds_write_b32 v22, v88
	s_waitcnt vmcnt(21)
	ds_write_b32 v24, v89
	s_waitcnt vmcnt(20)
	ds_write_b32 v26, v90
	s_waitcnt vmcnt(19)
	ds_write_b32 v28, v91
	s_waitcnt vmcnt(18)
	ds_write_b32 v42, v92
	s_waitcnt vmcnt(17)
	ds_write_b32 v44, v93
	s_waitcnt vmcnt(16)
; #define LAS __attribute__((address_space(3)))
; __device__ __forceinline__ unsigned cvtpk_s(float lo, float hi) { f32x2_t v = {lo, hi}; bf16x2_t b = __builtin_convertvector(v, bf16x2_t); return __builtin_bit_cast(unsigned, b); }
; #define LDS_WAIT() asm volatile("s_waitcnt lgkmcnt(0)" ::: "memory")
; __device__ __forceinline__ void transpose_item(const float* W, int N, bf16_t* WT, int ldw, int drow0, int dk0, LAS float* scr, int k0, int n0, int lane) {
;     ...
;     for (int i = 0; i < 32; ++i) { const int kk = 2 * i + (lane >> 5); scr[kk * 33 + (lane & 31)] = W[(size_t)(k0 + kk) * N + n0 + (lane & 31)]; }
;     LDS_WAIT(); asm volatile("" ::: "memory");
;     const int c = lane & 7;
; #pragma unroll
;     for (int j = 0; j < 4; ++j) { const int n = (lane >> 3) + 8 * j; const LAS float* s = scr + (8 * c) * 33 + n;
;         u32x4 o; o.x = cvtpk_s(s[0 * 33], s[1 * 33]); o.y = cvtpk_s(s[2 * 33], s[3 * 33]); o.z = cvtpk_s(s[4 * 33], s[5 * 33]); o.w = cvtpk_s(s[6 * 33], s[7 * 33]);
;         *(u32x4*)(WT + (size_t)(drow0 + n) * ldw + dk0 + k0 + 8 * c) = o; }
	ds_write_b32 v46, v94
	s_add_i32 s9, s9, 16
	s_add_i32 s12, s12, 16
	s_add_i32 s14, s14, -16
	v_mad_u64_u32 v[144:145], s[16:17], v181, s67, v[36:37]
	v_mad_u64_u32 v[146:147], s[16:17], v170, s67, v[36:37]
	v_mad_u64_u32 v[148:149], s[16:17], v189, s67, v[36:37]
	v_mad_u64_u32 v[150:151], s[16:17], v188, s67, v[36:37]
	v_mad_u64_u32 v[152:153], s[16:17], v191, s67, v[36:37]
	v_mad_u64_u32 v[154:155], s[16:17], v190, s67, v[36:37]
	v_mad_u64_u32 v[156:157], s[16:17], v193, s67, v[36:37]
	v_mad_u64_u32 v[158:159], s[16:17], v192, s67, v[36:37]
	v_mad_u64_u32 v[160:161], s[16:17], v195, s67, v[36:37]
	v_mad_u64_u32 v[162:163], s[16:17], v194, s67, v[36:37]
	v_mad_u64_u32 v[164:165], s[16:17], v197, s67, v[36:37]
	v_mad_u64_u32 v[166:167], s[16:17], v196, s67, v[36:37]
	v_mad_u64_u32 v[168:169], s[16:17], v216, s67, v[36:37]
	v_mad_u64_u32 v[182:183], s[16:17], v211, s67, v[36:37]
	v_mad_u64_u32 v[184:185], s[16:17], v218, s67, v[36:37]
	v_mad_u64_u32 v[186:187], s[16:17], v217, s67, v[36:37]
	s_waitcnt vmcnt(15)
	ds_write_b32 v144, v219
	s_waitcnt vmcnt(14)
	ds_write_b32 v146, v220
	s_waitcnt vmcnt(13)
	ds_write_b32 v148, v221
	s_waitcnt vmcnt(12)
	ds_write_b32 v150, v222
	s_waitcnt vmcnt(11)
	ds_write_b32 v152, v223
	s_waitcnt vmcnt(10)
	ds_write_b32 v154, v224
	s_waitcnt vmcnt(9)
	ds_write_b32 v156, v225
	s_waitcnt vmcnt(8)
	ds_write_b32 v158, v226
	s_waitcnt vmcnt(7)
	ds_write_b32 v160, v227
	s_waitcnt vmcnt(6)
	ds_write_b32 v162, v228
	s_waitcnt vmcnt(5)
	ds_write_b32 v164, v229
	s_waitcnt vmcnt(4)
	ds_write_b32 v166, v230
	s_waitcnt vmcnt(3)
	ds_write_b32 v168, v231
	s_waitcnt vmcnt(2)
	ds_write_b32 v182, v232
	s_waitcnt vmcnt(1)
	ds_write_b32 v184, v233
	s_waitcnt vmcnt(0)
	ds_write_b32 v186, v234
	s_waitcnt lgkmcnt(0)
	s_mov_b32 s9, s41
	s_lshl_b64 s[8:9], s[8:9], 1
	s_add_u32 s8, s4, s8
	ds_read2_b32 v[6:7], v60 offset0:33 offset1:41
	ds_read2_b32 v[8:9], v60 offset1:8
	ds_read2_b32 v[10:11], v60 offset0:66 offset1:74
	ds_read2_b32 v[12:13], v60 offset0:99 offset1:107
	ds_read2_b32 v[14:15], v60 offset0:132 offset1:140
	ds_read2_b32 v[16:17], v60 offset0:165 offset1:173
	ds_read2_b32 v[18:19], v60 offset0:198 offset1:206
	ds_read2_b32 v[20:21], v60 offset0:231 offset1:239
	s_addc_u32 s9, s5, s9
	v_lshlrev_b32_e32 v30, 1, v38
	v_lshl_add_u64 v[2:3], s[8:9], 0, v[30:31]
	v_lshl_add_u64 v[22:23], v[2:3], 0, s[50:51]
	s_waitcnt lgkmcnt(6)
	v_cvt_pk_bf16_f32 v2, v8, v6
	v_or_b32_e32 v6, s11, v59
	v_lshlrev_b32_e32 v30, 11, v6
	s_waitcnt lgkmcnt(4)
	v_cvt_pk_bf16_f32 v3, v10, v12
	s_waitcnt lgkmcnt(2)
	v_cvt_pk_bf16_f32 v4, v14, v16
	s_waitcnt lgkmcnt(0)
	v_cvt_pk_bf16_f32 v5, v18, v20
	v_lshl_add_u64 v[24:25], v[22:23], 0, v[30:31]
	global_store_dwordx4 v[24:25], v[2:5], off
	v_or_b32_e32 v6, s11, v61
	v_lshlrev_b32_e32 v30, 11, v6
	v_cvt_pk_bf16_f32 v2, v9, v7
	v_cvt_pk_bf16_f32 v3, v11, v13
	v_cvt_pk_bf16_f32 v4, v15, v17
	v_cvt_pk_bf16_f32 v5, v19, v21
	ds_read2_b32 v[8:9], v60 offset0:49 offset1:57
	ds_read2_b32 v[10:11], v60 offset0:16 offset1:24
	ds_read2_b32 v[12:13], v60 offset0:82 offset1:90
	ds_read2_b32 v[14:15], v60 offset0:115 offset1:123
	ds_read2_b32 v[16:17], v60 offset0:148 offset1:156
	ds_read2_b32 v[18:19], v60 offset0:181 offset1:189
	ds_read2_b32 v[20:21], v60 offset0:214 offset1:222
	ds_read2_b32 v[24:25], v60 offset0:247 offset1:255
	v_lshl_add_u64 v[6:7], v[22:23], 0, v[30:31]
	global_store_dwordx4 v[6:7], v[2:5], off
	v_or_b32_e32 v6, s11, v62
	v_lshlrev_b32_e32 v30, 11, v6
	s_waitcnt lgkmcnt(6)
	v_cvt_pk_bf16_f32 v2, v10, v8
	s_waitcnt lgkmcnt(4)
	v_cvt_pk_bf16_f32 v3, v12, v14
	s_waitcnt lgkmcnt(2)
	v_cvt_pk_bf16_f32 v4, v16, v18
	s_waitcnt lgkmcnt(0)
	v_cvt_pk_bf16_f32 v5, v20, v24
	v_lshl_add_u64 v[6:7], v[22:23], 0, v[30:31]
	global_store_dwordx4 v[6:7], v[2:5], off
	v_or_b32_e32 v6, s11, v63
	v_lshlrev_b32_e32 v30, 11, v6
	v_cvt_pk_bf16_f32 v2, v11, v9
	v_cvt_pk_bf16_f32 v3, v13, v15
	v_cvt_pk_bf16_f32 v4, v17, v19
	v_cvt_pk_bf16_f32 v5, v21, v25
	v_lshl_add_u64 v[6:7], v[22:23], 0, v[30:31]
	global_store_dwordx4 v[6:7], v[2:5], off
	s_waitcnt lgkmcnt(0)

; #define LAS __attribute__((address_space(3)))
; __device__ __forceinline__ void transpose_item(const float* W, int N, bf16_t* WT, int ldw, int drow0, int dk0, LAS float* scr, int k0, int n0, int lane) {
; #pragma unroll 8
;     for (int i = 0; i < 32; ++i) { const int kk = 2 * i + (lane >> 5); scr[kk * 33 + (lane & 31)] = W[(size_t)(k0 + kk) * N + n0 + (lane & 31)]; }
.LBB0_60:
	s_lshl_b32 s15, s12, 1
	s_lshl_b32 s16, s11, 1
	v_or_b32_e32 v30, s15, v1
	v_or_b32_e32 v41, s16, v32
	s_add_i32 s17, s15, 4
	s_add_i32 s18, s16, 4
	s_add_i32 s19, s15, 8
	s_add_i32 s20, s16, 8
	s_add_i32 s21, s15, 12
	s_add_i32 s22, s16, 12
	s_add_i32 s23, s15, 16
	s_add_i32 s26, s16, 16
	s_add_i32 s27, s15, 20
	s_add_i32 s34, s16, 20
	s_add_i32 s35, s15, 24
	s_add_i32 s40, s16, 24
	s_add_i32 s15, s15, 28
	s_add_i32 s16, s16, 28
	v_add_u32_e32 v6, s8, v41
	v_or_b32_e32 v48, s17, v1
	v_or_b32_e32 v49, s18, v32
	v_or_b32_e32 v50, s19, v1
	v_or_b32_e32 v51, s20, v32
	v_or_b32_e32 v52, s21, v1
	v_or_b32_e32 v53, s22, v32
	v_or_b32_e32 v54, s23, v1
	v_or_b32_e32 v55, s26, v32
	v_or_b32_e32 v56, s27, v1
	v_or_b32_e32 v57, s34, v32
	v_or_b32_e32 v71, s35, v1
	v_or_b32_e32 v76, s40, v32
	v_or_b32_e32 v77, s15, v1
	v_or_b32_e32 v78, s16, v32
	v_add_u32_e32 v4, s13, v30
	v_ashrrev_i32_e32 v7, 31, v6
	v_add_u32_e32 v8, s13, v48
	v_add_u32_e32 v10, s8, v49
	v_add_u32_e32 v12, s13, v50
	v_add_u32_e32 v14, s8, v51
	v_add_u32_e32 v16, s13, v52
	v_add_u32_e32 v18, s8, v53
	v_add_u32_e32 v20, s13, v54
	v_add_u32_e32 v22, s8, v55
	v_add_u32_e32 v24, s13, v56
	v_add_u32_e32 v26, s8, v57
	v_add_u32_e32 v28, s13, v71
	v_add_u32_e32 v42, s8, v76
	v_add_u32_e32 v44, s13, v77
	v_add_u32_e32 v46, s8, v78
	v_ashrrev_i32_e32 v5, 31, v4
	v_lshlrev_b64 v[6:7], 12, v[6:7]
	v_ashrrev_i32_e32 v11, 31, v10
	v_ashrrev_i32_e32 v9, 31, v8
	v_ashrrev_i32_e32 v15, 31, v14
	v_ashrrev_i32_e32 v13, 31, v12
	v_ashrrev_i32_e32 v19, 31, v18
	v_ashrrev_i32_e32 v17, 31, v16
	v_ashrrev_i32_e32 v23, 31, v22
	v_ashrrev_i32_e32 v21, 31, v20
	v_ashrrev_i32_e32 v27, 31, v26
	v_ashrrev_i32_e32 v25, 31, v24
	v_ashrrev_i32_e32 v43, 31, v42
	v_ashrrev_i32_e32 v29, 31, v28
	v_ashrrev_i32_e32 v47, 31, v46
	v_ashrrev_i32_e32 v45, 31, v44
	v_lshlrev_b64 v[4:5], 12, v[4:5]
	v_lshl_add_u64 v[6:7], v[2:3], 0, v[6:7]
	v_lshlrev_b64 v[8:9], 12, v[8:9]
	v_lshlrev_b64 v[10:11], 12, v[10:11]
	v_lshlrev_b64 v[12:13], 12, v[12:13]
	v_lshlrev_b64 v[14:15], 12, v[14:15]
	v_lshlrev_b64 v[16:17], 12, v[16:17]
	v_lshlrev_b64 v[18:19], 12, v[18:19]
	v_lshlrev_b64 v[20:21], 12, v[20:21]
	v_lshlrev_b64 v[22:23], 12, v[22:23]
	v_lshlrev_b64 v[24:25], 12, v[24:25]
	v_lshlrev_b64 v[26:27], 12, v[26:27]
	v_lshlrev_b64 v[28:29], 12, v[28:29]
	v_lshlrev_b64 v[42:43], 12, v[42:43]
	v_lshlrev_b64 v[44:45], 12, v[44:45]
	v_lshlrev_b64 v[46:47], 12, v[46:47]
	v_lshl_add_u64 v[4:5], v[2:3], 0, v[4:5]
	v_lshl_add_u64 v[10:11], v[2:3], 0, v[10:11]
	v_lshl_add_u64 v[8:9], v[2:3], 0, v[8:9]
	v_lshl_add_u64 v[14:15], v[2:3], 0, v[14:15]
	v_lshl_add_u64 v[12:13], v[2:3], 0, v[12:13]
	v_lshl_add_u64 v[18:19], v[2:3], 0, v[18:19]
	v_lshl_add_u64 v[16:17], v[2:3], 0, v[16:17]
	v_lshl_add_u64 v[22:23], v[2:3], 0, v[22:23]
	v_lshl_add_u64 v[20:21], v[2:3], 0, v[20:21]
	v_lshl_add_u64 v[26:27], v[2:3], 0, v[26:27]
	v_lshl_add_u64 v[24:25], v[2:3], 0, v[24:25]
	v_lshl_add_u64 v[42:43], v[2:3], 0, v[42:43]
	v_lshl_add_u64 v[28:29], v[2:3], 0, v[28:29]
	v_lshl_add_u64 v[46:47], v[2:3], 0, v[46:47]
	v_lshl_add_u64 v[44:45], v[2:3], 0, v[44:45]
	global_load_dword v79, v[6:7], off
	global_load_dword v80, v[4:5], off
	global_load_dword v81, v[10:11], off
	global_load_dword v82, v[8:9], off
	global_load_dword v83, v[14:15], off
	global_load_dword v84, v[12:13], off
	global_load_dword v85, v[18:19], off
	global_load_dword v86, v[16:17], off
	global_load_dword v87, v[22:23], off
	global_load_dword v88, v[20:21], off
	global_load_dword v89, v[26:27], off
	global_load_dword v90, v[24:25], off
	global_load_dword v91, v[42:43], off
	global_load_dword v92, v[28:29], off
	global_load_dword v93, v[46:47], off
	global_load_dword v94, v[44:45], off
	s_add_i32 s11, s11, 16
	s_add_i32 s12, s12, 16
	s_add_i32 s14, s14, -16
	s_lshl_b32 s15, s12, 1
	s_lshl_b32 s16, s11, 1
	v_or_b32_e32 v170, s15, v1
	v_or_b32_e32 v181, s16, v32
	s_add_i32 s17, s15, 4
	s_add_i32 s18, s16, 4
	s_add_i32 s19, s15, 8
	s_add_i32 s20, s16, 8
	s_add_i32 s21, s15, 12
	s_add_i32 s22, s16, 12
	s_add_i32 s23, s15, 16
	s_add_i32 s26, s16, 16
	s_add_i32 s27, s15, 20
	s_add_i32 s34, s16, 20
	s_add_i32 s35, s15, 24
	s_add_i32 s40, s16, 24
	s_add_i32 s15, s15, 28
	s_add_i32 s16, s16, 28
	v_add_u32_e32 v146, s8, v181
	v_or_b32_e32 v188, s17, v1
	v_or_b32_e32 v189, s18, v32
	v_or_b32_e32 v190, s19, v1
	v_or_b32_e32 v191, s20, v32
	v_or_b32_e32 v192, s21, v1
	v_or_b32_e32 v193, s22, v32
	v_or_b32_e32 v194, s23, v1
	v_or_b32_e32 v195, s26, v32
	v_or_b32_e32 v196, s27, v1
	v_or_b32_e32 v197, s34, v32
	v_or_b32_e32 v211, s35, v1
	v_or_b32_e32 v216, s40, v32
	v_or_b32_e32 v217, s15, v1
	v_or_b32_e32 v218, s16, v32
	v_add_u32_e32 v144, s13, v170
	v_ashrrev_i32_e32 v147, 31, v146
	v_add_u32_e32 v148, s13, v188
	v_add_u32_e32 v150, s8, v189
	v_add_u32_e32 v152, s13, v190
	v_add_u32_e32 v154, s8, v191
	v_add_u32_e32 v156, s13, v192
	v_add_u32_e32 v158, s8, v193
	v_add_u32_e32 v160, s13, v194
	v_add_u32_e32 v162, s8, v195
	v_add_u32_e32 v164, s13, v196
	v_add_u32_e32 v166, s8, v197
	v_add_u32_e32 v168, s13, v211
	v_add_u32_e32 v182, s8, v216
	v_add_u32_e32 v184, s13, v217
	v_add_u32_e32 v186, s8, v218
	v_ashrrev_i32_e32 v145, 31, v144
	v_lshlrev_b64 v[146:147], 12, v[146:147]
	v_ashrrev_i32_e32 v151, 31, v150
	v_ashrrev_i32_e32 v149, 31, v148
	v_ashrrev_i32_e32 v155, 31, v154
	v_ashrrev_i32_e32 v153, 31, v152
	v_ashrrev_i32_e32 v159, 31, v158
	v_ashrrev_i32_e32 v157, 31, v156
	v_ashrrev_i32_e32 v163, 31, v162
	v_ashrrev_i32_e32 v161, 31, v160
	v_ashrrev_i32_e32 v167, 31, v166
	v_ashrrev_i32_e32 v165, 31, v164
	v_ashrrev_i32_e32 v183, 31, v182
	v_ashrrev_i32_e32 v169, 31, v168
; __device__ __forceinline__ void transpose_item(const float* W, int N, bf16_t* WT, int ldw, int drow0, int dk0, LAS float* scr, int k0, int n0, int lane) {
;     ...
;     for (int i = 0; i < 32; ++i) { const int kk = 2 * i + (lane >> 5); scr[kk * 33 + (lane & 31)] = W[(size_t)(k0 + kk) * N + n0 + (lane & 31)]; }
	v_ashrrev_i32_e32 v187, 31, v186
	v_ashrrev_i32_e32 v185, 31, v184
	v_lshlrev_b64 v[144:145], 12, v[144:145]
	v_lshl_add_u64 v[146:147], v[2:3], 0, v[146:147]
	v_lshlrev_b64 v[148:149], 12, v[148:149]
	v_lshlrev_b64 v[150:151], 12, v[150:151]
	v_lshlrev_b64 v[152:153], 12, v[152:153]
	v_lshlrev_b64 v[154:155], 12, v[154:155]
	v_lshlrev_b64 v[156:157], 12, v[156:157]
	v_lshlrev_b64 v[158:159], 12, v[158:159]
	v_lshlrev_b64 v[160:161], 12, v[160:161]
	v_lshlrev_b64 v[162:163], 12, v[162:163]
	v_lshlrev_b64 v[164:165], 12, v[164:165]
	v_lshlrev_b64 v[166:167], 12, v[166:167]
	v_lshlrev_b64 v[168:169], 12, v[168:169]
	v_lshlrev_b64 v[182:183], 12, v[182:183]
	v_lshlrev_b64 v[184:185], 12, v[184:185]
	v_lshlrev_b64 v[186:187], 12, v[186:187]
	v_lshl_add_u64 v[144:145], v[2:3], 0, v[144:145]
	v_lshl_add_u64 v[150:151], v[2:3], 0, v[150:151]
	v_lshl_add_u64 v[148:149], v[2:3], 0, v[148:149]
	v_lshl_add_u64 v[154:155], v[2:3], 0, v[154:155]
	v_lshl_add_u64 v[152:153], v[2:3], 0, v[152:153]
	v_lshl_add_u64 v[158:159], v[2:3], 0, v[158:159]
	v_lshl_add_u64 v[156:157], v[2:3], 0, v[156:157]
	v_lshl_add_u64 v[162:163], v[2:3], 0, v[162:163]
	v_lshl_add_u64 v[160:161], v[2:3], 0, v[160:161]
	v_lshl_add_u64 v[166:167], v[2:3], 0, v[166:167]
	v_lshl_add_u64 v[164:165], v[2:3], 0, v[164:165]
	v_lshl_add_u64 v[182:183], v[2:3], 0, v[182:183]
	v_lshl_add_u64 v[168:169], v[2:3], 0, v[168:169]
	v_lshl_add_u64 v[186:187], v[2:3], 0, v[186:187]
	v_lshl_add_u64 v[184:185], v[2:3], 0, v[184:185]
	global_load_dword v219, v[146:147], off
	global_load_dword v220, v[144:145], off
	global_load_dword v221, v[150:151], off
	global_load_dword v222, v[148:149], off
	global_load_dword v223, v[154:155], off
	global_load_dword v224, v[152:153], off
	global_load_dword v225, v[158:159], off
	global_load_dword v226, v[156:157], off
	global_load_dword v227, v[162:163], off
	global_load_dword v228, v[160:161], off
	global_load_dword v229, v[166:167], off
	global_load_dword v230, v[164:165], off
	global_load_dword v231, v[182:183], off
	global_load_dword v232, v[168:169], off
	global_load_dword v233, v[186:187], off
	global_load_dword v234, v[184:185], off
	v_mad_u64_u32 v[4:5], s[16:17], v41, s67, v[36:37]
	v_mad_u64_u32 v[6:7], s[16:17], v30, s67, v[36:37]
	v_mad_u64_u32 v[8:9], s[16:17], v49, s67, v[36:37]
	v_mad_u64_u32 v[10:11], s[16:17], v48, s67, v[36:37]
	v_mad_u64_u32 v[12:13], s[16:17], v51, s67, v[36:37]
	v_mad_u64_u32 v[14:15], s[16:17], v50, s67, v[36:37]
	v_mad_u64_u32 v[16:17], s[16:17], v53, s67, v[36:37]
	v_mad_u64_u32 v[18:19], s[16:17], v52, s67, v[36:37]
	v_mad_u64_u32 v[20:21], s[16:17], v55, s67, v[36:37]
	v_mad_u64_u32 v[22:23], s[16:17], v54, s67, v[36:37]
	v_mad_u64_u32 v[24:25], s[16:17], v57, s67, v[36:37]
	v_mad_u64_u32 v[26:27], s[16:17], v56, s67, v[36:37]
	v_mad_u64_u32 v[28:29], s[16:17], v76, s67, v[36:37]
	v_mad_u64_u32 v[42:43], s[16:17], v71, s67, v[36:37]
	v_mad_u64_u32 v[44:45], s[16:17], v78, s67, v[36:37]
	v_mad_u64_u32 v[46:47], s[16:17], v77, s67, v[36:37]
	s_waitcnt vmcnt(31)
	ds_write_b32 v4, v79
	s_waitcnt vmcnt(30)
	ds_write_b32 v6, v80
	s_waitcnt vmcnt(29)
	ds_write_b32 v8, v81
	s_waitcnt vmcnt(28)
	ds_write_b32 v10, v82
	s_waitcnt vmcnt(27)
	ds_write_b32 v12, v83
	s_waitcnt vmcnt(26)
	ds_write_b32 v14, v84
	s_waitcnt vmcnt(25)
	ds_write_b32 v16, v85
	s_waitcnt vmcnt(24)
	ds_write_b32 v18, v86
	s_waitcnt vmcnt(23)
	ds_write_b32 v20, v87
	s_waitcnt vmcnt(22)
	ds_write_b32 v22, v88
	s_waitcnt vmcnt(21)
	ds_write_b32 v24, v89
	s_waitcnt vmcnt(20)
	ds_write_b32 v26, v90
	s_waitcnt vmcnt(19)
	ds_write_b32 v28, v91
	s_waitcnt vmcnt(18)
	ds_write_b32 v42, v92
	s_waitcnt vmcnt(17)
	ds_write_b32 v44, v93
	s_waitcnt vmcnt(16)
; #define LAS __attribute__((address_space(3)))
; __device__ __forceinline__ unsigned cvtpk_s(float lo, float hi) { f32x2_t v = {lo, hi}; bf16x2_t b = __builtin_convertvector(v, bf16x2_t); return __builtin_bit_cast(unsigned, b); }
; #define LDS_WAIT() asm volatile("s_waitcnt lgkmcnt(0)" ::: "memory")
; __device__ __forceinline__ void transpose_item(const float* W, int N, bf16_t* WT, int ldw, int drow0, int dk0, LAS float* scr, int k0, int n0, int lane) {
;     ...
;     for (int i = 0; i < 32; ++i) { const int kk = 2 * i + (lane >> 5); scr[kk * 33 + (lane & 31)] = W[(size_t)(k0 + kk) * N + n0 + (lane & 31)]; }
;     LDS_WAIT(); asm volatile("" ::: "memory");
;     const int c = lane & 7;
; #pragma unroll
;     for (int j = 0; j < 4; ++j) { const int n = (lane >> 3) + 8 * j; const LAS float* s = scr + (8 * c) * 33 + n;
;         u32x4 o; o.x = cvtpk_s(s[0 * 33], s[1 * 33]); o.y = cvtpk_s(s[2 * 33], s[3 * 33]); o.z = cvtpk_s(s[4 * 33], s[5 * 33]); o.w = cvtpk_s(s[6 * 33], s[7 * 33]);
;         *(u32x4*)(WT + (size_t)(drow0 + n) * ldw + dk0 + k0 + 8 * c) = o; }
; __device__ __forceinline__ void prologue(const kptr_t kp, LAS float* scr, int gw, int NGW, int lane) {
;     ...
;             if (r < IT_P) { const int kb = r / 32, nb = r % 32, n0 = 32 * nb; transpose_item(KPTR(const float, 17) + (size_t)l * 512 * D, D, (bf16_t*)(wl + W_PAB), D, 256 * (n0 / 128) + 128 + (n0 % 128), 512, scr, 64 * kb, n0, lane); continue; } r -= IT_P;
	ds_write_b32 v46, v94
	s_add_i32 s11, s11, 16
	s_add_i32 s12, s12, 16
	s_add_i32 s14, s14, -16
	v_mad_u64_u32 v[144:145], s[16:17], v181, s67, v[36:37]
	v_mad_u64_u32 v[146:147], s[16:17], v170, s67, v[36:37]
	v_mad_u64_u32 v[148:149], s[16:17], v189, s67, v[36:37]
	v_mad_u64_u32 v[150:151], s[16:17], v188, s67, v[36:37]
	v_mad_u64_u32 v[152:153], s[16:17], v191, s67, v[36:37]
	v_mad_u64_u32 v[154:155], s[16:17], v190, s67, v[36:37]
	v_mad_u64_u32 v[156:157], s[16:17], v193, s67, v[36:37]
	v_mad_u64_u32 v[158:159], s[16:17], v192, s67, v[36:37]
	v_mad_u64_u32 v[160:161], s[16:17], v195, s67, v[36:37]
	v_mad_u64_u32 v[162:163], s[16:17], v194, s67, v[36:37]
	v_mad_u64_u32 v[164:165], s[16:17], v197, s67, v[36:37]
	v_mad_u64_u32 v[166:167], s[16:17], v196, s67, v[36:37]
	v_mad_u64_u32 v[168:169], s[16:17], v216, s67, v[36:37]
	v_mad_u64_u32 v[182:183], s[16:17], v211, s67, v[36:37]
	v_mad_u64_u32 v[184:185], s[16:17], v218, s67, v[36:37]
	v_mad_u64_u32 v[186:187], s[16:17], v217, s67, v[36:37]
	s_waitcnt vmcnt(15)
	ds_write_b32 v144, v219
	s_waitcnt vmcnt(14)
	ds_write_b32 v146, v220
	s_waitcnt vmcnt(13)
	ds_write_b32 v148, v221
	s_waitcnt vmcnt(12)
	ds_write_b32 v150, v222
	s_waitcnt vmcnt(11)
	ds_write_b32 v152, v223
	s_waitcnt vmcnt(10)
	ds_write_b32 v154, v224
	s_waitcnt vmcnt(9)
	ds_write_b32 v156, v225
	s_waitcnt vmcnt(8)
	ds_write_b32 v158, v226
	s_waitcnt vmcnt(7)
	ds_write_b32 v160, v227
	s_waitcnt vmcnt(6)
	ds_write_b32 v162, v228
	s_waitcnt vmcnt(5)
	ds_write_b32 v164, v229
	s_waitcnt vmcnt(4)
	ds_write_b32 v166, v230
	s_waitcnt vmcnt(3)
	ds_write_b32 v168, v231
	s_waitcnt vmcnt(2)
	ds_write_b32 v182, v232
	s_waitcnt vmcnt(1)
	ds_write_b32 v184, v233
	s_waitcnt vmcnt(0)
	ds_write_b32 v186, v234
	s_lshl_b32 s11, s3, 6
	s_and_b32 s11, s11, 0x700
	s_and_b32 s9, s9, 0x60
	s_or_b32 s9, s11, s9
	s_or_b32 s11, s9, 0x80
	s_waitcnt lgkmcnt(0)
	s_mov_b32 s9, s41
	s_lshl_b64 s[8:9], s[8:9], 1
	s_add_u32 s8, s4, s8
	ds_read2_b32 v[6:7], v60 offset0:33 offset1:41
	ds_read2_b32 v[8:9], v60 offset1:8
	ds_read2_b32 v[10:11], v60 offset0:66 offset1:74
	ds_read2_b32 v[12:13], v60 offset0:99 offset1:107
	ds_read2_b32 v[14:15], v60 offset0:132 offset1:140
	ds_read2_b32 v[16:17], v60 offset0:165 offset1:173
	ds_read2_b32 v[18:19], v60 offset0:198 offset1:206
	ds_read2_b32 v[20:21], v60 offset0:231 offset1:239
	s_addc_u32 s9, s5, s9
	v_lshlrev_b32_e32 v30, 1, v38
	v_lshl_add_u64 v[2:3], s[8:9], 0, v[30:31]
	v_lshl_add_u64 v[22:23], v[2:3], 0, s[52:53]
	s_waitcnt lgkmcnt(6)
	v_cvt_pk_bf16_f32 v2, v8, v6
	v_or_b32_e32 v6, s11, v59
	v_lshlrev_b32_e32 v30, 11, v6
	s_waitcnt lgkmcnt(4)
	v_cvt_pk_bf16_f32 v3, v10, v12
	s_waitcnt lgkmcnt(2)
	v_cvt_pk_bf16_f32 v4, v14, v16
	s_waitcnt lgkmcnt(0)
	v_cvt_pk_bf16_f32 v5, v18, v20
	v_lshl_add_u64 v[24:25], v[22:23], 0, v[30:31]
	global_store_dwordx4 v[24:25], v[2:5], off
	v_or_b32_e32 v6, s11, v61
	v_lshlrev_b32_e32 v30, 11, v6
	v_cvt_pk_bf16_f32 v2, v9, v7
	v_cvt_pk_bf16_f32 v3, v11, v13
	v_cvt_pk_bf16_f32 v4, v15, v17
	v_cvt_pk_bf16_f32 v5, v19, v21
	ds_read2_b32 v[8:9], v60 offset0:49 offset1:57
	ds_read2_b32 v[10:11], v60 offset0:16 offset1:24
	ds_read2_b32 v[12:13], v60 offset0:82 offset1:90
	ds_read2_b32 v[14:15], v60 offset0:115 offset1:123
	ds_read2_b32 v[16:17], v60 offset0:148 offset1:156
	ds_read2_b32 v[18:19], v60 offset0:181 offset1:189
	ds_read2_b32 v[20:21], v60 offset0:214 offset1:222
	ds_read2_b32 v[24:25], v60 offset0:247 offset1:255
	v_lshl_add_u64 v[6:7], v[22:23], 0, v[30:31]
	global_store_dwordx4 v[6:7], v[2:5], off
	v_or_b32_e32 v6, s11, v62
	v_lshlrev_b32_e32 v30, 11, v6
	s_waitcnt lgkmcnt(6)
	v_cvt_pk_bf16_f32 v2, v10, v8
	s_waitcnt lgkmcnt(4)
	v_cvt_pk_bf16_f32 v3, v12, v14
	s_waitcnt lgkmcnt(2)
	v_cvt_pk_bf16_f32 v4, v16, v18
	s_waitcnt lgkmcnt(0)
	v_cvt_pk_bf16_f32 v5, v20, v24
	v_lshl_add_u64 v[6:7], v[22:23], 0, v[30:31]
	global_store_dwordx4 v[6:7], v[2:5], off
	v_or_b32_e32 v6, s11, v63
	v_lshlrev_b32_e32 v30, 11, v6
	v_cvt_pk_bf16_f32 v2, v11, v9
	v_cvt_pk_bf16_f32 v3, v13, v15
	v_cvt_pk_bf16_f32 v4, v17, v19
	v_cvt_pk_bf16_f32 v5, v21, v25
	v_lshl_add_u64 v[6:7], v[22:23], 0, v[30:31]
	global_store_dwordx4 v[6:7], v[2:5], off
	s_waitcnt lgkmcnt(0)

; #define LAS __attribute__((address_space(3)))
; __device__ __forceinline__ void transpose_item(const float* W, int N, bf16_t* WT, int ldw, int drow0, int dk0, LAS float* scr, int k0, int n0, int lane) {
; #pragma unroll 8
;     for (int i = 0; i < 32; ++i) { const int kk = 2 * i + (lane >> 5); scr[kk * 33 + (lane & 31)] = W[(size_t)(k0 + kk) * N + n0 + (lane & 31)]; }
.LBB0_65:
	s_lshl_b32 s15, s12, 1
	s_lshl_b32 s16, s11, 1
	v_or_b32_e32 v30, s15, v1
	v_or_b32_e32 v41, s16, v32
	s_add_i32 s17, s15, 4
	s_add_i32 s18, s16, 4
	s_add_i32 s19, s15, 8
	s_add_i32 s20, s16, 8
	s_add_i32 s21, s15, 12
	s_add_i32 s22, s16, 12
	s_add_i32 s23, s15, 16
	s_add_i32 s26, s16, 16
	s_add_i32 s27, s15, 20
	s_add_i32 s34, s16, 20
	s_add_i32 s35, s15, 24
	s_add_i32 s40, s16, 24
	s_add_i32 s15, s15, 28
	s_add_i32 s16, s16, 28
	v_add_u32_e32 v6, s8, v41
	v_or_b32_e32 v48, s17, v1
	v_or_b32_e32 v49, s18, v32
	v_or_b32_e32 v50, s19, v1
	v_or_b32_e32 v51, s20, v32
	v_or_b32_e32 v52, s21, v1
	v_or_b32_e32 v53, s22, v32
	v_or_b32_e32 v54, s23, v1
	v_or_b32_e32 v55, s26, v32
	v_or_b32_e32 v56, s27, v1
	v_or_b32_e32 v57, s34, v32
	v_or_b32_e32 v71, s35, v1
	v_or_b32_e32 v76, s40, v32
	v_or_b32_e32 v77, s15, v1
	v_or_b32_e32 v78, s16, v32
	v_add_u32_e32 v4, s13, v30
	v_ashrrev_i32_e32 v7, 31, v6
	v_add_u32_e32 v8, s13, v48
	v_add_u32_e32 v10, s8, v49
	v_add_u32_e32 v12, s13, v50
	v_add_u32_e32 v14, s8, v51
	v_add_u32_e32 v16, s13, v52
	v_add_u32_e32 v18, s8, v53
	v_add_u32_e32 v20, s13, v54
	v_add_u32_e32 v22, s8, v55
	v_add_u32_e32 v24, s13, v56
	v_add_u32_e32 v26, s8, v57
	v_add_u32_e32 v28, s13, v71
	v_add_u32_e32 v42, s8, v76
	v_add_u32_e32 v44, s13, v77
	v_add_u32_e32 v46, s8, v78
	v_ashrrev_i32_e32 v5, 31, v4
	v_lshlrev_b64 v[6:7], 12, v[6:7]
	v_ashrrev_i32_e32 v11, 31, v10
	v_ashrrev_i32_e32 v9, 31, v8
	v_ashrrev_i32_e32 v15, 31, v14
	v_ashrrev_i32_e32 v13, 31, v12
	v_ashrrev_i32_e32 v19, 31, v18
	v_ashrrev_i32_e32 v17, 31, v16
	v_ashrrev_i32_e32 v23, 31, v22
	v_ashrrev_i32_e32 v21, 31, v20
	v_ashrrev_i32_e32 v27, 31, v26
	v_ashrrev_i32_e32 v25, 31, v24
	v_ashrrev_i32_e32 v43, 31, v42
	v_ashrrev_i32_e32 v29, 31, v28
	v_ashrrev_i32_e32 v47, 31, v46
	v_ashrrev_i32_e32 v45, 31, v44
	v_lshlrev_b64 v[4:5], 12, v[4:5]
	v_lshl_add_u64 v[6:7], v[2:3], 0, v[6:7]
	v_lshlrev_b64 v[8:9], 12, v[8:9]
	v_lshlrev_b64 v[10:11], 12, v[10:11]
	v_lshlrev_b64 v[12:13], 12, v[12:13]
	v_lshlrev_b64 v[14:15], 12, v[14:15]
	v_lshlrev_b64 v[16:17], 12, v[16:17]
	v_lshlrev_b64 v[18:19], 12, v[18:19]
	v_lshlrev_b64 v[20:21], 12, v[20:21]
	v_lshlrev_b64 v[22:23], 12, v[22:23]
	v_lshlrev_b64 v[24:25], 12, v[24:25]
	v_lshlrev_b64 v[26:27], 12, v[26:27]
	v_lshlrev_b64 v[28:29], 12, v[28:29]
	v_lshlrev_b64 v[42:43], 12, v[42:43]
	v_lshlrev_b64 v[44:45], 12, v[44:45]
	v_lshlrev_b64 v[46:47], 12, v[46:47]
	v_lshl_add_u64 v[4:5], v[2:3], 0, v[4:5]
	v_lshl_add_u64 v[10:11], v[2:3], 0, v[10:11]
	v_lshl_add_u64 v[8:9], v[2:3], 0, v[8:9]
	v_lshl_add_u64 v[14:15], v[2:3], 0, v[14:15]
	v_lshl_add_u64 v[12:13], v[2:3], 0, v[12:13]
	v_lshl_add_u64 v[18:19], v[2:3], 0, v[18:19]
	v_lshl_add_u64 v[16:17], v[2:3], 0, v[16:17]
	v_lshl_add_u64 v[22:23], v[2:3], 0, v[22:23]
	v_lshl_add_u64 v[20:21], v[2:3], 0, v[20:21]
	v_lshl_add_u64 v[26:27], v[2:3], 0, v[26:27]
	v_lshl_add_u64 v[24:25], v[2:3], 0, v[24:25]
	v_lshl_add_u64 v[42:43], v[2:3], 0, v[42:43]
	v_lshl_add_u64 v[28:29], v[2:3], 0, v[28:29]
	v_lshl_add_u64 v[46:47], v[2:3], 0, v[46:47]
	v_lshl_add_u64 v[44:45], v[2:3], 0, v[44:45]
	global_load_dword v79, v[6:7], off
	global_load_dword v80, v[4:5], off
	global_load_dword v81, v[10:11], off
	global_load_dword v82, v[8:9], off
	global_load_dword v83, v[14:15], off
	global_load_dword v84, v[12:13], off
	global_load_dword v85, v[18:19], off
	global_load_dword v86, v[16:17], off
	global_load_dword v87, v[22:23], off
	global_load_dword v88, v[20:21], off
	global_load_dword v89, v[26:27], off
	global_load_dword v90, v[24:25], off
	global_load_dword v91, v[42:43], off
	global_load_dword v92, v[28:29], off
	global_load_dword v93, v[46:47], off
	global_load_dword v94, v[44:45], off
	s_add_i32 s11, s11, 16
	s_add_i32 s12, s12, 16
	s_add_i32 s14, s14, -16
	s_lshl_b32 s15, s12, 1
	s_lshl_b32 s16, s11, 1
	v_or_b32_e32 v170, s15, v1
	v_or_b32_e32 v181, s16, v32
	s_add_i32 s17, s15, 4
	s_add_i32 s18, s16, 4
	s_add_i32 s19, s15, 8
	s_add_i32 s20, s16, 8
	s_add_i32 s21, s15, 12
	s_add_i32 s22, s16, 12
	s_add_i32 s23, s15, 16
	s_add_i32 s26, s16, 16
	s_add_i32 s27, s15, 20
	s_add_i32 s34, s16, 20
	s_add_i32 s35, s15, 24
	s_add_i32 s40, s16, 24
	s_add_i32 s15, s15, 28
	s_add_i32 s16, s16, 28
	v_add_u32_e32 v146, s8, v181
	v_or_b32_e32 v188, s17, v1
	v_or_b32_e32 v189, s18, v32
	v_or_b32_e32 v190, s19, v1
	v_or_b32_e32 v191, s20, v32
	v_or_b32_e32 v192, s21, v1
	v_or_b32_e32 v193, s22, v32
	v_or_b32_e32 v194, s23, v1
	v_or_b32_e32 v195, s26, v32
	v_or_b32_e32 v196, s27, v1
	v_or_b32_e32 v197, s34, v32
	v_or_b32_e32 v211, s35, v1
	v_or_b32_e32 v216, s40, v32
	v_or_b32_e32 v217, s15, v1
	v_or_b32_e32 v218, s16, v32
	v_add_u32_e32 v144, s13, v170
	v_ashrrev_i32_e32 v147, 31, v146
	v_add_u32_e32 v148, s13, v188
	v_add_u32_e32 v150, s8, v189
	v_add_u32_e32 v152, s13, v190
	v_add_u32_e32 v154, s8, v191
	v_add_u32_e32 v156, s13, v192
	v_add_u32_e32 v158, s8, v193
	v_add_u32_e32 v160, s13, v194
	v_add_u32_e32 v162, s8, v195
	v_add_u32_e32 v164, s13, v196
	v_add_u32_e32 v166, s8, v197
	v_add_u32_e32 v168, s13, v211
	v_add_u32_e32 v182, s8, v216
	v_add_u32_e32 v184, s13, v217
	v_add_u32_e32 v186, s8, v218
	v_ashrrev_i32_e32 v145, 31, v144
	v_lshlrev_b64 v[146:147], 12, v[146:147]
	v_ashrrev_i32_e32 v151, 31, v150
	v_ashrrev_i32_e32 v149, 31, v148
	v_ashrrev_i32_e32 v155, 31, v154
	v_ashrrev_i32_e32 v153, 31, v152
	v_ashrrev_i32_e32 v159, 31, v158
	v_ashrrev_i32_e32 v157, 31, v156
	v_ashrrev_i32_e32 v163, 31, v162
	v_ashrrev_i32_e32 v161, 31, v160
	v_ashrrev_i32_e32 v167, 31, v166
	v_ashrrev_i32_e32 v165, 31, v164
	v_ashrrev_i32_e32 v183, 31, v182
	v_ashrrev_i32_e32 v169, 31, v168
; __device__ __forceinline__ void transpose_item(const float* W, int N, bf16_t* WT, int ldw, int drow0, int dk0, LAS float* scr, int k0, int n0, int lane) {
;     ...
;     for (int i = 0; i < 32; ++i) { const int kk = 2 * i + (lane >> 5); scr[kk * 33 + (lane & 31)] = W[(size_t)(k0 + kk) * N + n0 + (lane & 31)]; }
	v_ashrrev_i32_e32 v187, 31, v186
	v_ashrrev_i32_e32 v185, 31, v184
	v_lshlrev_b64 v[144:145], 12, v[144:145]
	v_lshl_add_u64 v[146:147], v[2:3], 0, v[146:147]
	v_lshlrev_b64 v[148:149], 12, v[148:149]
	v_lshlrev_b64 v[150:151], 12, v[150:151]
	v_lshlrev_b64 v[152:153], 12, v[152:153]
	v_lshlrev_b64 v[154:155], 12, v[154:155]
	v_lshlrev_b64 v[156:157], 12, v[156:157]
	v_lshlrev_b64 v[158:159], 12, v[158:159]
	v_lshlrev_b64 v[160:161], 12, v[160:161]
	v_lshlrev_b64 v[162:163], 12, v[162:163]
	v_lshlrev_b64 v[164:165], 12, v[164:165]
	v_lshlrev_b64 v[166:167], 12, v[166:167]
	v_lshlrev_b64 v[168:169], 12, v[168:169]
	v_lshlrev_b64 v[182:183], 12, v[182:183]
	v_lshlrev_b64 v[184:185], 12, v[184:185]
	v_lshlrev_b64 v[186:187], 12, v[186:187]
	v_lshl_add_u64 v[144:145], v[2:3], 0, v[144:145]
	v_lshl_add_u64 v[150:151], v[2:3], 0, v[150:151]
	v_lshl_add_u64 v[148:149], v[2:3], 0, v[148:149]
	v_lshl_add_u64 v[154:155], v[2:3], 0, v[154:155]
	v_lshl_add_u64 v[152:153], v[2:3], 0, v[152:153]
	v_lshl_add_u64 v[158:159], v[2:3], 0, v[158:159]
	v_lshl_add_u64 v[156:157], v[2:3], 0, v[156:157]
	v_lshl_add_u64 v[162:163], v[2:3], 0, v[162:163]
	v_lshl_add_u64 v[160:161], v[2:3], 0, v[160:161]
	v_lshl_add_u64 v[166:167], v[2:3], 0, v[166:167]
	v_lshl_add_u64 v[164:165], v[2:3], 0, v[164:165]
	v_lshl_add_u64 v[182:183], v[2:3], 0, v[182:183]
	v_lshl_add_u64 v[168:169], v[2:3], 0, v[168:169]
	v_lshl_add_u64 v[186:187], v[2:3], 0, v[186:187]
	v_lshl_add_u64 v[184:185], v[2:3], 0, v[184:185]
	global_load_dword v219, v[146:147], off
	global_load_dword v220, v[144:145], off
	global_load_dword v221, v[150:151], off
	global_load_dword v222, v[148:149], off
	global_load_dword v223, v[154:155], off
	global_load_dword v224, v[152:153], off
	global_load_dword v225, v[158:159], off
	global_load_dword v226, v[156:157], off
	global_load_dword v227, v[162:163], off
	global_load_dword v228, v[160:161], off
	global_load_dword v229, v[166:167], off
	global_load_dword v230, v[164:165], off
	global_load_dword v231, v[182:183], off
	global_load_dword v232, v[168:169], off
	global_load_dword v233, v[186:187], off
	global_load_dword v234, v[184:185], off
	v_mad_u64_u32 v[4:5], s[16:17], v41, s67, v[36:37]
	v_mad_u64_u32 v[6:7], s[16:17], v30, s67, v[36:37]
	v_mad_u64_u32 v[8:9], s[16:17], v49, s67, v[36:37]
	v_mad_u64_u32 v[10:11], s[16:17], v48, s67, v[36:37]
	v_mad_u64_u32 v[12:13], s[16:17], v51, s67, v[36:37]
	v_mad_u64_u32 v[14:15], s[16:17], v50, s67, v[36:37]
	v_mad_u64_u32 v[16:17], s[16:17], v53, s67, v[36:37]
	v_mad_u64_u32 v[18:19], s[16:17], v52, s67, v[36:37]
	v_mad_u64_u32 v[20:21], s[16:17], v55, s67, v[36:37]
	v_mad_u64_u32 v[22:23], s[16:17], v54, s67, v[36:37]
	v_mad_u64_u32 v[24:25], s[16:17], v57, s67, v[36:37]
	v_mad_u64_u32 v[26:27], s[16:17], v56, s67, v[36:37]
	v_mad_u64_u32 v[28:29], s[16:17], v76, s67, v[36:37]
	v_mad_u64_u32 v[42:43], s[16:17], v71, s67, v[36:37]
	v_mad_u64_u32 v[44:45], s[16:17], v78, s67, v[36:37]
	v_mad_u64_u32 v[46:47], s[16:17], v77, s67, v[36:37]
	s_waitcnt vmcnt(31)
	ds_write_b32 v4, v79
	s_waitcnt vmcnt(30)
	ds_write_b32 v6, v80
	s_waitcnt vmcnt(29)
	ds_write_b32 v8, v81
	s_waitcnt vmcnt(28)
	ds_write_b32 v10, v82
	s_waitcnt vmcnt(27)
	ds_write_b32 v12, v83
	s_waitcnt vmcnt(26)
	ds_write_b32 v14, v84
	s_waitcnt vmcnt(25)
	ds_write_b32 v16, v85
	s_waitcnt vmcnt(24)
	ds_write_b32 v18, v86
	s_waitcnt vmcnt(23)
	ds_write_b32 v20, v87
	s_waitcnt vmcnt(22)
	ds_write_b32 v22, v88
	s_waitcnt vmcnt(21)
	ds_write_b32 v24, v89
	s_waitcnt vmcnt(20)
	ds_write_b32 v26, v90
	s_waitcnt vmcnt(19)
	ds_write_b32 v28, v91
	s_waitcnt vmcnt(18)
	ds_write_b32 v42, v92
	s_waitcnt vmcnt(17)
	ds_write_b32 v44, v93
	s_waitcnt vmcnt(16)
; #define LAS __attribute__((address_space(3)))
; __device__ __forceinline__ unsigned cvtpk_s(float lo, float hi) { f32x2_t v = {lo, hi}; bf16x2_t b = __builtin_convertvector(v, bf16x2_t); return __builtin_bit_cast(unsigned, b); }
; #define LDS_WAIT() asm volatile("s_waitcnt lgkmcnt(0)" ::: "memory")
; __device__ __forceinline__ void transpose_item(const float* W, int N, bf16_t* WT, int ldw, int drow0, int dk0, LAS float* scr, int k0, int n0, int lane) {
;     ...
;     for (int i = 0; i < 32; ++i) { const int kk = 2 * i + (lane >> 5); scr[kk * 33 + (lane & 31)] = W[(size_t)(k0 + kk) * N + n0 + (lane & 31)]; }
;     LDS_WAIT(); asm volatile("" ::: "memory");
;     const int c = lane & 7;
; #pragma unroll
;     for (int j = 0; j < 4; ++j) { const int n = (lane >> 3) + 8 * j; const LAS float* s = scr + (8 * c) * 33 + n;
;         u32x4 o; o.x = cvtpk_s(s[0 * 33], s[1 * 33]); o.y = cvtpk_s(s[2 * 33], s[3 * 33]); o.z = cvtpk_s(s[4 * 33], s[5 * 33]); o.w = cvtpk_s(s[6 * 33], s[7 * 33]);
;         *(u32x4*)(WT + (size_t)(drow0 + n) * ldw + dk0 + k0 + 8 * c) = o; }
	ds_write_b32 v46, v94
	s_add_i32 s11, s11, 16
	s_add_i32 s12, s12, 16
	s_add_i32 s14, s14, -16
	v_mad_u64_u32 v[144:145], s[16:17], v181, s67, v[36:37]
	v_mad_u64_u32 v[146:147], s[16:17], v170, s67, v[36:37]
	v_mad_u64_u32 v[148:149], s[16:17], v189, s67, v[36:37]
	v_mad_u64_u32 v[150:151], s[16:17], v188, s67, v[36:37]
	v_mad_u64_u32 v[152:153], s[16:17], v191, s67, v[36:37]
	v_mad_u64_u32 v[154:155], s[16:17], v190, s67, v[36:37]
	v_mad_u64_u32 v[156:157], s[16:17], v193, s67, v[36:37]
	v_mad_u64_u32 v[158:159], s[16:17], v192, s67, v[36:37]
	v_mad_u64_u32 v[160:161], s[16:17], v195, s67, v[36:37]
	v_mad_u64_u32 v[162:163], s[16:17], v194, s67, v[36:37]
	v_mad_u64_u32 v[164:165], s[16:17], v197, s67, v[36:37]
	v_mad_u64_u32 v[166:167], s[16:17], v196, s67, v[36:37]
	v_mad_u64_u32 v[168:169], s[16:17], v216, s67, v[36:37]
	v_mad_u64_u32 v[182:183], s[16:17], v211, s67, v[36:37]
	v_mad_u64_u32 v[184:185], s[16:17], v218, s67, v[36:37]
	v_mad_u64_u32 v[186:187], s[16:17], v217, s67, v[36:37]
	s_waitcnt vmcnt(15)
	ds_write_b32 v144, v219
	s_waitcnt vmcnt(14)
	ds_write_b32 v146, v220
	s_waitcnt vmcnt(13)
	ds_write_b32 v148, v221
	s_waitcnt vmcnt(12)
	ds_write_b32 v150, v222
	s_waitcnt vmcnt(11)
	ds_write_b32 v152, v223
	s_waitcnt vmcnt(10)
	ds_write_b32 v154, v224
	s_waitcnt vmcnt(9)
	ds_write_b32 v156, v225
	s_waitcnt vmcnt(8)
	ds_write_b32 v158, v226
	s_waitcnt vmcnt(7)
	ds_write_b32 v160, v227
	s_waitcnt vmcnt(6)
	ds_write_b32 v162, v228
	s_waitcnt vmcnt(5)
	ds_write_b32 v164, v229
	s_waitcnt vmcnt(4)
	ds_write_b32 v166, v230
	s_waitcnt vmcnt(3)
	ds_write_b32 v168, v231
	s_waitcnt vmcnt(2)
	ds_write_b32 v182, v232
	s_waitcnt vmcnt(1)
	ds_write_b32 v184, v233
	s_waitcnt vmcnt(0)
	ds_write_b32 v186, v234
	s_lshl_b32 s11, s3, 6
	s_and_b32 s9, s9, 0x60
	s_and_b32 s11, s11, 0x700
	s_or_b32 s11, s11, s9
	s_waitcnt lgkmcnt(0)
	s_mov_b32 s9, s41
	s_lshl_b64 s[8:9], s[8:9], 1
	s_add_u32 s8, s4, s8
	ds_read2_b32 v[6:7], v60 offset0:33 offset1:41
	ds_read2_b32 v[8:9], v60 offset1:8
	ds_read2_b32 v[10:11], v60 offset0:66 offset1:74
	ds_read2_b32 v[12:13], v60 offset0:99 offset1:107
	ds_read2_b32 v[14:15], v60 offset0:132 offset1:140
	ds_read2_b32 v[16:17], v60 offset0:165 offset1:173
	ds_read2_b32 v[18:19], v60 offset0:198 offset1:206
	ds_read2_b32 v[20:21], v60 offset0:231 offset1:239
	s_addc_u32 s9, s5, s9
	v_lshlrev_b32_e32 v30, 1, v38
	v_lshl_add_u64 v[2:3], s[8:9], 0, v[30:31]
	v_lshl_add_u64 v[22:23], v[2:3], 0, s[54:55]
	s_waitcnt lgkmcnt(6)
	v_cvt_pk_bf16_f32 v2, v8, v6
	v_or_b32_e32 v6, s11, v59
	v_lshlrev_b32_e32 v30, 11, v6
	s_waitcnt lgkmcnt(4)
	v_cvt_pk_bf16_f32 v3, v10, v12
	s_waitcnt lgkmcnt(2)
	v_cvt_pk_bf16_f32 v4, v14, v16
	s_waitcnt lgkmcnt(0)
	v_cvt_pk_bf16_f32 v5, v18, v20
	v_lshl_add_u64 v[24:25], v[22:23], 0, v[30:31]
	global_store_dwordx4 v[24:25], v[2:5], off
	v_or_b32_e32 v6, s11, v61
	v_lshlrev_b32_e32 v30, 11, v6
	v_cvt_pk_bf16_f32 v2, v9, v7
	v_cvt_pk_bf16_f32 v3, v11, v13
	v_cvt_pk_bf16_f32 v4, v15, v17
	v_cvt_pk_bf16_f32 v5, v19, v21
	ds_read2_b32 v[8:9], v60 offset0:49 offset1:57
	ds_read2_b32 v[10:11], v60 offset0:16 offset1:24
	ds_read2_b32 v[12:13], v60 offset0:82 offset1:90
	ds_read2_b32 v[14:15], v60 offset0:115 offset1:123
	ds_read2_b32 v[16:17], v60 offset0:148 offset1:156
	ds_read2_b32 v[18:19], v60 offset0:181 offset1:189
	ds_read2_b32 v[20:21], v60 offset0:214 offset1:222
	ds_read2_b32 v[24:25], v60 offset0:247 offset1:255
	v_lshl_add_u64 v[6:7], v[22:23], 0, v[30:31]
	global_store_dwordx4 v[6:7], v[2:5], off
	v_or_b32_e32 v6, s11, v62
	v_lshlrev_b32_e32 v30, 11, v6
	s_waitcnt lgkmcnt(6)
	v_cvt_pk_bf16_f32 v2, v10, v8
	s_waitcnt lgkmcnt(4)
	v_cvt_pk_bf16_f32 v3, v12, v14
	s_waitcnt lgkmcnt(2)
	v_cvt_pk_bf16_f32 v4, v16, v18
	s_waitcnt lgkmcnt(0)
	v_cvt_pk_bf16_f32 v5, v20, v24
	v_lshl_add_u64 v[6:7], v[22:23], 0, v[30:31]
	global_store_dwordx4 v[6:7], v[2:5], off
	v_or_b32_e32 v6, s11, v63
	v_lshlrev_b32_e32 v30, 11, v6
	v_cvt_pk_bf16_f32 v2, v11, v9
	v_cvt_pk_bf16_f32 v3, v13, v15
	v_cvt_pk_bf16_f32 v4, v17, v19
	v_cvt_pk_bf16_f32 v5, v21, v25
	v_lshl_add_u64 v[6:7], v[22:23], 0, v[30:31]
	global_store_dwordx4 v[6:7], v[2:5], off
	s_waitcnt lgkmcnt(0)

; #define LAS __attribute__((address_space(3)))
; #define LDS_WAIT() asm volatile("s_waitcnt lgkmcnt(0)" ::: "memory")
; __device__ __forceinline__ void transpose_item(const float* W, int N, bf16_t* WT, int ldw, int drow0, int dk0, LAS float* scr, int k0, int n0, int lane) {
; #pragma unroll 8
;     for (int i = 0; i < 32; ++i) { const int kk = 2 * i + (lane >> 5); scr[kk * 33 + (lane & 31)] = W[(size_t)(k0 + kk) * N + n0 + (lane & 31)]; }
;     LDS_WAIT(); asm volatile("" ::: "memory");
.LBB0_70:
	s_lshl_b32 s15, s13, 1
	s_lshl_b32 s16, s8, 1
	v_or_b32_e32 v30, s15, v1
	v_or_b32_e32 v41, s16, v32
	s_add_i32 s17, s15, 4
	s_add_i32 s18, s16, 4
	s_add_i32 s19, s15, 8
	s_add_i32 s20, s16, 8
	s_add_i32 s21, s15, 12
	s_add_i32 s22, s16, 12
	s_add_i32 s23, s15, 16
	s_add_i32 s26, s16, 16
	s_add_i32 s27, s15, 20
	s_add_i32 s34, s16, 20
	s_add_i32 s35, s15, 24
	s_add_i32 s40, s16, 24
	s_add_i32 s15, s15, 28
	s_add_i32 s16, s16, 28
	v_add_u32_e32 v4, s9, v41
	v_or_b32_e32 v48, s17, v1
	v_or_b32_e32 v49, s18, v32
	v_or_b32_e32 v50, s19, v1
	v_or_b32_e32 v51, s20, v32
	v_or_b32_e32 v52, s21, v1
	v_or_b32_e32 v53, s22, v32
	v_or_b32_e32 v54, s23, v1
	v_or_b32_e32 v55, s26, v32
	v_or_b32_e32 v56, s27, v1
	v_or_b32_e32 v57, s34, v32
	v_or_b32_e32 v71, s35, v1
	v_or_b32_e32 v76, s40, v32
	v_or_b32_e32 v77, s15, v1
	v_or_b32_e32 v78, s16, v32
	v_add_u32_e32 v6, s12, v30
	v_mad_u64_u32 v[4:5], s[16:17], v4, s83, v[2:3]
	v_add_u32_e32 v10, s12, v48
	v_add_u32_e32 v8, s9, v49
	v_add_u32_e32 v14, s12, v50
	v_add_u32_e32 v12, s9, v51
	v_add_u32_e32 v18, s12, v52
	v_add_u32_e32 v16, s9, v53
	v_add_u32_e32 v22, s12, v54
	v_add_u32_e32 v20, s9, v55
	v_add_u32_e32 v26, s12, v56
	v_add_u32_e32 v24, s9, v57
	v_add_u32_e32 v42, s12, v71
	v_add_u32_e32 v28, s9, v76
	v_add_u32_e32 v46, s12, v77
	v_add_u32_e32 v44, s9, v78
	v_mad_u64_u32 v[6:7], s[16:17], v6, s83, v[2:3]
	v_mad_u64_u32 v[8:9], s[16:17], v8, s83, v[2:3]
	v_mad_u64_u32 v[10:11], s[16:17], v10, s83, v[2:3]
	v_mad_u64_u32 v[12:13], s[16:17], v12, s83, v[2:3]
	v_mad_u64_u32 v[14:15], s[16:17], v14, s83, v[2:3]
	v_mad_u64_u32 v[16:17], s[16:17], v16, s83, v[2:3]
	v_mad_u64_u32 v[18:19], s[16:17], v18, s83, v[2:3]
	v_mad_u64_u32 v[20:21], s[16:17], v20, s83, v[2:3]
	v_mad_u64_u32 v[22:23], s[16:17], v22, s83, v[2:3]
	v_mad_u64_u32 v[24:25], s[16:17], v24, s83, v[2:3]
	v_mad_u64_u32 v[26:27], s[16:17], v26, s83, v[2:3]
	v_mad_u64_u32 v[28:29], s[16:17], v28, s83, v[2:3]
	v_mad_u64_u32 v[42:43], s[16:17], v42, s83, v[2:3]
	v_mad_u64_u32 v[44:45], s[16:17], v44, s83, v[2:3]
	v_mad_u64_u32 v[46:47], s[16:17], v46, s83, v[2:3]
	global_load_dword v79, v[4:5], off
	global_load_dword v80, v[6:7], off
	global_load_dword v81, v[8:9], off
	global_load_dword v82, v[10:11], off
	global_load_dword v83, v[12:13], off
	global_load_dword v84, v[14:15], off
	global_load_dword v85, v[16:17], off
	global_load_dword v86, v[18:19], off
	global_load_dword v87, v[20:21], off
	global_load_dword v88, v[22:23], off
	global_load_dword v89, v[24:25], off
	global_load_dword v90, v[26:27], off
	global_load_dword v91, v[28:29], off
	global_load_dword v92, v[42:43], off
	global_load_dword v93, v[44:45], off
	global_load_dword v94, v[46:47], off
	s_add_i32 s8, s8, 16
	s_add_i32 s13, s13, 16
	s_add_i32 s14, s14, -16
	s_lshl_b32 s15, s13, 1
	s_lshl_b32 s16, s8, 1
	v_or_b32_e32 v170, s15, v1
	v_or_b32_e32 v181, s16, v32
	s_add_i32 s17, s15, 4
	s_add_i32 s18, s16, 4
	s_add_i32 s19, s15, 8
	s_add_i32 s20, s16, 8
	s_add_i32 s21, s15, 12
	s_add_i32 s22, s16, 12
	s_add_i32 s23, s15, 16
	s_add_i32 s26, s16, 16
	s_add_i32 s27, s15, 20
	s_add_i32 s34, s16, 20
	s_add_i32 s35, s15, 24
	s_add_i32 s40, s16, 24
	s_add_i32 s15, s15, 28
	s_add_i32 s16, s16, 28
	v_add_u32_e32 v144, s9, v181
	v_or_b32_e32 v188, s17, v1
	v_or_b32_e32 v189, s18, v32
	v_or_b32_e32 v190, s19, v1
	v_or_b32_e32 v191, s20, v32
	v_or_b32_e32 v192, s21, v1
	v_or_b32_e32 v193, s22, v32
	v_or_b32_e32 v194, s23, v1
	v_or_b32_e32 v195, s26, v32
	v_or_b32_e32 v196, s27, v1
	v_or_b32_e32 v197, s34, v32
	v_or_b32_e32 v211, s35, v1
	v_or_b32_e32 v216, s40, v32
	v_or_b32_e32 v217, s15, v1
	v_or_b32_e32 v218, s16, v32
	v_add_u32_e32 v146, s12, v170
	v_mad_u64_u32 v[144:145], s[16:17], v144, s83, v[2:3]
	v_add_u32_e32 v150, s12, v188
	v_add_u32_e32 v148, s9, v189
	v_add_u32_e32 v154, s12, v190
	v_add_u32_e32 v152, s9, v191
	v_add_u32_e32 v158, s12, v192
	v_add_u32_e32 v156, s9, v193
	v_add_u32_e32 v162, s12, v194
	v_add_u32_e32 v160, s9, v195
	v_add_u32_e32 v166, s12, v196
	v_add_u32_e32 v164, s9, v197
	v_add_u32_e32 v182, s12, v211
	v_add_u32_e32 v168, s9, v216
	v_add_u32_e32 v186, s12, v217
	v_add_u32_e32 v184, s9, v218
	v_mad_u64_u32 v[146:147], s[16:17], v146, s83, v[2:3]
	v_mad_u64_u32 v[148:149], s[16:17], v148, s83, v[2:3]
	v_mad_u64_u32 v[150:151], s[16:17], v150, s83, v[2:3]
	v_mad_u64_u32 v[152:153], s[16:17], v152, s83, v[2:3]
	v_mad_u64_u32 v[154:155], s[16:17], v154, s83, v[2:3]
	v_mad_u64_u32 v[156:157], s[16:17], v156, s83, v[2:3]
	v_mad_u64_u32 v[158:159], s[16:17], v158, s83, v[2:3]
	v_mad_u64_u32 v[160:161], s[16:17], v160, s83, v[2:3]
	v_mad_u64_u32 v[162:163], s[16:17], v162, s83, v[2:3]
	v_mad_u64_u32 v[164:165], s[16:17], v164, s83, v[2:3]
	v_mad_u64_u32 v[166:167], s[16:17], v166, s83, v[2:3]
	v_mad_u64_u32 v[168:169], s[16:17], v168, s83, v[2:3]
	v_mad_u64_u32 v[182:183], s[16:17], v182, s83, v[2:3]
	v_mad_u64_u32 v[184:185], s[16:17], v184, s83, v[2:3]
	v_mad_u64_u32 v[186:187], s[16:17], v186, s83, v[2:3]
	global_load_dword v219, v[144:145], off
	global_load_dword v220, v[146:147], off
	global_load_dword v221, v[148:149], off
	global_load_dword v222, v[150:151], off
	global_load_dword v223, v[152:153], off
	global_load_dword v224, v[154:155], off
	global_load_dword v225, v[156:157], off
	global_load_dword v226, v[158:159], off
	global_load_dword v227, v[160:161], off
	global_load_dword v228, v[162:163], off
	global_load_dword v229, v[164:165], off
	global_load_dword v230, v[166:167], off
	global_load_dword v231, v[168:169], off
	global_load_dword v232, v[182:183], off
	global_load_dword v233, v[184:185], off
	global_load_dword v234, v[186:187], off
	v_mad_u64_u32 v[4:5], s[16:17], v41, s67, v[36:37]
	v_mad_u64_u32 v[6:7], s[16:17], v30, s67, v[36:37]
	v_mad_u64_u32 v[8:9], s[16:17], v49, s67, v[36:37]
	v_mad_u64_u32 v[10:11], s[16:17], v48, s67, v[36:37]
	v_mad_u64_u32 v[12:13], s[16:17], v51, s67, v[36:37]
	v_mad_u64_u32 v[14:15], s[16:17], v50, s67, v[36:37]
	v_mad_u64_u32 v[16:17], s[16:17], v53, s67, v[36:37]
	v_mad_u64_u32 v[18:19], s[16:17], v52, s67, v[36:37]
	v_mad_u64_u32 v[20:21], s[16:17], v55, s67, v[36:37]
	v_mad_u64_u32 v[22:23], s[16:17], v54, s67, v[36:37]
	v_mad_u64_u32 v[24:25], s[16:17], v57, s67, v[36:37]
	v_mad_u64_u32 v[26:27], s[16:17], v56, s67, v[36:37]
	v_mad_u64_u32 v[28:29], s[16:17], v76, s67, v[36:37]
	v_mad_u64_u32 v[42:43], s[16:17], v71, s67, v[36:37]
	v_mad_u64_u32 v[44:45], s[16:17], v78, s67, v[36:37]
	v_mad_u64_u32 v[46:47], s[16:17], v77, s67, v[36:37]
	s_waitcnt vmcnt(31)
; #define LAS __attribute__((address_space(3)))
; __device__ __forceinline__ unsigned cvtpk_s(float lo, float hi) { f32x2_t v = {lo, hi}; bf16x2_t b = __builtin_convertvector(v, bf16x2_t); return __builtin_bit_cast(unsigned, b); }
; #define LDS_WAIT() asm volatile("s_waitcnt lgkmcnt(0)" ::: "memory")
; __device__ __forceinline__ void transpose_item(const float* W, int N, bf16_t* WT, int ldw, int drow0, int dk0, LAS float* scr, int k0, int n0, int lane) {
;     ...
;     for (int i = 0; i < 32; ++i) { const int kk = 2 * i + (lane >> 5); scr[kk * 33 + (lane & 31)] = W[(size_t)(k0 + kk) * N + n0 + (lane & 31)]; }
;     LDS_WAIT(); asm volatile("" ::: "memory");
;     const int c = lane & 7;
; #pragma unroll
;     for (int j = 0; j < 4; ++j) { const int n = (lane >> 3) + 8 * j; const LAS float* s = scr + (8 * c) * 33 + n;
;         u32x4 o; o.x = cvtpk_s(s[0 * 33], s[1 * 33]); o.y = cvtpk_s(s[2 * 33], s[3 * 33]); o.z = cvtpk_s(s[4 * 33], s[5 * 33]); o.w = cvtpk_s(s[6 * 33], s[7 * 33]);
;         *(u32x4*)(WT + (size_t)(drow0 + n) * ldw + dk0 + k0 + 8 * c) = o; }
;     LDS_WAIT(); asm volatile("" ::: "memory");
	ds_write_b32 v4, v79
	s_waitcnt vmcnt(30)
	ds_write_b32 v6, v80
	s_waitcnt vmcnt(29)
	ds_write_b32 v8, v81
	s_waitcnt vmcnt(28)
	ds_write_b32 v10, v82
	s_waitcnt vmcnt(27)
	ds_write_b32 v12, v83
	s_waitcnt vmcnt(26)
	ds_write_b32 v14, v84
	s_waitcnt vmcnt(25)
	ds_write_b32 v16, v85
	s_waitcnt vmcnt(24)
	ds_write_b32 v18, v86
	s_waitcnt vmcnt(23)
	ds_write_b32 v20, v87
	s_waitcnt vmcnt(22)
	ds_write_b32 v22, v88
	s_waitcnt vmcnt(21)
	ds_write_b32 v24, v89
	s_waitcnt vmcnt(20)
	ds_write_b32 v26, v90
	s_waitcnt vmcnt(19)
	ds_write_b32 v28, v91
	s_waitcnt vmcnt(18)
	ds_write_b32 v42, v92
	s_waitcnt vmcnt(17)
	ds_write_b32 v44, v93
	s_waitcnt vmcnt(16)
	ds_write_b32 v46, v94
	s_add_i32 s8, s8, 16
	s_add_i32 s13, s13, 16
	s_add_i32 s14, s14, -16
	v_mad_u64_u32 v[144:145], s[16:17], v181, s67, v[36:37]
	v_mad_u64_u32 v[146:147], s[16:17], v170, s67, v[36:37]
	v_mad_u64_u32 v[148:149], s[16:17], v189, s67, v[36:37]
	v_mad_u64_u32 v[150:151], s[16:17], v188, s67, v[36:37]
	v_mad_u64_u32 v[152:153], s[16:17], v191, s67, v[36:37]
	v_mad_u64_u32 v[154:155], s[16:17], v190, s67, v[36:37]
	v_mad_u64_u32 v[156:157], s[16:17], v193, s67, v[36:37]
	v_mad_u64_u32 v[158:159], s[16:17], v192, s67, v[36:37]
	v_mad_u64_u32 v[160:161], s[16:17], v195, s67, v[36:37]
	v_mad_u64_u32 v[162:163], s[16:17], v194, s67, v[36:37]
	v_mad_u64_u32 v[164:165], s[16:17], v197, s67, v[36:37]
	v_mad_u64_u32 v[166:167], s[16:17], v196, s67, v[36:37]
	v_mad_u64_u32 v[168:169], s[16:17], v216, s67, v[36:37]
	v_mad_u64_u32 v[182:183], s[16:17], v211, s67, v[36:37]
	v_mad_u64_u32 v[184:185], s[16:17], v218, s67, v[36:37]
	v_mad_u64_u32 v[186:187], s[16:17], v217, s67, v[36:37]
	s_waitcnt vmcnt(15)
	ds_write_b32 v144, v219
	s_waitcnt vmcnt(14)
	ds_write_b32 v146, v220
	s_waitcnt vmcnt(13)
	ds_write_b32 v148, v221
	s_waitcnt vmcnt(12)
	ds_write_b32 v150, v222
	s_waitcnt vmcnt(11)
	ds_write_b32 v152, v223
	s_waitcnt vmcnt(10)
	ds_write_b32 v154, v224
	s_waitcnt vmcnt(9)
	ds_write_b32 v156, v225
	s_waitcnt vmcnt(8)
	ds_write_b32 v158, v226
	s_waitcnt vmcnt(7)
	ds_write_b32 v160, v227
	s_waitcnt vmcnt(6)
	ds_write_b32 v162, v228
	s_waitcnt vmcnt(5)
	ds_write_b32 v164, v229
	s_waitcnt vmcnt(4)
	ds_write_b32 v166, v230
	s_waitcnt vmcnt(3)
	ds_write_b32 v168, v231
	s_waitcnt vmcnt(2)
	ds_write_b32 v182, v232
	s_waitcnt vmcnt(1)
	ds_write_b32 v184, v233
	s_waitcnt vmcnt(0)
	ds_write_b32 v186, v234
	s_waitcnt lgkmcnt(0)
	s_and_b32 s8, 0xffff, s9
	s_and_b32 s11, 0xffff, s11
	s_lshl_b32 s8, s8, 1
	s_add_u32 s8, s4, s8
	ds_read2_b32 v[6:7], v60 offset0:33 offset1:41
	ds_read2_b32 v[8:9], v60 offset1:8
	ds_read2_b32 v[10:11], v60 offset0:66 offset1:74
	ds_read2_b32 v[12:13], v60 offset0:99 offset1:107
	ds_read2_b32 v[14:15], v60 offset0:132 offset1:140
	ds_read2_b32 v[16:17], v60 offset0:165 offset1:173
	ds_read2_b32 v[18:19], v60 offset0:198 offset1:206
	ds_read2_b32 v[20:21], v60 offset0:231 offset1:239
	s_addc_u32 s9, s5, 0
	v_lshlrev_b32_e32 v30, 1, v38
	v_lshl_add_u64 v[2:3], s[8:9], 0, v[30:31]
	v_lshl_add_u64 v[22:23], v[2:3], 0, s[56:57]
	s_waitcnt lgkmcnt(6)
	v_cvt_pk_bf16_f32 v2, v8, v6
	v_or_b32_e32 v6, s11, v59
	v_lshlrev_b32_e32 v30, 11, v6
	s_waitcnt lgkmcnt(4)
	v_cvt_pk_bf16_f32 v3, v10, v12
	s_waitcnt lgkmcnt(2)
	v_cvt_pk_bf16_f32 v4, v14, v16
	s_waitcnt lgkmcnt(0)
	v_cvt_pk_bf16_f32 v5, v18, v20
	v_lshl_add_u64 v[24:25], v[22:23], 0, v[30:31]
	global_store_dwordx4 v[24:25], v[2:5], off
	v_or_b32_e32 v6, s11, v61
	v_lshlrev_b32_e32 v30, 11, v6
	v_cvt_pk_bf16_f32 v2, v9, v7
	v_cvt_pk_bf16_f32 v3, v11, v13
	v_cvt_pk_bf16_f32 v4, v15, v17
	v_cvt_pk_bf16_f32 v5, v19, v21
	ds_read2_b32 v[8:9], v60 offset0:49 offset1:57
	ds_read2_b32 v[10:11], v60 offset0:16 offset1:24
	ds_read2_b32 v[12:13], v60 offset0:82 offset1:90
	ds_read2_b32 v[14:15], v60 offset0:115 offset1:123
	ds_read2_b32 v[16:17], v60 offset0:148 offset1:156
	ds_read2_b32 v[18:19], v60 offset0:181 offset1:189
	ds_read2_b32 v[20:21], v60 offset0:214 offset1:222
	ds_read2_b32 v[24:25], v60 offset0:247 offset1:255
	v_lshl_add_u64 v[6:7], v[22:23], 0, v[30:31]
	global_store_dwordx4 v[6:7], v[2:5], off
	v_or_b32_e32 v6, s11, v62
	v_lshlrev_b32_e32 v30, 11, v6
	s_waitcnt lgkmcnt(6)
	v_cvt_pk_bf16_f32 v2, v10, v8
	s_waitcnt lgkmcnt(4)
	v_cvt_pk_bf16_f32 v3, v12, v14
	s_waitcnt lgkmcnt(2)
	v_cvt_pk_bf16_f32 v4, v16, v18
	s_waitcnt lgkmcnt(0)
	v_cvt_pk_bf16_f32 v5, v20, v24
	v_lshl_add_u64 v[6:7], v[22:23], 0, v[30:31]
	global_store_dwordx4 v[6:7], v[2:5], off
	v_or_b32_e32 v6, s11, v63
	v_lshlrev_b32_e32 v30, 11, v6
	v_cvt_pk_bf16_f32 v2, v11, v9
	v_cvt_pk_bf16_f32 v3, v13, v15
	v_cvt_pk_bf16_f32 v4, v17, v19
	v_cvt_pk_bf16_f32 v5, v21, v25
	v_lshl_add_u64 v[6:7], v[22:23], 0, v[30:31]
	global_store_dwordx4 v[6:7], v[2:5], off
	s_waitcnt lgkmcnt(0)

; #define LAS __attribute__((address_space(3)))
; #define LDS_WAIT() asm volatile("s_waitcnt lgkmcnt(0)" ::: "memory")
; __device__ __forceinline__ void transpose_item(const float* W, int N, bf16_t* WT, int ldw, int drow0, int dk0, LAS float* scr, int k0, int n0, int lane) {
; #pragma unroll 8
;     for (int i = 0; i < 32; ++i) { const int kk = 2 * i + (lane >> 5); scr[kk * 33 + (lane & 31)] = W[(size_t)(k0 + kk) * N + n0 + (lane & 31)]; }
;     LDS_WAIT(); asm volatile("" ::: "memory");
.LBB0_75:
	s_lshl_b32 s15, s12, 1
	s_lshl_b32 s16, s9, 1
	v_or_b32_e32 v30, s15, v1
	v_or_b32_e32 v41, s16, v32
	s_add_i32 s17, s15, 4
	s_add_i32 s18, s16, 4
	s_add_i32 s19, s15, 8
	s_add_i32 s20, s16, 8
	s_add_i32 s21, s15, 12
	s_add_i32 s22, s16, 12
	s_add_i32 s23, s15, 16
	s_add_i32 s26, s16, 16
	s_add_i32 s27, s15, 20
	s_add_i32 s34, s16, 20
	s_add_i32 s35, s15, 24
	s_add_i32 s40, s16, 24
	s_add_i32 s15, s15, 28
	s_add_i32 s16, s16, 28
	v_add_u32_e32 v6, s8, v41
	v_or_b32_e32 v48, s17, v1
	v_or_b32_e32 v49, s18, v32
	v_or_b32_e32 v50, s19, v1
	v_or_b32_e32 v51, s20, v32
	v_or_b32_e32 v52, s21, v1
	v_or_b32_e32 v53, s22, v32
	v_or_b32_e32 v54, s23, v1
	v_or_b32_e32 v55, s26, v32
	v_or_b32_e32 v56, s27, v1
	v_or_b32_e32 v57, s34, v32
	v_or_b32_e32 v71, s35, v1
	v_or_b32_e32 v76, s40, v32
	v_or_b32_e32 v77, s15, v1
	v_or_b32_e32 v78, s16, v32
	v_add_u32_e32 v4, s13, v30
	v_ashrrev_i32_e32 v7, 31, v6
	v_add_u32_e32 v8, s13, v48
	v_add_u32_e32 v10, s8, v49
	v_add_u32_e32 v12, s13, v50
	v_add_u32_e32 v14, s8, v51
	v_add_u32_e32 v16, s13, v52
	v_add_u32_e32 v18, s8, v53
	v_add_u32_e32 v20, s13, v54
	v_add_u32_e32 v22, s8, v55
	v_add_u32_e32 v24, s13, v56
	v_add_u32_e32 v26, s8, v57
	v_add_u32_e32 v28, s13, v71
	v_add_u32_e32 v42, s8, v76
	v_add_u32_e32 v44, s13, v77
	v_add_u32_e32 v46, s8, v78
	v_ashrrev_i32_e32 v5, 31, v4
	v_lshlrev_b64 v[6:7], 12, v[6:7]
	v_ashrrev_i32_e32 v11, 31, v10
	v_ashrrev_i32_e32 v9, 31, v8
	v_ashrrev_i32_e32 v15, 31, v14
	v_ashrrev_i32_e32 v13, 31, v12
	v_ashrrev_i32_e32 v19, 31, v18
	v_ashrrev_i32_e32 v17, 31, v16
	v_ashrrev_i32_e32 v23, 31, v22
	v_ashrrev_i32_e32 v21, 31, v20
	v_ashrrev_i32_e32 v27, 31, v26
	v_ashrrev_i32_e32 v25, 31, v24
	v_ashrrev_i32_e32 v43, 31, v42
	v_ashrrev_i32_e32 v29, 31, v28
	v_ashrrev_i32_e32 v47, 31, v46
	v_ashrrev_i32_e32 v45, 31, v44
	v_lshlrev_b64 v[4:5], 12, v[4:5]
	v_lshl_add_u64 v[6:7], v[2:3], 0, v[6:7]
	v_lshlrev_b64 v[8:9], 12, v[8:9]
	v_lshlrev_b64 v[10:11], 12, v[10:11]
	v_lshlrev_b64 v[12:13], 12, v[12:13]
	v_lshlrev_b64 v[14:15], 12, v[14:15]
	v_lshlrev_b64 v[16:17], 12, v[16:17]
	v_lshlrev_b64 v[18:19], 12, v[18:19]
	v_lshlrev_b64 v[20:21], 12, v[20:21]
	v_lshlrev_b64 v[22:23], 12, v[22:23]
	v_lshlrev_b64 v[24:25], 12, v[24:25]
	v_lshlrev_b64 v[26:27], 12, v[26:27]
	v_lshlrev_b64 v[28:29], 12, v[28:29]
	v_lshlrev_b64 v[42:43], 12, v[42:43]
	v_lshlrev_b64 v[44:45], 12, v[44:45]
	v_lshlrev_b64 v[46:47], 12, v[46:47]
	v_lshl_add_u64 v[4:5], v[2:3], 0, v[4:5]
	v_lshl_add_u64 v[10:11], v[2:3], 0, v[10:11]
	v_lshl_add_u64 v[8:9], v[2:3], 0, v[8:9]
	v_lshl_add_u64 v[14:15], v[2:3], 0, v[14:15]
	v_lshl_add_u64 v[12:13], v[2:3], 0, v[12:13]
	v_lshl_add_u64 v[18:19], v[2:3], 0, v[18:19]
	v_lshl_add_u64 v[16:17], v[2:3], 0, v[16:17]
	v_lshl_add_u64 v[22:23], v[2:3], 0, v[22:23]
	v_lshl_add_u64 v[20:21], v[2:3], 0, v[20:21]
	v_lshl_add_u64 v[26:27], v[2:3], 0, v[26:27]
	v_lshl_add_u64 v[24:25], v[2:3], 0, v[24:25]
	v_lshl_add_u64 v[42:43], v[2:3], 0, v[42:43]
	v_lshl_add_u64 v[28:29], v[2:3], 0, v[28:29]
	v_lshl_add_u64 v[46:47], v[2:3], 0, v[46:47]
	v_lshl_add_u64 v[44:45], v[2:3], 0, v[44:45]
	global_load_dword v79, v[6:7], off
	global_load_dword v80, v[4:5], off
	global_load_dword v81, v[10:11], off
	global_load_dword v82, v[8:9], off
	global_load_dword v83, v[14:15], off
	global_load_dword v84, v[12:13], off
	global_load_dword v85, v[18:19], off
	global_load_dword v86, v[16:17], off
	global_load_dword v87, v[22:23], off
	global_load_dword v88, v[20:21], off
	global_load_dword v89, v[26:27], off
	global_load_dword v90, v[24:25], off
	global_load_dword v91, v[42:43], off
	global_load_dword v92, v[28:29], off
	global_load_dword v93, v[46:47], off
	global_load_dword v94, v[44:45], off
	s_add_i32 s9, s9, 16
	s_add_i32 s12, s12, 16
	s_add_i32 s14, s14, -16
	s_lshl_b32 s15, s12, 1
	s_lshl_b32 s16, s9, 1
	v_or_b32_e32 v170, s15, v1
	v_or_b32_e32 v181, s16, v32
	s_add_i32 s17, s15, 4
	s_add_i32 s18, s16, 4
	s_add_i32 s19, s15, 8
	s_add_i32 s20, s16, 8
	s_add_i32 s21, s15, 12
	s_add_i32 s22, s16, 12
	s_add_i32 s23, s15, 16
	s_add_i32 s26, s16, 16
	s_add_i32 s27, s15, 20
	s_add_i32 s34, s16, 20
	s_add_i32 s35, s15, 24
	s_add_i32 s40, s16, 24
	s_add_i32 s15, s15, 28
	s_add_i32 s16, s16, 28
	v_add_u32_e32 v146, s8, v181
	v_or_b32_e32 v188, s17, v1
	v_or_b32_e32 v189, s18, v32
	v_or_b32_e32 v190, s19, v1
	v_or_b32_e32 v191, s20, v32
	v_or_b32_e32 v192, s21, v1
	v_or_b32_e32 v193, s22, v32
	v_or_b32_e32 v194, s23, v1
	v_or_b32_e32 v195, s26, v32
	v_or_b32_e32 v196, s27, v1
	v_or_b32_e32 v197, s34, v32
	v_or_b32_e32 v211, s35, v1
	v_or_b32_e32 v216, s40, v32
	v_or_b32_e32 v217, s15, v1
	v_or_b32_e32 v218, s16, v32
	v_add_u32_e32 v144, s13, v170
	v_ashrrev_i32_e32 v147, 31, v146
	v_add_u32_e32 v148, s13, v188
	v_add_u32_e32 v150, s8, v189
	v_add_u32_e32 v152, s13, v190
	v_add_u32_e32 v154, s8, v191
	v_add_u32_e32 v156, s13, v192
	v_add_u32_e32 v158, s8, v193
	v_add_u32_e32 v160, s13, v194
	v_add_u32_e32 v162, s8, v195
	v_add_u32_e32 v164, s13, v196
	v_add_u32_e32 v166, s8, v197
	v_add_u32_e32 v168, s13, v211
	v_add_u32_e32 v182, s8, v216
	v_add_u32_e32 v184, s13, v217
	v_add_u32_e32 v186, s8, v218
	v_ashrrev_i32_e32 v145, 31, v144
	v_lshlrev_b64 v[146:147], 12, v[146:147]
	v_ashrrev_i32_e32 v151, 31, v150
	v_ashrrev_i32_e32 v149, 31, v148
	v_ashrrev_i32_e32 v155, 31, v154
	v_ashrrev_i32_e32 v153, 31, v152
	v_ashrrev_i32_e32 v159, 31, v158
	v_ashrrev_i32_e32 v157, 31, v156
	v_ashrrev_i32_e32 v163, 31, v162
	v_ashrrev_i32_e32 v161, 31, v160
	v_ashrrev_i32_e32 v167, 31, v166
	v_ashrrev_i32_e32 v165, 31, v164
	v_ashrrev_i32_e32 v183, 31, v182
	v_ashrrev_i32_e32 v169, 31, v168
	v_ashrrev_i32_e32 v187, 31, v186
; #define LAS __attribute__((address_space(3)))
; #define LDS_WAIT() asm volatile("s_waitcnt lgkmcnt(0)" ::: "memory")
; __device__ __forceinline__ void transpose_item(const float* W, int N, bf16_t* WT, int ldw, int drow0, int dk0, LAS float* scr, int k0, int n0, int lane) {
; #pragma unroll 8
;     for (int i = 0; i < 32; ++i) { const int kk = 2 * i + (lane >> 5); scr[kk * 33 + (lane & 31)] = W[(size_t)(k0 + kk) * N + n0 + (lane & 31)]; }
;     LDS_WAIT(); asm volatile("" ::: "memory");
	v_ashrrev_i32_e32 v185, 31, v184
	v_lshlrev_b64 v[144:145], 12, v[144:145]
	v_lshl_add_u64 v[146:147], v[2:3], 0, v[146:147]
	v_lshlrev_b64 v[148:149], 12, v[148:149]
	v_lshlrev_b64 v[150:151], 12, v[150:151]
	v_lshlrev_b64 v[152:153], 12, v[152:153]
	v_lshlrev_b64 v[154:155], 12, v[154:155]
	v_lshlrev_b64 v[156:157], 12, v[156:157]
	v_lshlrev_b64 v[158:159], 12, v[158:159]
	v_lshlrev_b64 v[160:161], 12, v[160:161]
	v_lshlrev_b64 v[162:163], 12, v[162:163]
	v_lshlrev_b64 v[164:165], 12, v[164:165]
	v_lshlrev_b64 v[166:167], 12, v[166:167]
	v_lshlrev_b64 v[168:169], 12, v[168:169]
	v_lshlrev_b64 v[182:183], 12, v[182:183]
	v_lshlrev_b64 v[184:185], 12, v[184:185]
	v_lshlrev_b64 v[186:187], 12, v[186:187]
	v_lshl_add_u64 v[144:145], v[2:3], 0, v[144:145]
	v_lshl_add_u64 v[150:151], v[2:3], 0, v[150:151]
	v_lshl_add_u64 v[148:149], v[2:3], 0, v[148:149]
	v_lshl_add_u64 v[154:155], v[2:3], 0, v[154:155]
	v_lshl_add_u64 v[152:153], v[2:3], 0, v[152:153]
	v_lshl_add_u64 v[158:159], v[2:3], 0, v[158:159]
	v_lshl_add_u64 v[156:157], v[2:3], 0, v[156:157]
	v_lshl_add_u64 v[162:163], v[2:3], 0, v[162:163]
	v_lshl_add_u64 v[160:161], v[2:3], 0, v[160:161]
	v_lshl_add_u64 v[166:167], v[2:3], 0, v[166:167]
	v_lshl_add_u64 v[164:165], v[2:3], 0, v[164:165]
	v_lshl_add_u64 v[182:183], v[2:3], 0, v[182:183]
	v_lshl_add_u64 v[168:169], v[2:3], 0, v[168:169]
	v_lshl_add_u64 v[186:187], v[2:3], 0, v[186:187]
	v_lshl_add_u64 v[184:185], v[2:3], 0, v[184:185]
	global_load_dword v219, v[146:147], off
	global_load_dword v220, v[144:145], off
	global_load_dword v221, v[150:151], off
	global_load_dword v222, v[148:149], off
	global_load_dword v223, v[154:155], off
	global_load_dword v224, v[152:153], off
	global_load_dword v225, v[158:159], off
	global_load_dword v226, v[156:157], off
	global_load_dword v227, v[162:163], off
	global_load_dword v228, v[160:161], off
	global_load_dword v229, v[166:167], off
	global_load_dword v230, v[164:165], off
	global_load_dword v231, v[182:183], off
	global_load_dword v232, v[168:169], off
	global_load_dword v233, v[186:187], off
	global_load_dword v234, v[184:185], off
	v_mad_u64_u32 v[4:5], s[16:17], v41, s67, v[36:37]
	v_mad_u64_u32 v[6:7], s[16:17], v30, s67, v[36:37]
	v_mad_u64_u32 v[8:9], s[16:17], v49, s67, v[36:37]
	v_mad_u64_u32 v[10:11], s[16:17], v48, s67, v[36:37]
	v_mad_u64_u32 v[12:13], s[16:17], v51, s67, v[36:37]
	v_mad_u64_u32 v[14:15], s[16:17], v50, s67, v[36:37]
	v_mad_u64_u32 v[16:17], s[16:17], v53, s67, v[36:37]
	v_mad_u64_u32 v[18:19], s[16:17], v52, s67, v[36:37]
	v_mad_u64_u32 v[20:21], s[16:17], v55, s67, v[36:37]
	v_mad_u64_u32 v[22:23], s[16:17], v54, s67, v[36:37]
	v_mad_u64_u32 v[24:25], s[16:17], v57, s67, v[36:37]
	v_mad_u64_u32 v[26:27], s[16:17], v56, s67, v[36:37]
	v_mad_u64_u32 v[28:29], s[16:17], v76, s67, v[36:37]
	v_mad_u64_u32 v[42:43], s[16:17], v71, s67, v[36:37]
	v_mad_u64_u32 v[44:45], s[16:17], v78, s67, v[36:37]
	v_mad_u64_u32 v[46:47], s[16:17], v77, s67, v[36:37]
	s_waitcnt vmcnt(31)
	ds_write_b32 v4, v79
	s_waitcnt vmcnt(30)
	ds_write_b32 v6, v80
	s_waitcnt vmcnt(29)
	ds_write_b32 v8, v81
	s_waitcnt vmcnt(28)
	ds_write_b32 v10, v82
	s_waitcnt vmcnt(27)
	ds_write_b32 v12, v83
	s_waitcnt vmcnt(26)
	ds_write_b32 v14, v84
	s_waitcnt vmcnt(25)
	ds_write_b32 v16, v85
	s_waitcnt vmcnt(24)
	ds_write_b32 v18, v86
	s_waitcnt vmcnt(23)
	ds_write_b32 v20, v87
	s_waitcnt vmcnt(22)
	ds_write_b32 v22, v88
	s_waitcnt vmcnt(21)
	ds_write_b32 v24, v89
	s_waitcnt vmcnt(20)
	ds_write_b32 v26, v90
	s_waitcnt vmcnt(19)
	ds_write_b32 v28, v91
	s_waitcnt vmcnt(18)
	ds_write_b32 v42, v92
	s_waitcnt vmcnt(17)
	ds_write_b32 v44, v93
	s_waitcnt vmcnt(16)
; #define LAS __attribute__((address_space(3)))
; __device__ __forceinline__ unsigned cvtpk_s(float lo, float hi) { f32x2_t v = {lo, hi}; bf16x2_t b = __builtin_convertvector(v, bf16x2_t); return __builtin_bit_cast(unsigned, b); }
; #define LDS_WAIT() asm volatile("s_waitcnt lgkmcnt(0)" ::: "memory")
; __device__ __forceinline__ void transpose_item(const float* W, int N, bf16_t* WT, int ldw, int drow0, int dk0, LAS float* scr, int k0, int n0, int lane) {
;     ...
;     for (int i = 0; i < 32; ++i) { const int kk = 2 * i + (lane >> 5); scr[kk * 33 + (lane & 31)] = W[(size_t)(k0 + kk) * N + n0 + (lane & 31)]; }
;     LDS_WAIT(); asm volatile("" ::: "memory");
;     const int c = lane & 7;
; #pragma unroll
;     for (int j = 0; j < 4; ++j) { const int n = (lane >> 3) + 8 * j; const LAS float* s = scr + (8 * c) * 33 + n;
;         u32x4 o; o.x = cvtpk_s(s[0 * 33], s[1 * 33]); o.y = cvtpk_s(s[2 * 33], s[3 * 33]); o.z = cvtpk_s(s[4 * 33], s[5 * 33]); o.w = cvtpk_s(s[6 * 33], s[7 * 33]);
;         *(u32x4*)(WT + (size_t)(drow0 + n) * ldw + dk0 + k0 + 8 * c) = o; }
;     LDS_WAIT(); asm volatile("" ::: "memory");
	ds_write_b32 v46, v94
	s_add_i32 s9, s9, 16
	s_add_i32 s12, s12, 16
	s_add_i32 s14, s14, -16
	v_mad_u64_u32 v[144:145], s[16:17], v181, s67, v[36:37]
	v_mad_u64_u32 v[146:147], s[16:17], v170, s67, v[36:37]
	v_mad_u64_u32 v[148:149], s[16:17], v189, s67, v[36:37]
	v_mad_u64_u32 v[150:151], s[16:17], v188, s67, v[36:37]
	v_mad_u64_u32 v[152:153], s[16:17], v191, s67, v[36:37]
	v_mad_u64_u32 v[154:155], s[16:17], v190, s67, v[36:37]
	v_mad_u64_u32 v[156:157], s[16:17], v193, s67, v[36:37]
	v_mad_u64_u32 v[158:159], s[16:17], v192, s67, v[36:37]
	v_mad_u64_u32 v[160:161], s[16:17], v195, s67, v[36:37]
	v_mad_u64_u32 v[162:163], s[16:17], v194, s67, v[36:37]
	v_mad_u64_u32 v[164:165], s[16:17], v197, s67, v[36:37]
	v_mad_u64_u32 v[166:167], s[16:17], v196, s67, v[36:37]
	v_mad_u64_u32 v[168:169], s[16:17], v216, s67, v[36:37]
	v_mad_u64_u32 v[182:183], s[16:17], v211, s67, v[36:37]
	v_mad_u64_u32 v[184:185], s[16:17], v218, s67, v[36:37]
	v_mad_u64_u32 v[186:187], s[16:17], v217, s67, v[36:37]
	s_waitcnt vmcnt(15)
	ds_write_b32 v144, v219
	s_waitcnt vmcnt(14)
	ds_write_b32 v146, v220
	s_waitcnt vmcnt(13)
	ds_write_b32 v148, v221
	s_waitcnt vmcnt(12)
	ds_write_b32 v150, v222
	s_waitcnt vmcnt(11)
	ds_write_b32 v152, v223
	s_waitcnt vmcnt(10)
	ds_write_b32 v154, v224
	s_waitcnt vmcnt(9)
	ds_write_b32 v156, v225
	s_waitcnt vmcnt(8)
	ds_write_b32 v158, v226
	s_waitcnt vmcnt(7)
	ds_write_b32 v160, v227
	s_waitcnt vmcnt(6)
	ds_write_b32 v162, v228
	s_waitcnt vmcnt(5)
	ds_write_b32 v164, v229
	s_waitcnt vmcnt(4)
	ds_write_b32 v166, v230
	s_waitcnt vmcnt(3)
	ds_write_b32 v168, v231
	s_waitcnt vmcnt(2)
	ds_write_b32 v182, v232
	s_waitcnt vmcnt(1)
	ds_write_b32 v184, v233
	s_waitcnt vmcnt(0)
	ds_write_b32 v186, v234
	s_mov_b32 s9, s41
	s_waitcnt lgkmcnt(0)
	s_lshl_b64 s[8:9], s[8:9], 1
	s_add_u32 s8, s4, s8
	s_addc_u32 s9, s5, s9
	v_lshlrev_b32_e32 v30, 1, v38
	ds_read2_b32 v[6:7], v60 offset0:33 offset1:41
	ds_read2_b32 v[8:9], v60 offset1:8
	ds_read2_b32 v[10:11], v60 offset0:66 offset1:74
	ds_read2_b32 v[12:13], v60 offset0:99 offset1:107
	ds_read2_b32 v[14:15], v60 offset0:132 offset1:140
	ds_read2_b32 v[16:17], v60 offset0:165 offset1:173
	ds_read2_b32 v[18:19], v60 offset0:198 offset1:206
	ds_read2_b32 v[20:21], v60 offset0:231 offset1:239
	v_lshl_add_u64 v[2:3], s[8:9], 0, v[30:31]
	v_lshl_add_u64 v[22:23], v[2:3], 0, s[58:59]
	s_waitcnt lgkmcnt(6)
	v_cvt_pk_bf16_f32 v2, v8, v6
	v_or_b32_e32 v6, s11, v59
	v_mul_u32_u24_e32 v6, 0xb00, v6
	v_lshlrev_b32_e32 v30, 1, v6
	s_waitcnt lgkmcnt(4)
	v_cvt_pk_bf16_f32 v3, v10, v12
	s_waitcnt lgkmcnt(2)
	v_cvt_pk_bf16_f32 v4, v14, v16
	s_waitcnt lgkmcnt(0)
	v_cvt_pk_bf16_f32 v5, v18, v20
	v_lshl_add_u64 v[24:25], v[22:23], 0, v[30:31]
	v_or_b32_e32 v6, s11, v61
	global_store_dwordx4 v[24:25], v[2:5], off
	v_mul_u32_u24_e32 v6, 0xb00, v6
	v_lshlrev_b32_e32 v30, 1, v6
	v_cvt_pk_bf16_f32 v2, v9, v7
	v_cvt_pk_bf16_f32 v3, v11, v13
	v_cvt_pk_bf16_f32 v4, v15, v17
	v_cvt_pk_bf16_f32 v5, v19, v21
	ds_read2_b32 v[8:9], v60 offset0:16 offset1:24
	ds_read2_b32 v[10:11], v60 offset0:49 offset1:57
	ds_read2_b32 v[12:13], v60 offset0:82 offset1:90
	ds_read2_b32 v[14:15], v60 offset0:115 offset1:123
	ds_read2_b32 v[16:17], v60 offset0:148 offset1:156
	ds_read2_b32 v[18:19], v60 offset0:181 offset1:189
	ds_read2_b32 v[20:21], v60 offset0:214 offset1:222
	ds_read2_b32 v[24:25], v60 offset0:247 offset1:255
	v_lshl_add_u64 v[6:7], v[22:23], 0, v[30:31]
	global_store_dwordx4 v[6:7], v[2:5], off
	v_or_b32_e32 v6, s11, v62
	v_mul_u32_u24_e32 v6, 0xb00, v6
	v_lshlrev_b32_e32 v30, 1, v6
	s_waitcnt lgkmcnt(6)
	v_cvt_pk_bf16_f32 v2, v8, v10
	s_waitcnt lgkmcnt(4)
	v_cvt_pk_bf16_f32 v3, v12, v14
	s_waitcnt lgkmcnt(2)
	v_cvt_pk_bf16_f32 v4, v16, v18
	s_waitcnt lgkmcnt(0)
	v_cvt_pk_bf16_f32 v5, v20, v24
	v_lshl_add_u64 v[6:7], v[22:23], 0, v[30:31]
	global_store_dwordx4 v[6:7], v[2:5], off
	v_or_b32_e32 v6, s11, v63
	v_mul_u32_u24_e32 v6, 0xb00, v6
	v_lshlrev_b32_e32 v30, 1, v6
	v_cvt_pk_bf16_f32 v2, v9, v11
	v_cvt_pk_bf16_f32 v3, v13, v15
	v_cvt_pk_bf16_f32 v4, v17, v19
	v_cvt_pk_bf16_f32 v5, v21, v25
	v_lshl_add_u64 v[6:7], v[22:23], 0, v[30:31]
	global_store_dwordx4 v[6:7], v[2:5], off
	s_waitcnt lgkmcnt(0)

; #define LAS __attribute__((address_space(3)))
; #define LDS_WAIT() asm volatile("s_waitcnt lgkmcnt(0)" ::: "memory")
; __device__ __forceinline__ void transpose_item(const float* W, int N, bf16_t* WT, int ldw, int drow0, int dk0, LAS float* scr, int k0, int n0, int lane) {
; #pragma unroll 8
;     for (int i = 0; i < 32; ++i) { const int kk = 2 * i + (lane >> 5); scr[kk * 33 + (lane & 31)] = W[(size_t)(k0 + kk) * N + n0 + (lane & 31)]; }
;     LDS_WAIT(); asm volatile("" ::: "memory");
.LBB0_84:
	s_lshl_b32 s11, s8, 1
	s_lshl_b32 s13, s10, 1
	v_or_b32_e32 v30, s11, v1
	v_or_b32_e32 v41, s13, v32
	s_add_i32 s14, s11, 4
	s_add_i32 s15, s13, 4
	s_add_i32 s16, s11, 8
	s_add_i32 s17, s13, 8
	s_add_i32 s18, s11, 12
	s_add_i32 s19, s13, 12
	s_add_i32 s20, s11, 16
	s_add_i32 s21, s13, 16
	s_add_i32 s22, s11, 20
	s_add_i32 s23, s13, 20
	s_add_i32 s26, s11, 24
	s_add_i32 s27, s13, 24
	s_add_i32 s11, s11, 28
	s_add_i32 s13, s13, 28
	v_add_u32_e32 v4, s6, v41
	v_or_b32_e32 v48, s14, v1
	v_or_b32_e32 v49, s15, v32
	v_or_b32_e32 v50, s16, v1
	v_or_b32_e32 v51, s17, v32
	v_or_b32_e32 v52, s18, v1
	v_or_b32_e32 v53, s19, v32
	v_or_b32_e32 v54, s20, v1
	v_or_b32_e32 v55, s21, v32
	v_or_b32_e32 v56, s22, v1
	v_or_b32_e32 v57, s23, v32
	v_or_b32_e32 v71, s26, v1
	v_or_b32_e32 v76, s27, v32
	v_or_b32_e32 v77, s11, v1
	v_or_b32_e32 v78, s13, v32
	v_add_u32_e32 v6, s7, v30
	v_mad_i64_i32 v[4:5], s[14:15], v4, s81, v[2:3]
	v_add_u32_e32 v10, s7, v48
	v_add_u32_e32 v8, s6, v49
	v_add_u32_e32 v14, s7, v50
	v_add_u32_e32 v12, s6, v51
	v_add_u32_e32 v18, s7, v52
	v_add_u32_e32 v16, s6, v53
	v_add_u32_e32 v22, s7, v54
	v_add_u32_e32 v20, s6, v55
	v_add_u32_e32 v26, s7, v56
	v_add_u32_e32 v24, s6, v57
	v_add_u32_e32 v42, s7, v71
	v_add_u32_e32 v28, s6, v76
	v_add_u32_e32 v46, s7, v77
	v_add_u32_e32 v44, s6, v78
	v_mad_i64_i32 v[6:7], s[14:15], v6, s81, v[2:3]
	v_mad_i64_i32 v[8:9], s[14:15], v8, s81, v[2:3]
	v_mad_i64_i32 v[10:11], s[14:15], v10, s81, v[2:3]
	v_mad_i64_i32 v[12:13], s[14:15], v12, s81, v[2:3]
	v_mad_i64_i32 v[14:15], s[14:15], v14, s81, v[2:3]
	v_mad_i64_i32 v[16:17], s[14:15], v16, s81, v[2:3]
	v_mad_i64_i32 v[18:19], s[14:15], v18, s81, v[2:3]
	v_mad_i64_i32 v[20:21], s[14:15], v20, s81, v[2:3]
	v_mad_i64_i32 v[22:23], s[14:15], v22, s81, v[2:3]
	v_mad_i64_i32 v[24:25], s[14:15], v24, s81, v[2:3]
	v_mad_i64_i32 v[26:27], s[14:15], v26, s81, v[2:3]
	v_mad_i64_i32 v[28:29], s[14:15], v28, s81, v[2:3]
	v_mad_i64_i32 v[42:43], s[14:15], v42, s81, v[2:3]
	v_mad_i64_i32 v[44:45], s[14:15], v44, s81, v[2:3]
	v_mad_i64_i32 v[46:47], s[14:15], v46, s81, v[2:3]
	global_load_dword v79, v[4:5], off
	global_load_dword v80, v[6:7], off
	global_load_dword v81, v[8:9], off
	global_load_dword v82, v[10:11], off
	global_load_dword v83, v[12:13], off
	global_load_dword v84, v[14:15], off
	global_load_dword v85, v[16:17], off
	global_load_dword v86, v[18:19], off
	global_load_dword v87, v[20:21], off
	global_load_dword v88, v[22:23], off
	global_load_dword v89, v[24:25], off
	global_load_dword v90, v[26:27], off
	global_load_dword v91, v[28:29], off
	global_load_dword v92, v[42:43], off
	global_load_dword v93, v[44:45], off
	global_load_dword v94, v[46:47], off
	s_add_i32 s10, s10, 16
	s_add_i32 s8, s8, 16
	s_add_i32 s9, s9, -16
	s_lshl_b32 s11, s8, 1
	s_lshl_b32 s13, s10, 1
	v_or_b32_e32 v170, s11, v1
	v_or_b32_e32 v181, s13, v32
	s_add_i32 s14, s11, 4
	s_add_i32 s15, s13, 4
	s_add_i32 s16, s11, 8
	s_add_i32 s17, s13, 8
	s_add_i32 s18, s11, 12
	s_add_i32 s19, s13, 12
	s_add_i32 s20, s11, 16
	s_add_i32 s21, s13, 16
	s_add_i32 s22, s11, 20
	s_add_i32 s23, s13, 20
	s_add_i32 s26, s11, 24
	s_add_i32 s27, s13, 24
	s_add_i32 s11, s11, 28
	s_add_i32 s13, s13, 28
	v_add_u32_e32 v144, s6, v181
	v_or_b32_e32 v188, s14, v1
	v_or_b32_e32 v189, s15, v32
	v_or_b32_e32 v190, s16, v1
	v_or_b32_e32 v191, s17, v32
	v_or_b32_e32 v192, s18, v1
	v_or_b32_e32 v193, s19, v32
	v_or_b32_e32 v194, s20, v1
	v_or_b32_e32 v195, s21, v32
	v_or_b32_e32 v196, s22, v1
	v_or_b32_e32 v197, s23, v32
	v_or_b32_e32 v211, s26, v1
	v_or_b32_e32 v216, s27, v32
	v_or_b32_e32 v217, s11, v1
	v_or_b32_e32 v218, s13, v32
	v_add_u32_e32 v146, s7, v170
	v_mad_i64_i32 v[144:145], s[14:15], v144, s81, v[2:3]
	v_add_u32_e32 v150, s7, v188
	v_add_u32_e32 v148, s6, v189
	v_add_u32_e32 v154, s7, v190
	v_add_u32_e32 v152, s6, v191
	v_add_u32_e32 v158, s7, v192
	v_add_u32_e32 v156, s6, v193
	v_add_u32_e32 v162, s7, v194
	v_add_u32_e32 v160, s6, v195
	v_add_u32_e32 v166, s7, v196
	v_add_u32_e32 v164, s6, v197
	v_add_u32_e32 v182, s7, v211
	v_add_u32_e32 v168, s6, v216
	v_add_u32_e32 v186, s7, v217
	v_add_u32_e32 v184, s6, v218
	v_mad_i64_i32 v[146:147], s[14:15], v146, s81, v[2:3]
	v_mad_i64_i32 v[148:149], s[14:15], v148, s81, v[2:3]
	v_mad_i64_i32 v[150:151], s[14:15], v150, s81, v[2:3]
	v_mad_i64_i32 v[152:153], s[14:15], v152, s81, v[2:3]
	v_mad_i64_i32 v[154:155], s[14:15], v154, s81, v[2:3]
	v_mad_i64_i32 v[156:157], s[14:15], v156, s81, v[2:3]
	v_mad_i64_i32 v[158:159], s[14:15], v158, s81, v[2:3]
	v_mad_i64_i32 v[160:161], s[14:15], v160, s81, v[2:3]
	v_mad_i64_i32 v[162:163], s[14:15], v162, s81, v[2:3]
	v_mad_i64_i32 v[164:165], s[14:15], v164, s81, v[2:3]
	v_mad_i64_i32 v[166:167], s[14:15], v166, s81, v[2:3]
	v_mad_i64_i32 v[168:169], s[14:15], v168, s81, v[2:3]
	v_mad_i64_i32 v[182:183], s[14:15], v182, s81, v[2:3]
	v_mad_i64_i32 v[184:185], s[14:15], v184, s81, v[2:3]
	v_mad_i64_i32 v[186:187], s[14:15], v186, s81, v[2:3]
	global_load_dword v219, v[144:145], off
	global_load_dword v220, v[146:147], off
	global_load_dword v221, v[148:149], off
	global_load_dword v222, v[150:151], off
	global_load_dword v223, v[152:153], off
	global_load_dword v224, v[154:155], off
	global_load_dword v225, v[156:157], off
	global_load_dword v226, v[158:159], off
	global_load_dword v227, v[160:161], off
	global_load_dword v228, v[162:163], off
	global_load_dword v229, v[164:165], off
	global_load_dword v230, v[166:167], off
	global_load_dword v231, v[168:169], off
	global_load_dword v232, v[182:183], off
	global_load_dword v233, v[184:185], off
	global_load_dword v234, v[186:187], off
	v_mad_u64_u32 v[4:5], s[14:15], v41, s67, v[36:37]
	v_mad_u64_u32 v[6:7], s[14:15], v30, s67, v[36:37]
	v_mad_u64_u32 v[8:9], s[14:15], v49, s67, v[36:37]
	v_mad_u64_u32 v[10:11], s[14:15], v48, s67, v[36:37]
	v_mad_u64_u32 v[12:13], s[14:15], v51, s67, v[36:37]
	v_mad_u64_u32 v[14:15], s[14:15], v50, s67, v[36:37]
	v_mad_u64_u32 v[16:17], s[14:15], v53, s67, v[36:37]
	v_mad_u64_u32 v[18:19], s[14:15], v52, s67, v[36:37]
	v_mad_u64_u32 v[20:21], s[14:15], v55, s67, v[36:37]
	v_mad_u64_u32 v[22:23], s[14:15], v54, s67, v[36:37]
	v_mad_u64_u32 v[24:25], s[14:15], v57, s67, v[36:37]
	v_mad_u64_u32 v[26:27], s[14:15], v56, s67, v[36:37]
	v_mad_u64_u32 v[28:29], s[14:15], v76, s67, v[36:37]
	v_mad_u64_u32 v[42:43], s[14:15], v71, s67, v[36:37]
	v_mad_u64_u32 v[44:45], s[14:15], v78, s67, v[36:37]
	v_mad_u64_u32 v[46:47], s[14:15], v77, s67, v[36:37]
	s_waitcnt vmcnt(31)
; #define LAS __attribute__((address_space(3)))
; __device__ __forceinline__ unsigned cvtpk_s(float lo, float hi) { f32x2_t v = {lo, hi}; bf16x2_t b = __builtin_convertvector(v, bf16x2_t); return __builtin_bit_cast(unsigned, b); }
; #define LDS_WAIT() asm volatile("s_waitcnt lgkmcnt(0)" ::: "memory")
; __device__ __forceinline__ void transpose_item(const float* W, int N, bf16_t* WT, int ldw, int drow0, int dk0, LAS float* scr, int k0, int n0, int lane) {
;     ...
;     for (int i = 0; i < 32; ++i) { const int kk = 2 * i + (lane >> 5); scr[kk * 33 + (lane & 31)] = W[(size_t)(k0 + kk) * N + n0 + (lane & 31)]; }
;     LDS_WAIT(); asm volatile("" ::: "memory");
;     const int c = lane & 7;
; #pragma unroll
;     for (int j = 0; j < 4; ++j) { const int n = (lane >> 3) + 8 * j; const LAS float* s = scr + (8 * c) * 33 + n;
;         u32x4 o; o.x = cvtpk_s(s[0 * 33], s[1 * 33]); o.y = cvtpk_s(s[2 * 33], s[3 * 33]); o.z = cvtpk_s(s[4 * 33], s[5 * 33]); o.w = cvtpk_s(s[6 * 33], s[7 * 33]);
;         *(u32x4*)(WT + (size_t)(drow0 + n) * ldw + dk0 + k0 + 8 * c) = o; }
;     LDS_WAIT(); asm volatile("" ::: "memory");
	ds_write_b32 v4, v79
	s_waitcnt vmcnt(30)
	ds_write_b32 v6, v80
	s_waitcnt vmcnt(29)
	ds_write_b32 v8, v81
	s_waitcnt vmcnt(28)
	ds_write_b32 v10, v82
	s_waitcnt vmcnt(27)
	ds_write_b32 v12, v83
	s_waitcnt vmcnt(26)
	ds_write_b32 v14, v84
	s_waitcnt vmcnt(25)
	ds_write_b32 v16, v85
	s_waitcnt vmcnt(24)
	ds_write_b32 v18, v86
	s_waitcnt vmcnt(23)
	ds_write_b32 v20, v87
	s_waitcnt vmcnt(22)
	ds_write_b32 v22, v88
	s_waitcnt vmcnt(21)
	ds_write_b32 v24, v89
	s_waitcnt vmcnt(20)
	ds_write_b32 v26, v90
	s_waitcnt vmcnt(19)
	ds_write_b32 v28, v91
	s_waitcnt vmcnt(18)
	ds_write_b32 v42, v92
	s_waitcnt vmcnt(17)
	ds_write_b32 v44, v93
	s_waitcnt vmcnt(16)
	ds_write_b32 v46, v94
	s_add_i32 s10, s10, 16
	s_add_i32 s8, s8, 16
	s_add_i32 s9, s9, -16
	v_mad_u64_u32 v[144:145], s[14:15], v181, s67, v[36:37]
	v_mad_u64_u32 v[146:147], s[14:15], v170, s67, v[36:37]
	v_mad_u64_u32 v[148:149], s[14:15], v189, s67, v[36:37]
	v_mad_u64_u32 v[150:151], s[14:15], v188, s67, v[36:37]
	v_mad_u64_u32 v[152:153], s[14:15], v191, s67, v[36:37]
	v_mad_u64_u32 v[154:155], s[14:15], v190, s67, v[36:37]
	v_mad_u64_u32 v[156:157], s[14:15], v193, s67, v[36:37]
	v_mad_u64_u32 v[158:159], s[14:15], v192, s67, v[36:37]
	v_mad_u64_u32 v[160:161], s[14:15], v195, s67, v[36:37]
	v_mad_u64_u32 v[162:163], s[14:15], v194, s67, v[36:37]
	v_mad_u64_u32 v[164:165], s[14:15], v197, s67, v[36:37]
	v_mad_u64_u32 v[166:167], s[14:15], v196, s67, v[36:37]
	v_mad_u64_u32 v[168:169], s[14:15], v216, s67, v[36:37]
	v_mad_u64_u32 v[182:183], s[14:15], v211, s67, v[36:37]
	v_mad_u64_u32 v[184:185], s[14:15], v218, s67, v[36:37]
	v_mad_u64_u32 v[186:187], s[14:15], v217, s67, v[36:37]
	s_waitcnt vmcnt(15)
	ds_write_b32 v144, v219
	s_waitcnt vmcnt(14)
	ds_write_b32 v146, v220
	s_waitcnt vmcnt(13)
	ds_write_b32 v148, v221
	s_waitcnt vmcnt(12)
	ds_write_b32 v150, v222
	s_waitcnt vmcnt(11)
	ds_write_b32 v152, v223
	s_waitcnt vmcnt(10)
	ds_write_b32 v154, v224
	s_waitcnt vmcnt(9)
	ds_write_b32 v156, v225
	s_waitcnt vmcnt(8)
	ds_write_b32 v158, v226
	s_waitcnt vmcnt(7)
	ds_write_b32 v160, v227
	s_waitcnt vmcnt(6)
	ds_write_b32 v162, v228
	s_waitcnt vmcnt(5)
	ds_write_b32 v164, v229
	s_waitcnt vmcnt(4)
	ds_write_b32 v166, v230
	s_waitcnt vmcnt(3)
	ds_write_b32 v168, v231
	s_waitcnt vmcnt(2)
	ds_write_b32 v182, v232
	s_waitcnt vmcnt(1)
	ds_write_b32 v184, v233
	s_waitcnt vmcnt(0)
	ds_write_b32 v186, v234
	s_waitcnt lgkmcnt(0)
	s_ashr_i32 s7, s6, 31
	ds_read2_b32 v[6:7], v60 offset0:33 offset1:41
	ds_read2_b32 v[8:9], v60 offset1:8
	ds_read2_b32 v[10:11], v60 offset0:66 offset1:74
	ds_read2_b32 v[12:13], v60 offset0:99 offset1:107
	ds_read2_b32 v[14:15], v60 offset0:132 offset1:140
	ds_read2_b32 v[16:17], v60 offset0:165 offset1:173
	ds_read2_b32 v[18:19], v60 offset0:198 offset1:206
	ds_read2_b32 v[20:21], v60 offset0:231 offset1:239
	s_lshl_b64 s[6:7], s[6:7], 1
	s_add_u32 s4, s4, s6
	v_add_u32_e32 v24, s12, v59
	s_addc_u32 s5, s5, s7
	v_lshlrev_b32_e32 v30, 1, v38
	v_ashrrev_i32_e32 v25, 31, v24
	v_lshl_add_u64 v[22:23], s[4:5], 0, v[30:31]
	v_lshlrev_b64 v[24:25], 11, v[24:25]
	s_waitcnt lgkmcnt(6)
	v_cvt_pk_bf16_f32 v2, v8, v6
	s_waitcnt lgkmcnt(4)
	v_cvt_pk_bf16_f32 v3, v10, v12
	s_waitcnt lgkmcnt(2)
	v_cvt_pk_bf16_f32 v4, v14, v16
	s_waitcnt lgkmcnt(0)
	v_cvt_pk_bf16_f32 v5, v18, v20
	v_lshl_add_u64 v[24:25], v[22:23], 0, v[24:25]
	v_add_u32_e32 v6, s12, v61
	global_store_dwordx4 v[24:25], v[2:5], off
	s_nop 1
	v_cvt_pk_bf16_f32 v2, v9, v7
	v_ashrrev_i32_e32 v7, 31, v6
	v_cvt_pk_bf16_f32 v3, v11, v13
	v_cvt_pk_bf16_f32 v4, v15, v17
	v_cvt_pk_bf16_f32 v5, v19, v21
	v_lshlrev_b64 v[6:7], 11, v[6:7]
	ds_read2_b32 v[8:9], v60 offset0:49 offset1:57
	ds_read2_b32 v[10:11], v60 offset0:16 offset1:24
	ds_read2_b32 v[12:13], v60 offset0:82 offset1:90
	ds_read2_b32 v[14:15], v60 offset0:115 offset1:123
	ds_read2_b32 v[16:17], v60 offset0:148 offset1:156
	ds_read2_b32 v[18:19], v60 offset0:181 offset1:189
	ds_read2_b32 v[20:21], v60 offset0:214 offset1:222
	ds_read2_b32 v[24:25], v60 offset0:247 offset1:255
	v_lshl_add_u64 v[6:7], v[22:23], 0, v[6:7]
	global_store_dwordx4 v[6:7], v[2:5], off
	v_add_u32_e32 v6, s12, v62
	v_ashrrev_i32_e32 v7, 31, v6
	v_lshlrev_b64 v[6:7], 11, v[6:7]
	s_waitcnt lgkmcnt(6)
	v_cvt_pk_bf16_f32 v2, v10, v8
	s_waitcnt lgkmcnt(4)
	v_cvt_pk_bf16_f32 v3, v12, v14
	s_waitcnt lgkmcnt(2)
	v_cvt_pk_bf16_f32 v4, v16, v18
	s_waitcnt lgkmcnt(0)
	v_cvt_pk_bf16_f32 v5, v20, v24
	v_lshl_add_u64 v[6:7], v[22:23], 0, v[6:7]
	global_store_dwordx4 v[6:7], v[2:5], off
	v_add_u32_e32 v6, s12, v63
	v_ashrrev_i32_e32 v7, 31, v6
	v_lshlrev_b64 v[6:7], 11, v[6:7]
	v_cvt_pk_bf16_f32 v2, v11, v9
	v_cvt_pk_bf16_f32 v3, v13, v15
	v_cvt_pk_bf16_f32 v4, v17, v19
	v_cvt_pk_bf16_f32 v5, v21, v25
	v_lshl_add_u64 v[6:7], v[22:23], 0, v[6:7]
	global_store_dwordx4 v[6:7], v[2:5], off
	s_waitcnt lgkmcnt(0)

; __device__ __forceinline__ void prologue(const kptr_t kp, LAS float* scr, int gw, int NGW, int lane) {
;     ...
;             const int l = r / 576, rem = r % 576, cgp = rem / 16, ks = rem % 16, j0 = cgp * 256 + 4 * lane;
;             const float* c = KPTR(const float, 1); const float* cc = KPTR(const float, 3);
;             const float* wp = KPTR(const float, 4) + ((size_t)l * 1024 + ks * 64) * 9216 + j0;
;             f32x4 a0 = {0.f, 0.f, 0.f, 0.f}, a1 = a0, a2 = a0;
; #pragma unroll 4
;             for (int kk = 0; kk < 64; ++kk) {
;                 const int k = ks * 64 + kk; const float x0 = c[k], x1 = c[1024 + k], x2 = cc[k];
;                 const float s0 = x0 / (1.0f + expf(-x0)), s1 = x1 / (1.0f + expf(-x1)), s2 = x2 / (1.0f + expf(-x2));
;                 const f32x4 w = *(const f32x4*)(wp + (size_t)kk * 9216);
;                 a0 += w * s0; a1 += w * s1; a2 += w * s2;
;             }
.LBB0_88:
	v_lshlrev_b32_e32 v2, 2, v42
	v_add_u32_e32 v3, 0x1000, v64
	global_load_dword v4, v64, s[92:93]
	global_load_dword v5, v3, s[92:93]
	global_load_dword v6, v64, s[90:91]
	s_mov_b64 s[12:13], s[4:5]
	global_load_dwordx4 v[76:79], v2, s[12:13]
	s_add_u32 s12, s12, 0x9000
	s_addc_u32 s13, s13, 0
	global_load_dwordx4 v[80:83], v2, s[12:13]
	s_add_u32 s12, s12, 0x9000
	s_addc_u32 s13, s13, 0
	global_load_dwordx4 v[84:87], v2, s[12:13]
	s_add_u32 s12, s12, 0x9000
	s_addc_u32 s13, s13, 0
	global_load_dwordx4 v[88:91], v2, s[12:13]
	s_add_u32 s12, s12, 0x9000
	s_addc_u32 s13, s13, 0
	global_load_dwordx4 v[92:95], v2, s[12:13]
	s_add_u32 s12, s12, 0x9000
	s_addc_u32 s13, s13, 0
	global_load_dwordx4 v[96:99], v2, s[12:13]
	s_add_u32 s12, s12, 0x9000
	s_addc_u32 s13, s13, 0
	global_load_dwordx4 v[100:103], v2, s[12:13]
	s_add_u32 s12, s12, 0x9000
	s_addc_u32 s13, s13, 0
	global_load_dwordx4 v[104:107], v2, s[12:13]
	s_add_u32 s12, s12, 0x9000
	s_addc_u32 s13, s13, 0
	global_load_dwordx4 v[108:111], v2, s[12:13]
	s_add_u32 s12, s12, 0x9000
	s_addc_u32 s13, s13, 0
	global_load_dwordx4 v[112:115], v2, s[12:13]
	s_add_u32 s12, s12, 0x9000
	s_addc_u32 s13, s13, 0
	global_load_dwordx4 v[116:119], v2, s[12:13]
	s_add_u32 s12, s12, 0x9000
	s_addc_u32 s13, s13, 0
	global_load_dwordx4 v[120:123], v2, s[12:13]
	s_add_u32 s12, s12, 0x9000
	s_addc_u32 s13, s13, 0
	global_load_dwordx4 v[124:127], v2, s[12:13]
	s_add_u32 s12, s12, 0x9000
	s_addc_u32 s13, s13, 0
	global_load_dwordx4 v[128:131], v2, s[12:13]
	s_add_u32 s12, s12, 0x9000
	s_addc_u32 s13, s13, 0
	global_load_dwordx4 v[132:135], v2, s[12:13]
	s_add_u32 s12, s12, 0x9000
	s_addc_u32 s13, s13, 0
	global_load_dwordx4 v[136:139], v2, s[12:13]
	s_add_u32 s12, s12, 0x9000
	s_addc_u32 s13, s13, 0
	global_load_dwordx4 v[140:143], v2, s[12:13]
	s_add_u32 s12, s12, 0x9000
	s_addc_u32 s13, s13, 0
	global_load_dwordx4 v[144:147], v2, s[12:13]
	s_add_u32 s12, s12, 0x9000
	s_addc_u32 s13, s13, 0
	global_load_dwordx4 v[148:151], v2, s[12:13]
	s_add_u32 s12, s12, 0x9000
	s_addc_u32 s13, s13, 0
	global_load_dwordx4 v[152:155], v2, s[12:13]
	s_add_u32 s12, s12, 0x9000
	s_addc_u32 s13, s13, 0
	global_load_dwordx4 v[156:159], v2, s[12:13]
	s_add_u32 s12, s12, 0x9000
	s_addc_u32 s13, s13, 0
	global_load_dwordx4 v[160:163], v2, s[12:13]
	s_add_u32 s12, s12, 0x9000
	s_addc_u32 s13, s13, 0
	global_load_dwordx4 v[164:167], v2, s[12:13]
	s_add_u32 s12, s12, 0x9000
	s_addc_u32 s13, s13, 0
	global_load_dwordx4 v[168:171], v2, s[12:13]
	s_add_u32 s12, s12, 0x9000
	s_addc_u32 s13, s13, 0
	global_load_dwordx4 v[172:175], v2, s[12:13]
	s_add_u32 s12, s12, 0x9000
	s_addc_u32 s13, s13, 0
	global_load_dwordx4 v[176:179], v2, s[12:13]
	s_add_u32 s12, s12, 0x9000
	s_addc_u32 s13, s13, 0
	global_load_dwordx4 v[180:183], v2, s[12:13]
	s_add_u32 s12, s12, 0x9000
	s_addc_u32 s13, s13, 0
	global_load_dwordx4 v[184:187], v2, s[12:13]
	s_add_u32 s12, s12, 0x9000
	s_addc_u32 s13, s13, 0
	global_load_dwordx4 v[188:191], v2, s[12:13]
	s_add_u32 s12, s12, 0x9000
	s_addc_u32 s13, s13, 0
	global_load_dwordx4 v[192:195], v2, s[12:13]
	s_add_u32 s12, s12, 0x9000
	s_addc_u32 s13, s13, 0
	global_load_dwordx4 v[196:199], v2, s[12:13]
	s_add_u32 s12, s12, 0x9000
	s_addc_u32 s13, s13, 0
	global_load_dwordx4 v[200:203], v2, s[12:13]
	s_add_u32 s12, s12, 0x9000
	s_addc_u32 s13, s13, 0
	s_waitcnt vmcnt(32)
	v_mul_f32_e32 v10, 0xbfb8aa3b, v4
	v_mul_f32_e32 v11, 0xbfb8aa3b, v5
	v_mul_f32_e32 v12, 0xbfb8aa3b, v6
	v_exp_f32_e32 v10, v10
	v_exp_f32_e32 v11, v11
	v_exp_f32_e32 v12, v12
	s_nop 0
	v_add_f32_e32 v10, 1.0, v10
	v_add_f32_e32 v11, 1.0, v11
	v_add_f32_e32 v12, 1.0, v12
	v_rcp_f32_e32 v10, v10
	v_rcp_f32_e32 v11, v11
	v_rcp_f32_e32 v12, v12
	s_nop 0
	v_mul_f32_e32 v7, v4, v10
	v_mul_f32_e32 v8, v5, v11
	v_mul_f32_e32 v9, v6, v12
	s_nop 0
	s_waitcnt vmcnt(31)
	v_readlane_b32 s6, v7, 0
	v_readlane_b32 s7, v8, 0
	v_readlane_b32 s18, v9, 0
	v_fmac_f32_e32 v46, s6, v76
	v_fmac_f32_e32 v47, s6, v77
	v_fmac_f32_e32 v44, s6, v78
	v_fmac_f32_e32 v45, s6, v79
	v_fmac_f32_e32 v54, s7, v76
	v_fmac_f32_e32 v55, s7, v77
	v_fmac_f32_e32 v50, s7, v78
	v_fmac_f32_e32 v51, s7, v79
	v_fmac_f32_e32 v52, s18, v76
	v_fmac_f32_e32 v53, s18, v77
	v_fmac_f32_e32 v48, s18, v78
	v_fmac_f32_e32 v49, s18, v79
	global_load_dwordx4 v[76:79], v2, s[12:13]
	s_add_u32 s12, s12, 0x9000
	s_addc_u32 s13, s13, 0
	s_waitcnt vmcnt(31)
	v_readlane_b32 s6, v7, 1
	v_readlane_b32 s7, v8, 1
	v_readlane_b32 s18, v9, 1
	v_fmac_f32_e32 v46, s6, v80
	v_fmac_f32_e32 v47, s6, v81
	v_fmac_f32_e32 v44, s6, v82
	v_fmac_f32_e32 v45, s6, v83
	v_fmac_f32_e32 v54, s7, v80
	v_fmac_f32_e32 v55, s7, v81
	v_fmac_f32_e32 v50, s7, v82
	v_fmac_f32_e32 v51, s7, v83
	v_fmac_f32_e32 v52, s18, v80
	v_fmac_f32_e32 v53, s18, v81
	v_fmac_f32_e32 v48, s18, v82
	v_fmac_f32_e32 v49, s18, v83
	global_load_dwordx4 v[80:83], v2, s[12:13]
	s_add_u32 s12, s12, 0x9000
	s_addc_u32 s13, s13, 0
	s_waitcnt vmcnt(31)
	v_readlane_b32 s6, v7, 2
	v_readlane_b32 s7, v8, 2
	v_readlane_b32 s18, v9, 2
	v_fmac_f32_e32 v46, s6, v84
	v_fmac_f32_e32 v47, s6, v85
	v_fmac_f32_e32 v44, s6, v86
	v_fmac_f32_e32 v45, s6, v87
	v_fmac_f32_e32 v54, s7, v84
	v_fmac_f32_e32 v55, s7, v85
	v_fmac_f32_e32 v50, s7, v86
	v_fmac_f32_e32 v51, s7, v87
	v_fmac_f32_e32 v52, s18, v84
	v_fmac_f32_e32 v53, s18, v85
	v_fmac_f32_e32 v48, s18, v86
	v_fmac_f32_e32 v49, s18, v87
	global_load_dwordx4 v[84:87], v2, s[12:13]
	s_add_u32 s12, s12, 0x9000
	s_addc_u32 s13, s13, 0
	s_waitcnt vmcnt(31)
; __device__ __forceinline__ void prologue(const kptr_t kp, LAS float* scr, int gw, int NGW, int lane) {
;     ...
;             for (int kk = 0; kk < 64; ++kk) {
;                 const int k = ks * 64 + kk; const float x0 = c[k], x1 = c[1024 + k], x2 = cc[k];
;                 const float s0 = x0 / (1.0f + expf(-x0)), s1 = x1 / (1.0f + expf(-x1)), s2 = x2 / (1.0f + expf(-x2));
;                 const f32x4 w = *(const f32x4*)(wp + (size_t)kk * 9216);
;                 a0 += w * s0; a1 += w * s1; a2 += w * s2;
	v_readlane_b32 s6, v7, 3
	v_readlane_b32 s7, v8, 3
	v_readlane_b32 s18, v9, 3
	v_fmac_f32_e32 v46, s6, v88
	v_fmac_f32_e32 v47, s6, v89
	v_fmac_f32_e32 v44, s6, v90
	v_fmac_f32_e32 v45, s6, v91
	v_fmac_f32_e32 v54, s7, v88
	v_fmac_f32_e32 v55, s7, v89
	v_fmac_f32_e32 v50, s7, v90
	v_fmac_f32_e32 v51, s7, v91
	v_fmac_f32_e32 v52, s18, v88
	v_fmac_f32_e32 v53, s18, v89
	v_fmac_f32_e32 v48, s18, v90
	v_fmac_f32_e32 v49, s18, v91
	global_load_dwordx4 v[88:91], v2, s[12:13]
	s_add_u32 s12, s12, 0x9000
	s_addc_u32 s13, s13, 0
	s_waitcnt vmcnt(31)
	v_readlane_b32 s6, v7, 4
	v_readlane_b32 s7, v8, 4
	v_readlane_b32 s18, v9, 4
	v_fmac_f32_e32 v46, s6, v92
	v_fmac_f32_e32 v47, s6, v93
	v_fmac_f32_e32 v44, s6, v94
	v_fmac_f32_e32 v45, s6, v95
	v_fmac_f32_e32 v54, s7, v92
	v_fmac_f32_e32 v55, s7, v93
	v_fmac_f32_e32 v50, s7, v94
	v_fmac_f32_e32 v51, s7, v95
	v_fmac_f32_e32 v52, s18, v92
	v_fmac_f32_e32 v53, s18, v93
	v_fmac_f32_e32 v48, s18, v94
	v_fmac_f32_e32 v49, s18, v95
	global_load_dwordx4 v[92:95], v2, s[12:13]
	s_add_u32 s12, s12, 0x9000
	s_addc_u32 s13, s13, 0
	s_waitcnt vmcnt(31)
	v_readlane_b32 s6, v7, 5
	v_readlane_b32 s7, v8, 5
	v_readlane_b32 s18, v9, 5
	v_fmac_f32_e32 v46, s6, v96
	v_fmac_f32_e32 v47, s6, v97
	v_fmac_f32_e32 v44, s6, v98
	v_fmac_f32_e32 v45, s6, v99
	v_fmac_f32_e32 v54, s7, v96
	v_fmac_f32_e32 v55, s7, v97
	v_fmac_f32_e32 v50, s7, v98
	v_fmac_f32_e32 v51, s7, v99
	v_fmac_f32_e32 v52, s18, v96
	v_fmac_f32_e32 v53, s18, v97
	v_fmac_f32_e32 v48, s18, v98
	v_fmac_f32_e32 v49, s18, v99
	global_load_dwordx4 v[96:99], v2, s[12:13]
	s_add_u32 s12, s12, 0x9000
	s_addc_u32 s13, s13, 0
	s_waitcnt vmcnt(31)
	v_readlane_b32 s6, v7, 6
	v_readlane_b32 s7, v8, 6
	v_readlane_b32 s18, v9, 6
	v_fmac_f32_e32 v46, s6, v100
	v_fmac_f32_e32 v47, s6, v101
	v_fmac_f32_e32 v44, s6, v102
	v_fmac_f32_e32 v45, s6, v103
	v_fmac_f32_e32 v54, s7, v100
	v_fmac_f32_e32 v55, s7, v101
	v_fmac_f32_e32 v50, s7, v102
	v_fmac_f32_e32 v51, s7, v103
	v_fmac_f32_e32 v52, s18, v100
	v_fmac_f32_e32 v53, s18, v101
	v_fmac_f32_e32 v48, s18, v102
	v_fmac_f32_e32 v49, s18, v103
	global_load_dwordx4 v[100:103], v2, s[12:13]
	s_add_u32 s12, s12, 0x9000
	s_addc_u32 s13, s13, 0
	s_waitcnt vmcnt(31)
	v_readlane_b32 s6, v7, 7
	v_readlane_b32 s7, v8, 7
	v_readlane_b32 s18, v9, 7
	v_fmac_f32_e32 v46, s6, v104
	v_fmac_f32_e32 v47, s6, v105
	v_fmac_f32_e32 v44, s6, v106
	v_fmac_f32_e32 v45, s6, v107
	v_fmac_f32_e32 v54, s7, v104
	v_fmac_f32_e32 v55, s7, v105
	v_fmac_f32_e32 v50, s7, v106
	v_fmac_f32_e32 v51, s7, v107
	v_fmac_f32_e32 v52, s18, v104
	v_fmac_f32_e32 v53, s18, v105
	v_fmac_f32_e32 v48, s18, v106
	v_fmac_f32_e32 v49, s18, v107
	global_load_dwordx4 v[104:107], v2, s[12:13]
	s_add_u32 s12, s12, 0x9000
	s_addc_u32 s13, s13, 0
	s_waitcnt vmcnt(31)
	v_readlane_b32 s6, v7, 8
	v_readlane_b32 s7, v8, 8
	v_readlane_b32 s18, v9, 8
	v_fmac_f32_e32 v46, s6, v108
	v_fmac_f32_e32 v47, s6, v109
	v_fmac_f32_e32 v44, s6, v110
	v_fmac_f32_e32 v45, s6, v111
	v_fmac_f32_e32 v54, s7, v108
	v_fmac_f32_e32 v55, s7, v109
	v_fmac_f32_e32 v50, s7, v110
	v_fmac_f32_e32 v51, s7, v111
	v_fmac_f32_e32 v52, s18, v108
	v_fmac_f32_e32 v53, s18, v109
	v_fmac_f32_e32 v48, s18, v110
	v_fmac_f32_e32 v49, s18, v111
	global_load_dwordx4 v[108:111], v2, s[12:13]
	s_add_u32 s12, s12, 0x9000
	s_addc_u32 s13, s13, 0
	s_waitcnt vmcnt(31)
	v_readlane_b32 s6, v7, 9
	v_readlane_b32 s7, v8, 9
	v_readlane_b32 s18, v9, 9
	v_fmac_f32_e32 v46, s6, v112
	v_fmac_f32_e32 v47, s6, v113
	v_fmac_f32_e32 v44, s6, v114
	v_fmac_f32_e32 v45, s6, v115
	v_fmac_f32_e32 v54, s7, v112
	v_fmac_f32_e32 v55, s7, v113
	v_fmac_f32_e32 v50, s7, v114
	v_fmac_f32_e32 v51, s7, v115
	v_fmac_f32_e32 v52, s18, v112
	v_fmac_f32_e32 v53, s18, v113
	v_fmac_f32_e32 v48, s18, v114
	v_fmac_f32_e32 v49, s18, v115
	global_load_dwordx4 v[112:115], v2, s[12:13]
	s_add_u32 s12, s12, 0x9000
	s_addc_u32 s13, s13, 0
	s_waitcnt vmcnt(31)
	v_readlane_b32 s6, v7, 10
	v_readlane_b32 s7, v8, 10
	v_readlane_b32 s18, v9, 10
	v_fmac_f32_e32 v46, s6, v116
	v_fmac_f32_e32 v47, s6, v117
	v_fmac_f32_e32 v44, s6, v118
	v_fmac_f32_e32 v45, s6, v119
	v_fmac_f32_e32 v54, s7, v116
	v_fmac_f32_e32 v55, s7, v117
	v_fmac_f32_e32 v50, s7, v118
	v_fmac_f32_e32 v51, s7, v119
	v_fmac_f32_e32 v52, s18, v116
	v_fmac_f32_e32 v53, s18, v117
	v_fmac_f32_e32 v48, s18, v118
	v_fmac_f32_e32 v49, s18, v119
	global_load_dwordx4 v[116:119], v2, s[12:13]
	s_add_u32 s12, s12, 0x9000
	s_addc_u32 s13, s13, 0
	s_waitcnt vmcnt(31)
	v_readlane_b32 s6, v7, 11
	v_readlane_b32 s7, v8, 11
	v_readlane_b32 s18, v9, 11
	v_fmac_f32_e32 v46, s6, v120
	v_fmac_f32_e32 v47, s6, v121
	v_fmac_f32_e32 v44, s6, v122
	v_fmac_f32_e32 v45, s6, v123
	v_fmac_f32_e32 v54, s7, v120
	v_fmac_f32_e32 v55, s7, v121
	v_fmac_f32_e32 v50, s7, v122
	v_fmac_f32_e32 v51, s7, v123
	v_fmac_f32_e32 v52, s18, v120
	v_fmac_f32_e32 v53, s18, v121
	v_fmac_f32_e32 v48, s18, v122
	v_fmac_f32_e32 v49, s18, v123
	global_load_dwordx4 v[120:123], v2, s[12:13]
	s_add_u32 s12, s12, 0x9000
	s_addc_u32 s13, s13, 0
	s_waitcnt vmcnt(31)
	v_readlane_b32 s6, v7, 12
	v_readlane_b32 s7, v8, 12
	v_readlane_b32 s18, v9, 12
	v_fmac_f32_e32 v46, s6, v124
	v_fmac_f32_e32 v47, s6, v125
	v_fmac_f32_e32 v44, s6, v126
	v_fmac_f32_e32 v45, s6, v127
	v_fmac_f32_e32 v54, s7, v124
	v_fmac_f32_e32 v55, s7, v125
	v_fmac_f32_e32 v50, s7, v126
	v_fmac_f32_e32 v51, s7, v127
	v_fmac_f32_e32 v52, s18, v124
	v_fmac_f32_e32 v53, s18, v125
	v_fmac_f32_e32 v48, s18, v126
	v_fmac_f32_e32 v49, s18, v127
	global_load_dwordx4 v[124:127], v2, s[12:13]
	s_add_u32 s12, s12, 0x9000
	s_addc_u32 s13, s13, 0
	s_waitcnt vmcnt(31)
; __device__ __forceinline__ void prologue(const kptr_t kp, LAS float* scr, int gw, int NGW, int lane) {
;     ...
;             for (int kk = 0; kk < 64; ++kk) {
;                 const int k = ks * 64 + kk; const float x0 = c[k], x1 = c[1024 + k], x2 = cc[k];
;                 const float s0 = x0 / (1.0f + expf(-x0)), s1 = x1 / (1.0f + expf(-x1)), s2 = x2 / (1.0f + expf(-x2));
;                 const f32x4 w = *(const f32x4*)(wp + (size_t)kk * 9216);
;                 a0 += w * s0; a1 += w * s1; a2 += w * s2;
	v_readlane_b32 s6, v7, 13
	v_readlane_b32 s7, v8, 13
	v_readlane_b32 s18, v9, 13
	v_fmac_f32_e32 v46, s6, v128
	v_fmac_f32_e32 v47, s6, v129
	v_fmac_f32_e32 v44, s6, v130
	v_fmac_f32_e32 v45, s6, v131
	v_fmac_f32_e32 v54, s7, v128
	v_fmac_f32_e32 v55, s7, v129
	v_fmac_f32_e32 v50, s7, v130
	v_fmac_f32_e32 v51, s7, v131
	v_fmac_f32_e32 v52, s18, v128
	v_fmac_f32_e32 v53, s18, v129
	v_fmac_f32_e32 v48, s18, v130
	v_fmac_f32_e32 v49, s18, v131
	global_load_dwordx4 v[128:131], v2, s[12:13]
	s_add_u32 s12, s12, 0x9000
	s_addc_u32 s13, s13, 0
	s_waitcnt vmcnt(31)
	v_readlane_b32 s6, v7, 14
	v_readlane_b32 s7, v8, 14
	v_readlane_b32 s18, v9, 14
	v_fmac_f32_e32 v46, s6, v132
	v_fmac_f32_e32 v47, s6, v133
	v_fmac_f32_e32 v44, s6, v134
	v_fmac_f32_e32 v45, s6, v135
	v_fmac_f32_e32 v54, s7, v132
	v_fmac_f32_e32 v55, s7, v133
	v_fmac_f32_e32 v50, s7, v134
	v_fmac_f32_e32 v51, s7, v135
	v_fmac_f32_e32 v52, s18, v132
	v_fmac_f32_e32 v53, s18, v133
	v_fmac_f32_e32 v48, s18, v134
	v_fmac_f32_e32 v49, s18, v135
	global_load_dwordx4 v[132:135], v2, s[12:13]
	s_add_u32 s12, s12, 0x9000
	s_addc_u32 s13, s13, 0
	s_waitcnt vmcnt(31)
	v_readlane_b32 s6, v7, 15
	v_readlane_b32 s7, v8, 15
	v_readlane_b32 s18, v9, 15
	v_fmac_f32_e32 v46, s6, v136
	v_fmac_f32_e32 v47, s6, v137
	v_fmac_f32_e32 v44, s6, v138
	v_fmac_f32_e32 v45, s6, v139
	v_fmac_f32_e32 v54, s7, v136
	v_fmac_f32_e32 v55, s7, v137
	v_fmac_f32_e32 v50, s7, v138
	v_fmac_f32_e32 v51, s7, v139
	v_fmac_f32_e32 v52, s18, v136
	v_fmac_f32_e32 v53, s18, v137
	v_fmac_f32_e32 v48, s18, v138
	v_fmac_f32_e32 v49, s18, v139
	global_load_dwordx4 v[136:139], v2, s[12:13]
	s_add_u32 s12, s12, 0x9000
	s_addc_u32 s13, s13, 0
	s_waitcnt vmcnt(31)
	v_readlane_b32 s6, v7, 16
	v_readlane_b32 s7, v8, 16
	v_readlane_b32 s18, v9, 16
	v_fmac_f32_e32 v46, s6, v140
	v_fmac_f32_e32 v47, s6, v141
	v_fmac_f32_e32 v44, s6, v142
	v_fmac_f32_e32 v45, s6, v143
	v_fmac_f32_e32 v54, s7, v140
	v_fmac_f32_e32 v55, s7, v141
	v_fmac_f32_e32 v50, s7, v142
	v_fmac_f32_e32 v51, s7, v143
	v_fmac_f32_e32 v52, s18, v140
	v_fmac_f32_e32 v53, s18, v141
	v_fmac_f32_e32 v48, s18, v142
	v_fmac_f32_e32 v49, s18, v143
	global_load_dwordx4 v[140:143], v2, s[12:13]
	s_add_u32 s12, s12, 0x9000
	s_addc_u32 s13, s13, 0
	s_waitcnt vmcnt(31)
	v_readlane_b32 s6, v7, 17
	v_readlane_b32 s7, v8, 17
	v_readlane_b32 s18, v9, 17
	v_fmac_f32_e32 v46, s6, v144
	v_fmac_f32_e32 v47, s6, v145
	v_fmac_f32_e32 v44, s6, v146
	v_fmac_f32_e32 v45, s6, v147
	v_fmac_f32_e32 v54, s7, v144
	v_fmac_f32_e32 v55, s7, v145
	v_fmac_f32_e32 v50, s7, v146
	v_fmac_f32_e32 v51, s7, v147
	v_fmac_f32_e32 v52, s18, v144
	v_fmac_f32_e32 v53, s18, v145
	v_fmac_f32_e32 v48, s18, v146
	v_fmac_f32_e32 v49, s18, v147
	global_load_dwordx4 v[144:147], v2, s[12:13]
	s_add_u32 s12, s12, 0x9000
	s_addc_u32 s13, s13, 0
	s_waitcnt vmcnt(31)
	v_readlane_b32 s6, v7, 18
	v_readlane_b32 s7, v8, 18
	v_readlane_b32 s18, v9, 18
	v_fmac_f32_e32 v46, s6, v148
	v_fmac_f32_e32 v47, s6, v149
	v_fmac_f32_e32 v44, s6, v150
	v_fmac_f32_e32 v45, s6, v151
	v_fmac_f32_e32 v54, s7, v148
	v_fmac_f32_e32 v55, s7, v149
	v_fmac_f32_e32 v50, s7, v150
	v_fmac_f32_e32 v51, s7, v151
	v_fmac_f32_e32 v52, s18, v148
	v_fmac_f32_e32 v53, s18, v149
	v_fmac_f32_e32 v48, s18, v150
	v_fmac_f32_e32 v49, s18, v151
	global_load_dwordx4 v[148:151], v2, s[12:13]
	s_add_u32 s12, s12, 0x9000
	s_addc_u32 s13, s13, 0
	s_waitcnt vmcnt(31)
	v_readlane_b32 s6, v7, 19
	v_readlane_b32 s7, v8, 19
	v_readlane_b32 s18, v9, 19
	v_fmac_f32_e32 v46, s6, v152
	v_fmac_f32_e32 v47, s6, v153
	v_fmac_f32_e32 v44, s6, v154
	v_fmac_f32_e32 v45, s6, v155
	v_fmac_f32_e32 v54, s7, v152
	v_fmac_f32_e32 v55, s7, v153
	v_fmac_f32_e32 v50, s7, v154
	v_fmac_f32_e32 v51, s7, v155
	v_fmac_f32_e32 v52, s18, v152
	v_fmac_f32_e32 v53, s18, v153
	v_fmac_f32_e32 v48, s18, v154
	v_fmac_f32_e32 v49, s18, v155
	global_load_dwordx4 v[152:155], v2, s[12:13]
	s_add_u32 s12, s12, 0x9000
	s_addc_u32 s13, s13, 0
	s_waitcnt vmcnt(31)
	v_readlane_b32 s6, v7, 20
	v_readlane_b32 s7, v8, 20
	v_readlane_b32 s18, v9, 20
	v_fmac_f32_e32 v46, s6, v156
	v_fmac_f32_e32 v47, s6, v157
	v_fmac_f32_e32 v44, s6, v158
	v_fmac_f32_e32 v45, s6, v159
	v_fmac_f32_e32 v54, s7, v156
	v_fmac_f32_e32 v55, s7, v157
	v_fmac_f32_e32 v50, s7, v158
	v_fmac_f32_e32 v51, s7, v159
	v_fmac_f32_e32 v52, s18, v156
	v_fmac_f32_e32 v53, s18, v157
	v_fmac_f32_e32 v48, s18, v158
	v_fmac_f32_e32 v49, s18, v159
	global_load_dwordx4 v[156:159], v2, s[12:13]
	s_add_u32 s12, s12, 0x9000
	s_addc_u32 s13, s13, 0
	s_waitcnt vmcnt(31)
	v_readlane_b32 s6, v7, 21
	v_readlane_b32 s7, v8, 21
	v_readlane_b32 s18, v9, 21
	v_fmac_f32_e32 v46, s6, v160
	v_fmac_f32_e32 v47, s6, v161
	v_fmac_f32_e32 v44, s6, v162
	v_fmac_f32_e32 v45, s6, v163
	v_fmac_f32_e32 v54, s7, v160
	v_fmac_f32_e32 v55, s7, v161
	v_fmac_f32_e32 v50, s7, v162
	v_fmac_f32_e32 v51, s7, v163
	v_fmac_f32_e32 v52, s18, v160
	v_fmac_f32_e32 v53, s18, v161
	v_fmac_f32_e32 v48, s18, v162
	v_fmac_f32_e32 v49, s18, v163
	global_load_dwordx4 v[160:163], v2, s[12:13]
	s_add_u32 s12, s12, 0x9000
	s_addc_u32 s13, s13, 0
	s_waitcnt vmcnt(31)
	v_readlane_b32 s6, v7, 22
	v_readlane_b32 s7, v8, 22
	v_readlane_b32 s18, v9, 22
	v_fmac_f32_e32 v46, s6, v164
	v_fmac_f32_e32 v47, s6, v165
	v_fmac_f32_e32 v44, s6, v166
	v_fmac_f32_e32 v45, s6, v167
	v_fmac_f32_e32 v54, s7, v164
	v_fmac_f32_e32 v55, s7, v165
	v_fmac_f32_e32 v50, s7, v166
	v_fmac_f32_e32 v51, s7, v167
	v_fmac_f32_e32 v52, s18, v164
	v_fmac_f32_e32 v53, s18, v165
	v_fmac_f32_e32 v48, s18, v166
	v_fmac_f32_e32 v49, s18, v167
	global_load_dwordx4 v[164:167], v2, s[12:13]
	s_add_u32 s12, s12, 0x9000
	s_addc_u32 s13, s13, 0
	s_waitcnt vmcnt(31)
; __device__ __forceinline__ void prologue(const kptr_t kp, LAS float* scr, int gw, int NGW, int lane) {
;     ...
;             for (int kk = 0; kk < 64; ++kk) {
;                 const int k = ks * 64 + kk; const float x0 = c[k], x1 = c[1024 + k], x2 = cc[k];
;                 const float s0 = x0 / (1.0f + expf(-x0)), s1 = x1 / (1.0f + expf(-x1)), s2 = x2 / (1.0f + expf(-x2));
;                 const f32x4 w = *(const f32x4*)(wp + (size_t)kk * 9216);
;                 a0 += w * s0; a1 += w * s1; a2 += w * s2;
	v_readlane_b32 s6, v7, 23
	v_readlane_b32 s7, v8, 23
	v_readlane_b32 s18, v9, 23
	v_fmac_f32_e32 v46, s6, v168
	v_fmac_f32_e32 v47, s6, v169
	v_fmac_f32_e32 v44, s6, v170
	v_fmac_f32_e32 v45, s6, v171
	v_fmac_f32_e32 v54, s7, v168
	v_fmac_f32_e32 v55, s7, v169
	v_fmac_f32_e32 v50, s7, v170
	v_fmac_f32_e32 v51, s7, v171
	v_fmac_f32_e32 v52, s18, v168
	v_fmac_f32_e32 v53, s18, v169
	v_fmac_f32_e32 v48, s18, v170
	v_fmac_f32_e32 v49, s18, v171
	global_load_dwordx4 v[168:171], v2, s[12:13]
	s_add_u32 s12, s12, 0x9000
	s_addc_u32 s13, s13, 0
	s_waitcnt vmcnt(31)
	v_readlane_b32 s6, v7, 24
	v_readlane_b32 s7, v8, 24
	v_readlane_b32 s18, v9, 24
	v_fmac_f32_e32 v46, s6, v172
	v_fmac_f32_e32 v47, s6, v173
	v_fmac_f32_e32 v44, s6, v174
	v_fmac_f32_e32 v45, s6, v175
	v_fmac_f32_e32 v54, s7, v172
	v_fmac_f32_e32 v55, s7, v173
	v_fmac_f32_e32 v50, s7, v174
	v_fmac_f32_e32 v51, s7, v175
	v_fmac_f32_e32 v52, s18, v172
	v_fmac_f32_e32 v53, s18, v173
	v_fmac_f32_e32 v48, s18, v174
	v_fmac_f32_e32 v49, s18, v175
	global_load_dwordx4 v[172:175], v2, s[12:13]
	s_add_u32 s12, s12, 0x9000
	s_addc_u32 s13, s13, 0
	s_waitcnt vmcnt(31)
	v_readlane_b32 s6, v7, 25
	v_readlane_b32 s7, v8, 25
	v_readlane_b32 s18, v9, 25
	v_fmac_f32_e32 v46, s6, v176
	v_fmac_f32_e32 v47, s6, v177
	v_fmac_f32_e32 v44, s6, v178
	v_fmac_f32_e32 v45, s6, v179
	v_fmac_f32_e32 v54, s7, v176
	v_fmac_f32_e32 v55, s7, v177
	v_fmac_f32_e32 v50, s7, v178
	v_fmac_f32_e32 v51, s7, v179
	v_fmac_f32_e32 v52, s18, v176
	v_fmac_f32_e32 v53, s18, v177
	v_fmac_f32_e32 v48, s18, v178
	v_fmac_f32_e32 v49, s18, v179
	global_load_dwordx4 v[176:179], v2, s[12:13]
	s_add_u32 s12, s12, 0x9000
	s_addc_u32 s13, s13, 0
	s_waitcnt vmcnt(31)
	v_readlane_b32 s6, v7, 26
	v_readlane_b32 s7, v8, 26
	v_readlane_b32 s18, v9, 26
	v_fmac_f32_e32 v46, s6, v180
	v_fmac_f32_e32 v47, s6, v181
	v_fmac_f32_e32 v44, s6, v182
	v_fmac_f32_e32 v45, s6, v183
	v_fmac_f32_e32 v54, s7, v180
	v_fmac_f32_e32 v55, s7, v181
	v_fmac_f32_e32 v50, s7, v182
	v_fmac_f32_e32 v51, s7, v183
	v_fmac_f32_e32 v52, s18, v180
	v_fmac_f32_e32 v53, s18, v181
	v_fmac_f32_e32 v48, s18, v182
	v_fmac_f32_e32 v49, s18, v183
	global_load_dwordx4 v[180:183], v2, s[12:13]
	s_add_u32 s12, s12, 0x9000
	s_addc_u32 s13, s13, 0
	s_waitcnt vmcnt(31)
	v_readlane_b32 s6, v7, 27
	v_readlane_b32 s7, v8, 27
	v_readlane_b32 s18, v9, 27
	v_fmac_f32_e32 v46, s6, v184
	v_fmac_f32_e32 v47, s6, v185
	v_fmac_f32_e32 v44, s6, v186
	v_fmac_f32_e32 v45, s6, v187
	v_fmac_f32_e32 v54, s7, v184
	v_fmac_f32_e32 v55, s7, v185
	v_fmac_f32_e32 v50, s7, v186
	v_fmac_f32_e32 v51, s7, v187
	v_fmac_f32_e32 v52, s18, v184
	v_fmac_f32_e32 v53, s18, v185
	v_fmac_f32_e32 v48, s18, v186
	v_fmac_f32_e32 v49, s18, v187
	global_load_dwordx4 v[184:187], v2, s[12:13]
	s_add_u32 s12, s12, 0x9000
	s_addc_u32 s13, s13, 0
	s_waitcnt vmcnt(31)
	v_readlane_b32 s6, v7, 28
	v_readlane_b32 s7, v8, 28
	v_readlane_b32 s18, v9, 28
	v_fmac_f32_e32 v46, s6, v188
	v_fmac_f32_e32 v47, s6, v189
	v_fmac_f32_e32 v44, s6, v190
	v_fmac_f32_e32 v45, s6, v191
	v_fmac_f32_e32 v54, s7, v188
	v_fmac_f32_e32 v55, s7, v189
	v_fmac_f32_e32 v50, s7, v190
	v_fmac_f32_e32 v51, s7, v191
	v_fmac_f32_e32 v52, s18, v188
	v_fmac_f32_e32 v53, s18, v189
	v_fmac_f32_e32 v48, s18, v190
	v_fmac_f32_e32 v49, s18, v191
	global_load_dwordx4 v[188:191], v2, s[12:13]
	s_add_u32 s12, s12, 0x9000
	s_addc_u32 s13, s13, 0
	s_waitcnt vmcnt(31)
	v_readlane_b32 s6, v7, 29
	v_readlane_b32 s7, v8, 29
	v_readlane_b32 s18, v9, 29
	v_fmac_f32_e32 v46, s6, v192
	v_fmac_f32_e32 v47, s6, v193
	v_fmac_f32_e32 v44, s6, v194
	v_fmac_f32_e32 v45, s6, v195
	v_fmac_f32_e32 v54, s7, v192
	v_fmac_f32_e32 v55, s7, v193
	v_fmac_f32_e32 v50, s7, v194
	v_fmac_f32_e32 v51, s7, v195
	v_fmac_f32_e32 v52, s18, v192
	v_fmac_f32_e32 v53, s18, v193
	v_fmac_f32_e32 v48, s18, v194
	v_fmac_f32_e32 v49, s18, v195
	global_load_dwordx4 v[192:195], v2, s[12:13]
	s_add_u32 s12, s12, 0x9000
	s_addc_u32 s13, s13, 0
	s_waitcnt vmcnt(31)
	v_readlane_b32 s6, v7, 30
	v_readlane_b32 s7, v8, 30
	v_readlane_b32 s18, v9, 30
	v_fmac_f32_e32 v46, s6, v196
	v_fmac_f32_e32 v47, s6, v197
	v_fmac_f32_e32 v44, s6, v198
	v_fmac_f32_e32 v45, s6, v199
	v_fmac_f32_e32 v54, s7, v196
	v_fmac_f32_e32 v55, s7, v197
	v_fmac_f32_e32 v50, s7, v198
	v_fmac_f32_e32 v51, s7, v199
	v_fmac_f32_e32 v52, s18, v196
	v_fmac_f32_e32 v53, s18, v197
	v_fmac_f32_e32 v48, s18, v198
	v_fmac_f32_e32 v49, s18, v199
	global_load_dwordx4 v[196:199], v2, s[12:13]
	s_add_u32 s12, s12, 0x9000
	s_addc_u32 s13, s13, 0
	s_waitcnt vmcnt(31)
	v_readlane_b32 s6, v7, 31
	v_readlane_b32 s7, v8, 31
	v_readlane_b32 s18, v9, 31
	v_fmac_f32_e32 v46, s6, v200
	v_fmac_f32_e32 v47, s6, v201
	v_fmac_f32_e32 v44, s6, v202
	v_fmac_f32_e32 v45, s6, v203
	v_fmac_f32_e32 v54, s7, v200
	v_fmac_f32_e32 v55, s7, v201
	v_fmac_f32_e32 v50, s7, v202
	v_fmac_f32_e32 v51, s7, v203
	v_fmac_f32_e32 v52, s18, v200
	v_fmac_f32_e32 v53, s18, v201
	v_fmac_f32_e32 v48, s18, v202
	v_fmac_f32_e32 v49, s18, v203
	global_load_dwordx4 v[200:203], v2, s[12:13]
	s_add_u32 s12, s12, 0x9000
	s_addc_u32 s13, s13, 0
	s_waitcnt vmcnt(31)
	v_readlane_b32 s6, v7, 32
	v_readlane_b32 s7, v8, 32
	v_readlane_b32 s18, v9, 32
	v_fmac_f32_e32 v46, s6, v76
	v_fmac_f32_e32 v47, s6, v77
	v_fmac_f32_e32 v44, s6, v78
	v_fmac_f32_e32 v45, s6, v79
	v_fmac_f32_e32 v54, s7, v76
	v_fmac_f32_e32 v55, s7, v77
	v_fmac_f32_e32 v50, s7, v78
	v_fmac_f32_e32 v51, s7, v79
	v_fmac_f32_e32 v52, s18, v76
	v_fmac_f32_e32 v53, s18, v77
	v_fmac_f32_e32 v48, s18, v78
	v_fmac_f32_e32 v49, s18, v79
	s_waitcnt vmcnt(30)
; __device__ __forceinline__ void prologue(const kptr_t kp, LAS float* scr, int gw, int NGW, int lane) {
;     ...
;             for (int kk = 0; kk < 64; ++kk) {
;                 const int k = ks * 64 + kk; const float x0 = c[k], x1 = c[1024 + k], x2 = cc[k];
;                 const float s0 = x0 / (1.0f + expf(-x0)), s1 = x1 / (1.0f + expf(-x1)), s2 = x2 / (1.0f + expf(-x2));
;                 const f32x4 w = *(const f32x4*)(wp + (size_t)kk * 9216);
;                 a0 += w * s0; a1 += w * s1; a2 += w * s2;
	v_readlane_b32 s6, v7, 33
	v_readlane_b32 s7, v8, 33
	v_readlane_b32 s18, v9, 33
	v_fmac_f32_e32 v46, s6, v80
	v_fmac_f32_e32 v47, s6, v81
	v_fmac_f32_e32 v44, s6, v82
	v_fmac_f32_e32 v45, s6, v83
	v_fmac_f32_e32 v54, s7, v80
	v_fmac_f32_e32 v55, s7, v81
	v_fmac_f32_e32 v50, s7, v82
	v_fmac_f32_e32 v51, s7, v83
	v_fmac_f32_e32 v52, s18, v80
	v_fmac_f32_e32 v53, s18, v81
	v_fmac_f32_e32 v48, s18, v82
	v_fmac_f32_e32 v49, s18, v83
	s_waitcnt vmcnt(29)
	v_readlane_b32 s6, v7, 34
	v_readlane_b32 s7, v8, 34
	v_readlane_b32 s18, v9, 34
	v_fmac_f32_e32 v46, s6, v84
	v_fmac_f32_e32 v47, s6, v85
	v_fmac_f32_e32 v44, s6, v86
	v_fmac_f32_e32 v45, s6, v87
	v_fmac_f32_e32 v54, s7, v84
	v_fmac_f32_e32 v55, s7, v85
	v_fmac_f32_e32 v50, s7, v86
	v_fmac_f32_e32 v51, s7, v87
	v_fmac_f32_e32 v52, s18, v84
	v_fmac_f32_e32 v53, s18, v85
	v_fmac_f32_e32 v48, s18, v86
	v_fmac_f32_e32 v49, s18, v87
	s_waitcnt vmcnt(28)
	v_readlane_b32 s6, v7, 35
	v_readlane_b32 s7, v8, 35
	v_readlane_b32 s18, v9, 35
	v_fmac_f32_e32 v46, s6, v88
	v_fmac_f32_e32 v47, s6, v89
	v_fmac_f32_e32 v44, s6, v90
	v_fmac_f32_e32 v45, s6, v91
	v_fmac_f32_e32 v54, s7, v88
	v_fmac_f32_e32 v55, s7, v89
	v_fmac_f32_e32 v50, s7, v90
	v_fmac_f32_e32 v51, s7, v91
	v_fmac_f32_e32 v52, s18, v88
	v_fmac_f32_e32 v53, s18, v89
	v_fmac_f32_e32 v48, s18, v90
	v_fmac_f32_e32 v49, s18, v91
	s_waitcnt vmcnt(27)
	v_readlane_b32 s6, v7, 36
	v_readlane_b32 s7, v8, 36
	v_readlane_b32 s18, v9, 36
	v_fmac_f32_e32 v46, s6, v92
	v_fmac_f32_e32 v47, s6, v93
	v_fmac_f32_e32 v44, s6, v94
	v_fmac_f32_e32 v45, s6, v95
	v_fmac_f32_e32 v54, s7, v92
	v_fmac_f32_e32 v55, s7, v93
	v_fmac_f32_e32 v50, s7, v94
	v_fmac_f32_e32 v51, s7, v95
	v_fmac_f32_e32 v52, s18, v92
	v_fmac_f32_e32 v53, s18, v93
	v_fmac_f32_e32 v48, s18, v94
	v_fmac_f32_e32 v49, s18, v95
	s_waitcnt vmcnt(26)
	v_readlane_b32 s6, v7, 37
	v_readlane_b32 s7, v8, 37
	v_readlane_b32 s18, v9, 37
	v_fmac_f32_e32 v46, s6, v96
	v_fmac_f32_e32 v47, s6, v97
	v_fmac_f32_e32 v44, s6, v98
	v_fmac_f32_e32 v45, s6, v99
	v_fmac_f32_e32 v54, s7, v96
	v_fmac_f32_e32 v55, s7, v97
	v_fmac_f32_e32 v50, s7, v98
	v_fmac_f32_e32 v51, s7, v99
	v_fmac_f32_e32 v52, s18, v96
	v_fmac_f32_e32 v53, s18, v97
	v_fmac_f32_e32 v48, s18, v98
	v_fmac_f32_e32 v49, s18, v99
	s_waitcnt vmcnt(25)
	v_readlane_b32 s6, v7, 38
	v_readlane_b32 s7, v8, 38
	v_readlane_b32 s18, v9, 38
	v_fmac_f32_e32 v46, s6, v100
	v_fmac_f32_e32 v47, s6, v101
	v_fmac_f32_e32 v44, s6, v102
	v_fmac_f32_e32 v45, s6, v103
	v_fmac_f32_e32 v54, s7, v100
	v_fmac_f32_e32 v55, s7, v101
	v_fmac_f32_e32 v50, s7, v102
	v_fmac_f32_e32 v51, s7, v103
	v_fmac_f32_e32 v52, s18, v100
	v_fmac_f32_e32 v53, s18, v101
	v_fmac_f32_e32 v48, s18, v102
	v_fmac_f32_e32 v49, s18, v103
	s_waitcnt vmcnt(24)
	v_readlane_b32 s6, v7, 39
	v_readlane_b32 s7, v8, 39
	v_readlane_b32 s18, v9, 39
	v_fmac_f32_e32 v46, s6, v104
	v_fmac_f32_e32 v47, s6, v105
	v_fmac_f32_e32 v44, s6, v106
	v_fmac_f32_e32 v45, s6, v107
	v_fmac_f32_e32 v54, s7, v104
	v_fmac_f32_e32 v55, s7, v105
	v_fmac_f32_e32 v50, s7, v106
	v_fmac_f32_e32 v51, s7, v107
	v_fmac_f32_e32 v52, s18, v104
	v_fmac_f32_e32 v53, s18, v105
	v_fmac_f32_e32 v48, s18, v106
	v_fmac_f32_e32 v49, s18, v107
	s_waitcnt vmcnt(23)
	v_readlane_b32 s6, v7, 40
	v_readlane_b32 s7, v8, 40
	v_readlane_b32 s18, v9, 40
	v_fmac_f32_e32 v46, s6, v108
	v_fmac_f32_e32 v47, s6, v109
	v_fmac_f32_e32 v44, s6, v110
	v_fmac_f32_e32 v45, s6, v111
	v_fmac_f32_e32 v54, s7, v108
	v_fmac_f32_e32 v55, s7, v109
	v_fmac_f32_e32 v50, s7, v110
	v_fmac_f32_e32 v51, s7, v111
	v_fmac_f32_e32 v52, s18, v108
	v_fmac_f32_e32 v53, s18, v109
	v_fmac_f32_e32 v48, s18, v110
	v_fmac_f32_e32 v49, s18, v111
	s_waitcnt vmcnt(22)
	v_readlane_b32 s6, v7, 41
	v_readlane_b32 s7, v8, 41
	v_readlane_b32 s18, v9, 41
	v_fmac_f32_e32 v46, s6, v112
	v_fmac_f32_e32 v47, s6, v113
	v_fmac_f32_e32 v44, s6, v114
	v_fmac_f32_e32 v45, s6, v115
	v_fmac_f32_e32 v54, s7, v112
	v_fmac_f32_e32 v55, s7, v113
	v_fmac_f32_e32 v50, s7, v114
	v_fmac_f32_e32 v51, s7, v115
	v_fmac_f32_e32 v52, s18, v112
	v_fmac_f32_e32 v53, s18, v113
	v_fmac_f32_e32 v48, s18, v114
	v_fmac_f32_e32 v49, s18, v115
	s_waitcnt vmcnt(21)
	v_readlane_b32 s6, v7, 42
	v_readlane_b32 s7, v8, 42
	v_readlane_b32 s18, v9, 42
	v_fmac_f32_e32 v46, s6, v116
	v_fmac_f32_e32 v47, s6, v117
	v_fmac_f32_e32 v44, s6, v118
	v_fmac_f32_e32 v45, s6, v119
	v_fmac_f32_e32 v54, s7, v116
	v_fmac_f32_e32 v55, s7, v117
	v_fmac_f32_e32 v50, s7, v118
	v_fmac_f32_e32 v51, s7, v119
	v_fmac_f32_e32 v52, s18, v116
	v_fmac_f32_e32 v53, s18, v117
	v_fmac_f32_e32 v48, s18, v118
	v_fmac_f32_e32 v49, s18, v119
	s_waitcnt vmcnt(20)
	v_readlane_b32 s6, v7, 43
	v_readlane_b32 s7, v8, 43
	v_readlane_b32 s18, v9, 43
	v_fmac_f32_e32 v46, s6, v120
	v_fmac_f32_e32 v47, s6, v121
	v_fmac_f32_e32 v44, s6, v122
	v_fmac_f32_e32 v45, s6, v123
	v_fmac_f32_e32 v54, s7, v120
	v_fmac_f32_e32 v55, s7, v121
	v_fmac_f32_e32 v50, s7, v122
	v_fmac_f32_e32 v51, s7, v123
	v_fmac_f32_e32 v52, s18, v120
	v_fmac_f32_e32 v53, s18, v121
	v_fmac_f32_e32 v48, s18, v122
	v_fmac_f32_e32 v49, s18, v123
	s_waitcnt vmcnt(19)
	v_readlane_b32 s6, v7, 44
	v_readlane_b32 s7, v8, 44
	v_readlane_b32 s18, v9, 44
	v_fmac_f32_e32 v46, s6, v124
	v_fmac_f32_e32 v47, s6, v125
	v_fmac_f32_e32 v44, s6, v126
	v_fmac_f32_e32 v45, s6, v127
	v_fmac_f32_e32 v54, s7, v124
	v_fmac_f32_e32 v55, s7, v125
	v_fmac_f32_e32 v50, s7, v126
	v_fmac_f32_e32 v51, s7, v127
	v_fmac_f32_e32 v52, s18, v124
	v_fmac_f32_e32 v53, s18, v125
	v_fmac_f32_e32 v48, s18, v126
	v_fmac_f32_e32 v49, s18, v127
	s_waitcnt vmcnt(18)
; __device__ __forceinline__ void prologue(const kptr_t kp, LAS float* scr, int gw, int NGW, int lane) {
;     ...
;             for (int kk = 0; kk < 64; ++kk) {
;                 const int k = ks * 64 + kk; const float x0 = c[k], x1 = c[1024 + k], x2 = cc[k];
;                 const float s0 = x0 / (1.0f + expf(-x0)), s1 = x1 / (1.0f + expf(-x1)), s2 = x2 / (1.0f + expf(-x2));
;                 const f32x4 w = *(const f32x4*)(wp + (size_t)kk * 9216);
;                 a0 += w * s0; a1 += w * s1; a2 += w * s2;
	v_readlane_b32 s6, v7, 45
	v_readlane_b32 s7, v8, 45
	v_readlane_b32 s18, v9, 45
	v_fmac_f32_e32 v46, s6, v128
	v_fmac_f32_e32 v47, s6, v129
	v_fmac_f32_e32 v44, s6, v130
	v_fmac_f32_e32 v45, s6, v131
	v_fmac_f32_e32 v54, s7, v128
	v_fmac_f32_e32 v55, s7, v129
	v_fmac_f32_e32 v50, s7, v130
	v_fmac_f32_e32 v51, s7, v131
	v_fmac_f32_e32 v52, s18, v128
	v_fmac_f32_e32 v53, s18, v129
	v_fmac_f32_e32 v48, s18, v130
	v_fmac_f32_e32 v49, s18, v131
	s_waitcnt vmcnt(17)
	v_readlane_b32 s6, v7, 46
	v_readlane_b32 s7, v8, 46
	v_readlane_b32 s18, v9, 46
	v_fmac_f32_e32 v46, s6, v132
	v_fmac_f32_e32 v47, s6, v133
	v_fmac_f32_e32 v44, s6, v134
	v_fmac_f32_e32 v45, s6, v135
	v_fmac_f32_e32 v54, s7, v132
	v_fmac_f32_e32 v55, s7, v133
	v_fmac_f32_e32 v50, s7, v134
	v_fmac_f32_e32 v51, s7, v135
	v_fmac_f32_e32 v52, s18, v132
	v_fmac_f32_e32 v53, s18, v133
	v_fmac_f32_e32 v48, s18, v134
	v_fmac_f32_e32 v49, s18, v135
	s_waitcnt vmcnt(16)
	v_readlane_b32 s6, v7, 47
	v_readlane_b32 s7, v8, 47
	v_readlane_b32 s18, v9, 47
	v_fmac_f32_e32 v46, s6, v136
	v_fmac_f32_e32 v47, s6, v137
	v_fmac_f32_e32 v44, s6, v138
	v_fmac_f32_e32 v45, s6, v139
	v_fmac_f32_e32 v54, s7, v136
	v_fmac_f32_e32 v55, s7, v137
	v_fmac_f32_e32 v50, s7, v138
	v_fmac_f32_e32 v51, s7, v139
	v_fmac_f32_e32 v52, s18, v136
	v_fmac_f32_e32 v53, s18, v137
	v_fmac_f32_e32 v48, s18, v138
	v_fmac_f32_e32 v49, s18, v139
	s_waitcnt vmcnt(15)
	v_readlane_b32 s6, v7, 48
	v_readlane_b32 s7, v8, 48
	v_readlane_b32 s18, v9, 48
	v_fmac_f32_e32 v46, s6, v140
	v_fmac_f32_e32 v47, s6, v141
	v_fmac_f32_e32 v44, s6, v142
	v_fmac_f32_e32 v45, s6, v143
	v_fmac_f32_e32 v54, s7, v140
	v_fmac_f32_e32 v55, s7, v141
	v_fmac_f32_e32 v50, s7, v142
	v_fmac_f32_e32 v51, s7, v143
	v_fmac_f32_e32 v52, s18, v140
	v_fmac_f32_e32 v53, s18, v141
	v_fmac_f32_e32 v48, s18, v142
	v_fmac_f32_e32 v49, s18, v143
	s_waitcnt vmcnt(14)
	v_readlane_b32 s6, v7, 49
	v_readlane_b32 s7, v8, 49
	v_readlane_b32 s18, v9, 49
	v_fmac_f32_e32 v46, s6, v144
	v_fmac_f32_e32 v47, s6, v145
	v_fmac_f32_e32 v44, s6, v146
	v_fmac_f32_e32 v45, s6, v147
	v_fmac_f32_e32 v54, s7, v144
	v_fmac_f32_e32 v55, s7, v145
	v_fmac_f32_e32 v50, s7, v146
	v_fmac_f32_e32 v51, s7, v147
	v_fmac_f32_e32 v52, s18, v144
	v_fmac_f32_e32 v53, s18, v145
	v_fmac_f32_e32 v48, s18, v146
	v_fmac_f32_e32 v49, s18, v147
	s_waitcnt vmcnt(13)
	v_readlane_b32 s6, v7, 50
	v_readlane_b32 s7, v8, 50
	v_readlane_b32 s18, v9, 50
	v_fmac_f32_e32 v46, s6, v148
	v_fmac_f32_e32 v47, s6, v149
	v_fmac_f32_e32 v44, s6, v150
	v_fmac_f32_e32 v45, s6, v151
	v_fmac_f32_e32 v54, s7, v148
	v_fmac_f32_e32 v55, s7, v149
	v_fmac_f32_e32 v50, s7, v150
	v_fmac_f32_e32 v51, s7, v151
	v_fmac_f32_e32 v52, s18, v148
	v_fmac_f32_e32 v53, s18, v149
	v_fmac_f32_e32 v48, s18, v150
	v_fmac_f32_e32 v49, s18, v151
	s_waitcnt vmcnt(12)
	v_readlane_b32 s6, v7, 51
	v_readlane_b32 s7, v8, 51
	v_readlane_b32 s18, v9, 51
	v_fmac_f32_e32 v46, s6, v152
	v_fmac_f32_e32 v47, s6, v153
	v_fmac_f32_e32 v44, s6, v154
	v_fmac_f32_e32 v45, s6, v155
	v_fmac_f32_e32 v54, s7, v152
	v_fmac_f32_e32 v55, s7, v153
	v_fmac_f32_e32 v50, s7, v154
	v_fmac_f32_e32 v51, s7, v155
	v_fmac_f32_e32 v52, s18, v152
	v_fmac_f32_e32 v53, s18, v153
	v_fmac_f32_e32 v48, s18, v154
	v_fmac_f32_e32 v49, s18, v155
	s_waitcnt vmcnt(11)
	v_readlane_b32 s6, v7, 52
	v_readlane_b32 s7, v8, 52
	v_readlane_b32 s18, v9, 52
	v_fmac_f32_e32 v46, s6, v156
	v_fmac_f32_e32 v47, s6, v157
	v_fmac_f32_e32 v44, s6, v158
	v_fmac_f32_e32 v45, s6, v159
	v_fmac_f32_e32 v54, s7, v156
	v_fmac_f32_e32 v55, s7, v157
	v_fmac_f32_e32 v50, s7, v158
	v_fmac_f32_e32 v51, s7, v159
	v_fmac_f32_e32 v52, s18, v156
	v_fmac_f32_e32 v53, s18, v157
	v_fmac_f32_e32 v48, s18, v158
	v_fmac_f32_e32 v49, s18, v159
	s_waitcnt vmcnt(10)
	v_readlane_b32 s6, v7, 53
	v_readlane_b32 s7, v8, 53
	v_readlane_b32 s18, v9, 53
	v_fmac_f32_e32 v46, s6, v160
	v_fmac_f32_e32 v47, s6, v161
	v_fmac_f32_e32 v44, s6, v162
	v_fmac_f32_e32 v45, s6, v163
	v_fmac_f32_e32 v54, s7, v160
	v_fmac_f32_e32 v55, s7, v161
	v_fmac_f32_e32 v50, s7, v162
	v_fmac_f32_e32 v51, s7, v163
	v_fmac_f32_e32 v52, s18, v160
	v_fmac_f32_e32 v53, s18, v161
	v_fmac_f32_e32 v48, s18, v162
	v_fmac_f32_e32 v49, s18, v163
	s_waitcnt vmcnt(9)
	v_readlane_b32 s6, v7, 54
	v_readlane_b32 s7, v8, 54
	v_readlane_b32 s18, v9, 54
	v_fmac_f32_e32 v46, s6, v164
	v_fmac_f32_e32 v47, s6, v165
	v_fmac_f32_e32 v44, s6, v166
	v_fmac_f32_e32 v45, s6, v167
	v_fmac_f32_e32 v54, s7, v164
	v_fmac_f32_e32 v55, s7, v165
	v_fmac_f32_e32 v50, s7, v166
	v_fmac_f32_e32 v51, s7, v167
	v_fmac_f32_e32 v52, s18, v164
	v_fmac_f32_e32 v53, s18, v165
	v_fmac_f32_e32 v48, s18, v166
	v_fmac_f32_e32 v49, s18, v167
	s_waitcnt vmcnt(8)
; __device__ __forceinline__ void prologue(const kptr_t kp, LAS float* scr, int gw, int NGW, int lane) {
;     ...
;             for (int kk = 0; kk < 64; ++kk) {
;                 const int k = ks * 64 + kk; const float x0 = c[k], x1 = c[1024 + k], x2 = cc[k];
;                 const float s0 = x0 / (1.0f + expf(-x0)), s1 = x1 / (1.0f + expf(-x1)), s2 = x2 / (1.0f + expf(-x2));
;                 const f32x4 w = *(const f32x4*)(wp + (size_t)kk * 9216);
;                 a0 += w * s0; a1 += w * s1; a2 += w * s2;
;             }
;             if (ks == 0) { const f32x4 b = *(const f32x4*)(KPTR(const float, 5) + l * 9216 + j0); a0 += b; a1 += b; a2 += b; }
	v_readlane_b32 s6, v7, 55
	v_readlane_b32 s7, v8, 55
	v_readlane_b32 s18, v9, 55
	v_fmac_f32_e32 v46, s6, v168
	v_fmac_f32_e32 v47, s6, v169
	v_fmac_f32_e32 v44, s6, v170
	v_fmac_f32_e32 v45, s6, v171
	v_fmac_f32_e32 v54, s7, v168
	v_fmac_f32_e32 v55, s7, v169
	v_fmac_f32_e32 v50, s7, v170
	v_fmac_f32_e32 v51, s7, v171
	v_fmac_f32_e32 v52, s18, v168
	v_fmac_f32_e32 v53, s18, v169
	v_fmac_f32_e32 v48, s18, v170
	v_fmac_f32_e32 v49, s18, v171
	s_waitcnt vmcnt(7)
	v_readlane_b32 s6, v7, 56
	v_readlane_b32 s7, v8, 56
	v_readlane_b32 s18, v9, 56
	v_fmac_f32_e32 v46, s6, v172
	v_fmac_f32_e32 v47, s6, v173
	v_fmac_f32_e32 v44, s6, v174
	v_fmac_f32_e32 v45, s6, v175
	v_fmac_f32_e32 v54, s7, v172
	v_fmac_f32_e32 v55, s7, v173
	v_fmac_f32_e32 v50, s7, v174
	v_fmac_f32_e32 v51, s7, v175
	v_fmac_f32_e32 v52, s18, v172
	v_fmac_f32_e32 v53, s18, v173
	v_fmac_f32_e32 v48, s18, v174
	v_fmac_f32_e32 v49, s18, v175
	s_waitcnt vmcnt(6)
	v_readlane_b32 s6, v7, 57
	v_readlane_b32 s7, v8, 57
	v_readlane_b32 s18, v9, 57
	v_fmac_f32_e32 v46, s6, v176
	v_fmac_f32_e32 v47, s6, v177
	v_fmac_f32_e32 v44, s6, v178
	v_fmac_f32_e32 v45, s6, v179
	v_fmac_f32_e32 v54, s7, v176
	v_fmac_f32_e32 v55, s7, v177
	v_fmac_f32_e32 v50, s7, v178
	v_fmac_f32_e32 v51, s7, v179
	v_fmac_f32_e32 v52, s18, v176
	v_fmac_f32_e32 v53, s18, v177
	v_fmac_f32_e32 v48, s18, v178
	v_fmac_f32_e32 v49, s18, v179
	s_waitcnt vmcnt(5)
	v_readlane_b32 s6, v7, 58
	v_readlane_b32 s7, v8, 58
	v_readlane_b32 s18, v9, 58
	v_fmac_f32_e32 v46, s6, v180
	v_fmac_f32_e32 v47, s6, v181
	v_fmac_f32_e32 v44, s6, v182
	v_fmac_f32_e32 v45, s6, v183
	v_fmac_f32_e32 v54, s7, v180
	v_fmac_f32_e32 v55, s7, v181
	v_fmac_f32_e32 v50, s7, v182
	v_fmac_f32_e32 v51, s7, v183
	v_fmac_f32_e32 v52, s18, v180
	v_fmac_f32_e32 v53, s18, v181
	v_fmac_f32_e32 v48, s18, v182
	v_fmac_f32_e32 v49, s18, v183
	s_waitcnt vmcnt(4)
	v_readlane_b32 s6, v7, 59
	v_readlane_b32 s7, v8, 59
	v_readlane_b32 s18, v9, 59
	v_fmac_f32_e32 v46, s6, v184
	v_fmac_f32_e32 v47, s6, v185
	v_fmac_f32_e32 v44, s6, v186
	v_fmac_f32_e32 v45, s6, v187
	v_fmac_f32_e32 v54, s7, v184
	v_fmac_f32_e32 v55, s7, v185
	v_fmac_f32_e32 v50, s7, v186
	v_fmac_f32_e32 v51, s7, v187
	v_fmac_f32_e32 v52, s18, v184
	v_fmac_f32_e32 v53, s18, v185
	v_fmac_f32_e32 v48, s18, v186
	v_fmac_f32_e32 v49, s18, v187
	s_waitcnt vmcnt(3)
	v_readlane_b32 s6, v7, 60
	v_readlane_b32 s7, v8, 60
	v_readlane_b32 s18, v9, 60
	v_fmac_f32_e32 v46, s6, v188
	v_fmac_f32_e32 v47, s6, v189
	v_fmac_f32_e32 v44, s6, v190
	v_fmac_f32_e32 v45, s6, v191
	v_fmac_f32_e32 v54, s7, v188
	v_fmac_f32_e32 v55, s7, v189
	v_fmac_f32_e32 v50, s7, v190
	v_fmac_f32_e32 v51, s7, v191
	v_fmac_f32_e32 v52, s18, v188
	v_fmac_f32_e32 v53, s18, v189
	v_fmac_f32_e32 v48, s18, v190
	v_fmac_f32_e32 v49, s18, v191
	s_waitcnt vmcnt(2)
	v_readlane_b32 s6, v7, 61
	v_readlane_b32 s7, v8, 61
	v_readlane_b32 s18, v9, 61
	v_fmac_f32_e32 v46, s6, v192
	v_fmac_f32_e32 v47, s6, v193
	v_fmac_f32_e32 v44, s6, v194
	v_fmac_f32_e32 v45, s6, v195
	v_fmac_f32_e32 v54, s7, v192
	v_fmac_f32_e32 v55, s7, v193
	v_fmac_f32_e32 v50, s7, v194
	v_fmac_f32_e32 v51, s7, v195
	v_fmac_f32_e32 v52, s18, v192
	v_fmac_f32_e32 v53, s18, v193
	v_fmac_f32_e32 v48, s18, v194
	v_fmac_f32_e32 v49, s18, v195
	s_waitcnt vmcnt(1)
	v_readlane_b32 s6, v7, 62
	v_readlane_b32 s7, v8, 62
	v_readlane_b32 s18, v9, 62
	v_fmac_f32_e32 v46, s6, v196
	v_fmac_f32_e32 v47, s6, v197
	v_fmac_f32_e32 v44, s6, v198
	v_fmac_f32_e32 v45, s6, v199
	v_fmac_f32_e32 v54, s7, v196
	v_fmac_f32_e32 v55, s7, v197
	v_fmac_f32_e32 v50, s7, v198
	v_fmac_f32_e32 v51, s7, v199
	v_fmac_f32_e32 v52, s18, v196
	v_fmac_f32_e32 v53, s18, v197
	v_fmac_f32_e32 v48, s18, v198
	v_fmac_f32_e32 v49, s18, v199
	s_waitcnt vmcnt(0)
	v_readlane_b32 s6, v7, 63
	v_readlane_b32 s7, v8, 63
	v_readlane_b32 s18, v9, 63
	v_fmac_f32_e32 v46, s6, v200
	v_fmac_f32_e32 v47, s6, v201
	v_fmac_f32_e32 v44, s6, v202
	v_fmac_f32_e32 v45, s6, v203
	v_fmac_f32_e32 v54, s7, v200
	v_fmac_f32_e32 v55, s7, v201
	v_fmac_f32_e32 v50, s7, v202
	v_fmac_f32_e32 v51, s7, v203
	v_fmac_f32_e32 v52, s18, v200
	v_fmac_f32_e32 v53, s18, v201
	v_fmac_f32_e32 v48, s18, v202
	v_fmac_f32_e32 v49, s18, v203
	s_movk_i32 s64, 0x100
	s_mov_b32 s65, 0
	s_and_b32 s4, 0xffff, s82
	s_cmp_eq_u32 s4, 0
	s_cbranch_scc0 .LBB0_7
	s_load_dwordx2 s[4:5], s[36:37], 0x28
	s_mul_i32 s6, s40, 0x2400
	s_ashr_i32 s7, s6, 31
	s_lshl_b64 s[6:7], s[6:7], 2
	s_waitcnt lgkmcnt(0)
	s_add_u32 s4, s4, s6
	s_addc_u32 s5, s5, s7
	v_lshl_add_u64 v[2:3], v[42:43], 2, s[4:5]
	global_load_dwordx4 v[2:5], v[2:3], off
	s_waitcnt vmcnt(0)
	v_pk_add_f32 v[44:45], v[44:45], v[4:5]
	v_pk_add_f32 v[46:47], v[46:47], v[2:3]
	v_pk_add_f32 v[50:51], v[50:51], v[4:5]
	v_pk_add_f32 v[54:55], v[54:55], v[2:3]
	v_pk_add_f32 v[48:49], v[48:49], v[4:5]
	v_pk_add_f32 v[52:53], v[52:53], v[2:3]
	s_branch .LBB0_7
